# speedup vs baseline: 1.0156x; 1.0017x over previous
; #define PG8_STAGE(bufoff, gbase, voff) do { _Pragma("unroll") for (int _i = 0; _i < 2; ++_i) \
;     __builtin_amdgcn_global_load_lds((const unsigned*)((const char*)(gbase) + (voff)[_i]), (LAS unsigned*)(lds + (bufoff) + ldsw + _i * 8192), 16, 0, 0); } while (0)
; #define PG8_WAIT_V(n) asm volatile("s_waitcnt vmcnt(" #n ")" ::: "memory")
; #define PG8_BAR __builtin_amdgcn_s_barrier()
; template <class Epi, bool SPLITA = false>
; __device__ __forceinline__ void gemm_phase(const int tid, LAS unsigned char* lds, const Gemm g, const Order& S, const Epi& E) {
;     ...
;   for (int i = 0; i < 2; ++i) { int R, C; stage_rc(tid * 16 + i * 8192, R, C); const int Rb = Epi::PERM ? ((R & ~31) + perm32(R & 31)) : R;
;     voffA[i] = (unsigned)(R * g.lda + C) * 2u; voffB[i] = (unsigned)(Rb * g.ldb + C) * 2u; }
;   const size_t kstep = (size_t)(BK * 2);
;   const size_t hstepA = (size_t)HALF * g.lda * 2, hstepB = (size_t)HALF * g.ldb * 2;
;   const size_t tstepA = 2 * hstepA, tstepB = g.bpn < 0 ? 2 * hstepB : (size_t)g.bpn, apn = (size_t)g.apn;
;   const unsigned ldsw = (unsigned)wid * 1024u;
;   const int aoff = lds_byte(wr * 64 + fr, fq * 8), boff = lds_byte(wc * 32 + fr, fq * 8);
;     ...
;   Unit cur, nxt; int ui = 0;
;   if (!S.next(0, cur)) return;
;   Acc acc;
; #pragma unroll
;   for (int a = 0; a < 2; ++a)
; #pragma unroll
;     for (int b = 0; b < 2; ++b)
; #pragma unroll
;       for (int m = 0; m < 4; ++m)
; #pragma unroll
;         for (int n = 0; n < 2; ++n) acc[a][b][m][n] = (f32x4){0.f, 0.f, 0.f, 0.f};
;   bf16x8 At[4][2], B0[2][2], B1[2][2];
;   const char* cA = (const char*)g.A + (size_t)cur.pm * tstepA + (size_t)cur.pn * apn; const char* cB = (const char*)g.Bt + (size_t)cur.pn * tstepB;
;   const char* cA2 = SPLITA ? (const char*)g.A2 + (size_t)cur.pm * tstepA : cA; const int nt1 = SPLITA ? g.nt1 : nt;
;     ...
;   PG8_STAGE(PG8_SB(0, 0), cB, voffB); PG8_STAGE(PG8_SA(0, 0), cA, voffA); PG8_STAGE(PG8_SB(0, 1), cB + hstepB, voffB); PG8_STAGE(PG8_SA(0, 1), cA + hstepA, voffA);
;   if (wr == 1) PG8_BAR;
;   PG8_WAIT_V(4); PG8_BAR;
;   PG8_STAGE(PG8_SB(1, 0), cB + kstep, voffB); PG8_STAGE(PG8_SA(1, 0), cA + kstep, voffA); PG8_STAGE(PG8_SB(1, 1), cB + hstepB + kstep, voffB);
;   PG8_WAIT_V(6); PG8_BAR;
.LBB0_45:
	v_bfe_u32 v170, v208, 4, 2
	s_lshl_b32 s0, s0, 5
	v_and_b32_e32 v171, 15, v208
	v_lshlrev_b32_e32 v18, 4, v170
	v_lshlrev_b32_e32 v19, 2, v208
	s_and_b32 s43, s0, 0x60
	s_add_i32 m0, s4, 0x18000
	v_lshl_add_u64 v[8:9], v[8:9], 0, s[96:97]
	s_and_b32 s52, 0xffff, s6
	s_lshl_b32 s42, s1, 6
	v_lshl_or_b32 v18, v171, 6, v18
	s_lshl_b32 s1, s1, 13
	v_and_b32_e32 v19, 32, v19
	s_lshl_b32 s0, s43, 7
	s_waitcnt vmcnt(4)
	s_barrier
	global_load_lds_dwordx4 v[8:9], off
	v_lshl_add_u64 v[6:7], v[6:7], 0, s[96:97]
	s_add_i32 m0, s4, 0x1a000
	s_add_i32 s44, s4, 0x8000
	s_add_i32 s45, s4, 0xa000
	v_bitop3_b32 v172, s0, v18, v19 bitop3:0xf6
	global_load_lds_dwordx4 v[6:7], off
	v_lshl_add_u64 v[4:5], v[4:5], 0, s[96:97]
	s_mov_b32 m0, s44
	s_add_u32 s0, s16, 0x160080
	v_bitop3_b32 v20, v18, s1, v19 bitop3:0xde
	global_load_lds_dwordx4 v[4:5], off
	v_lshl_add_u64 v[2:3], v[2:3], 0, s[96:97]
	s_mov_b32 m0, s45
	s_addc_u32 s1, s17, 0
	global_load_lds_dwordx4 v[2:3], off
	s_add_i32 m0, s4, 0x1c000
	s_nop 0
	global_load_lds_dwordx4 v0, s[0:1]
	v_lshl_add_u64 v[2:3], s[0:1], 0, v[150:151]
	s_add_i32 m0, s4, 0x1e000
	s_movk_i32 s6, 0x1600
	global_load_lds_dwordx4 v150, s[0:1]
	v_lshrrev_b32_e32 v3, 1, v15
	v_mul_lo_u32 v2, v14, s6
	s_mov_b32 s7, 0x16000
	v_mad_u64_u32 v[2:3], s[0:1], v3, s7, v[2:3]
	v_or_b32_e32 v2, v2, v16
	v_add_lshl_u32 v156, v2, v17, 1
	v_lshrrev_b32_e32 v3, 1, v10
	v_mul_lo_u32 v2, v11, s6
	s_waitcnt vmcnt(6)
	v_mad_u64_u32 v[2:3], s[0:1], v3, s7, v[2:3]
	v_or_b32_e32 v2, v2, v12
	s_ashr_i32 s46, s92, 31
	v_mov_b32_e32 v157, v1
	v_add_lshl_u32 v158, v2, v13, 1
	v_mov_b32_e32 v159, v1
	s_mov_b32 s47, 0
	v_add_u32_e32 v173, 0, v20
	s_barrier

; #define PG8_STAGE(bufoff, gbase, voff) do { _Pragma("unroll") for (int _i = 0; _i < 2; ++_i) \
;     __builtin_amdgcn_global_load_lds((const unsigned*)((const char*)(gbase) + (voff)[_i]), (LAS unsigned*)(lds + (bufoff) + ldsw + _i * 8192), 16, 0, 0); } while (0)
; #define PG8_LDA(dst, b, h) do { _Pragma("unroll") for (int m = 0; m < 4; ++m) _Pragma("unroll") for (int k = 0; k < 2; ++k) dst[m][k] = *(const LAS bf16x8*)(lds + PG8_SA(b, h) + aoff + m * 2048 + k * 1024); } while (0)
; #define PG8_LDB(dst, b, h) do { _Pragma("unroll") for (int n = 0; n < 2; ++n) _Pragma("unroll") for (int k = 0; k < 2; ++k) dst[n][k] = *(const LAS bf16x8*)(lds + PG8_SB(b, h) + boff + n * 2048 + k * 1024); } while (0)
; #define PG8_MMA(ai, bj, At, Bt) do { __builtin_amdgcn_s_setprio(1); _Pragma("unroll") for (int m = 0; m < 4; ++m) _Pragma("unroll") for (int n = 0; n < 2; ++n) _Pragma("unroll") for (int k = 0; k < 2; ++k) \
;     acc[ai][bj][m][n] = __builtin_amdgcn_mfma_f32_16x16x32_bf16(Bt[n][k], At[m][k], acc[ai][bj][m][n], 0, 0, 0); __builtin_amdgcn_s_setprio(0); } while (0)
; #define PG8_WAIT_V(n) asm volatile("s_waitcnt vmcnt(" #n ")" ::: "memory")
; #define PG8_WAIT_L(n) asm volatile("s_waitcnt lgkmcnt(" #n ")" ::: "memory")
; template <class Epi, bool SPLITA = false>
; __device__ __forceinline__ void gemm_phase(const int tid, LAS unsigned char* lds, const Gemm g, const Order& S, const Epi& E) {
;     ...
;     for (int t = 0; t < nt; t += 2) {
;       const bool last = (t == nt - 2);
;       if constexpr (SPLITA) { if (t == nt1) E.mid(acc, cur, wr, wc, fr, fq); }
;       const char* a1 = PG8_TA(t + 1);
;       const char* a2 = last ? nA : PG8_TA(t + 2); const char* b2 = last ? nB : cB + (size_t)(t + 2) * kstep;
;       const char* a3 = last ? nA + kstep : PG8_TA(t + 3); const char* b3 = b2 + kstep;
;       PG8_LDB(B0, 0, 0); PG8_SCHED; PG8_LDA(At, 0, 0); PG8_STAGE(PG8_SA(1, 1), a1 + hstepA, voffA);
;       PG8_WAIT_L(8); PG8_BAR; PG8_WAIT_L(0); PG8_MMA(0, 0, At, B0); PG8_BAR; PG8_SCHED;
;       PG8_LDB(B1, 0, 1); PG8_STAGE(PG8_SB(0, 0), b2, voffB);
;       PG8_BAR; PG8_WAIT_L(0); PG8_MMA(0, 1, At, B1); PG8_BAR;
;       PG8_LDA(At, 0, 1); PG8_STAGE(PG8_SA(0, 0), a2, voffA);
;       PG8_BAR; PG8_WAIT_L(0); PG8_MMA(1, 0, At, B0); PG8_BAR; PG8_SCHED;
;       PG8_STAGE(PG8_SB(0, 1), b2 + hstepB, voffB);
;       PG8_WAIT_V(6); PG8_BAR; PG8_MMA(1, 1, At, B1); PG8_BAR;
.LBB0_57:
	s_add_u32 s8, s12, s16
	s_addc_u32 s9, s13, s17
	s_add_u32 s20, s8, 0x100
	s_addc_u32 s21, s9, 0
	s_add_u32 s18, s53, s16
	s_addc_u32 s19, s54, s17
	s_add_u32 s8, s8, 0x180
	s_addc_u32 s9, s9, 0
	s_add_i32 s55, 0, 0x10000
	v_add_u32_e32 v146, s55, v172
	ds_read_b128 v[134:137], v146
	ds_read_b128 v[138:141], v146 offset:1024
	ds_read_b128 v[142:145], v146 offset:2048
	ds_read_b128 v[146:149], v146 offset:3072
	s_cmpk_eq_i32 s16, 0x2b00
	s_cselect_b32 s23, s7, s9
	s_cselect_b32 s22, s6, s8
	s_cselect_b32 s19, s11, s19
	s_cselect_b32 s18, s10, s18
	s_cselect_b32 s41, s1, s21
	s_cselect_b32 s40, s0, s20
	v_lshl_add_u64 v[168:169], v[130:131], 0, s[16:17]
	s_add_i32 m0, s4, 0xc000
	ds_read_b128 v[160:163], v173
	ds_read_b128 v[164:167], v173 offset:1024
	ds_read_b128 v[174:177], v173 offset:2048
	ds_read_b128 v[178:181], v173 offset:3072
	ds_read_b128 v[182:185], v173 offset:4096
	ds_read_b128 v[186:189], v173 offset:5120
	ds_read_b128 v[190:193], v173 offset:6144
	ds_read_b128 v[210:213], v173 offset:7168
	global_load_lds_dwordx4 v[168:169], off
	v_lshl_add_u64 v[168:169], v[132:133], 0, s[16:17]
	s_add_i32 m0, s4, 0xe000
	s_nop 0
	global_load_lds_dwordx4 v[168:169], off
	s_waitcnt lgkmcnt(8)
	s_barrier
	s_waitcnt lgkmcnt(0)
	s_setprio 1
	s_waitcnt lgkmcnt(0)
	v_mfma_f32_16x16x32_bf16 v[126:129], v[134:137], v[160:163], v[126:129]
	v_mfma_f32_16x16x32_bf16 v[122:125], v[142:145], v[160:163], v[122:125]
	v_mfma_f32_16x16x32_bf16 v[118:121], v[134:137], v[174:177], v[118:121]
	v_mfma_f32_16x16x32_bf16 v[114:117], v[142:145], v[174:177], v[114:117]
	v_mfma_f32_16x16x32_bf16 v[98:101], v[134:137], v[182:185], v[98:101]
	v_mfma_f32_16x16x32_bf16 v[90:93], v[142:145], v[182:185], v[90:93]
	v_mfma_f32_16x16x32_bf16 v[82:85], v[134:137], v[190:193], v[82:85]
	v_mfma_f32_16x16x32_bf16 v[74:77], v[142:145], v[190:193], v[74:77]
	v_mfma_f32_16x16x32_bf16 v[126:129], v[138:141], v[164:167], v[126:129]
	v_mfma_f32_16x16x32_bf16 v[122:125], v[146:149], v[164:167], v[122:125]
	v_mfma_f32_16x16x32_bf16 v[118:121], v[138:141], v[178:181], v[118:121]
	v_mfma_f32_16x16x32_bf16 v[114:117], v[146:149], v[178:181], v[114:117]
	v_mfma_f32_16x16x32_bf16 v[98:101], v[138:141], v[186:189], v[98:101]
	v_mfma_f32_16x16x32_bf16 v[90:93], v[146:149], v[186:189], v[90:93]
	v_mfma_f32_16x16x32_bf16 v[82:85], v[138:141], v[210:213], v[82:85]
	v_mfma_f32_16x16x32_bf16 v[74:77], v[146:149], v[210:213], v[74:77]
	s_setprio 0
	s_barrier
	s_add_i32 s8, 0, 0x14000
	v_add_u32_e32 v168, s8, v172
	s_add_i32 s9, s55, s3
	ds_read_b128 v[214:217], v168
	ds_read_b128 v[218:221], v168 offset:1024
	ds_read_b128 v[222:225], v168 offset:2048
	ds_read_b128 v[226:229], v168 offset:3072
	v_lshl_add_u64 v[168:169], s[18:19], 0, v[0:1]
	s_mov_b32 m0, s9
	v_lshl_add_u64 v[198:199], s[18:19], 0, v[150:151]
	global_load_lds_dwordx4 v0, s[18:19]
	s_add_i32 m0, s9, 0x2000
	s_nop 0
	global_load_lds_dwordx4 v150, s[18:19]
	s_barrier
	s_waitcnt lgkmcnt(0)
	s_setprio 1
	s_waitcnt lgkmcnt(0)
	v_mfma_f32_16x16x32_bf16 v[110:113], v[214:217], v[160:163], v[110:113]
	v_mfma_f32_16x16x32_bf16 v[106:109], v[222:225], v[160:163], v[106:109]
	v_mfma_f32_16x16x32_bf16 v[102:105], v[214:217], v[174:177], v[102:105]
	v_mfma_f32_16x16x32_bf16 v[94:97], v[222:225], v[174:177], v[94:97]
	v_mfma_f32_16x16x32_bf16 v[86:89], v[214:217], v[182:185], v[86:89]
	v_mfma_f32_16x16x32_bf16 v[78:81], v[222:225], v[182:185], v[78:81]
	v_mfma_f32_16x16x32_bf16 v[70:73], v[214:217], v[190:193], v[70:73]
	v_mfma_f32_16x16x32_bf16 v[66:69], v[222:225], v[190:193], v[66:69]
	v_mfma_f32_16x16x32_bf16 v[110:113], v[218:221], v[164:167], v[110:113]
	v_mfma_f32_16x16x32_bf16 v[106:109], v[226:229], v[164:167], v[106:109]
	v_mfma_f32_16x16x32_bf16 v[102:105], v[218:221], v[178:181], v[102:105]
	v_mfma_f32_16x16x32_bf16 v[94:97], v[226:229], v[178:181], v[94:97]
	v_mfma_f32_16x16x32_bf16 v[86:89], v[218:221], v[186:189], v[86:89]
	v_mfma_f32_16x16x32_bf16 v[78:81], v[226:229], v[186:189], v[78:81]
	v_mfma_f32_16x16x32_bf16 v[70:73], v[218:221], v[210:213], v[70:73]
	v_mfma_f32_16x16x32_bf16 v[66:69], v[226:229], v[210:213], v[66:69]
	s_setprio 0
	s_mov_b32 m0, s4
	s_barrier
	ds_read_b128 v[160:163], v173 offset:16384
	ds_read_b128 v[164:167], v173 offset:17408
	ds_read_b128 v[174:177], v173 offset:18432
	ds_read_b128 v[178:181], v173 offset:19456
	ds_read_b128 v[182:185], v173 offset:20480
	ds_read_b128 v[186:189], v173 offset:21504
	ds_read_b128 v[190:193], v173 offset:22528
	ds_read_b128 v[210:213], v173 offset:23552
	global_load_lds_dwordx4 v154, s[40:41]
	s_mov_b32 m0, s28
	s_nop 0
	global_load_lds_dwordx4 v152, s[40:41]
	s_barrier
	s_waitcnt lgkmcnt(0)
	s_setprio 1
	s_waitcnt lgkmcnt(0)
	v_mfma_f32_16x16x32_bf16 v[62:65], v[134:137], v[160:163], v[62:65]
	v_mfma_f32_16x16x32_bf16 v[58:61], v[142:145], v[160:163], v[58:61]
	v_mfma_f32_16x16x32_bf16 v[50:53], v[134:137], v[174:177], v[50:53]
	v_mfma_f32_16x16x32_bf16 v[42:45], v[142:145], v[174:177], v[42:45]
	v_mfma_f32_16x16x32_bf16 v[34:37], v[134:137], v[182:185], v[34:37]
	v_mfma_f32_16x16x32_bf16 v[26:29], v[142:145], v[182:185], v[26:29]
	v_mfma_f32_16x16x32_bf16 v[18:21], v[134:137], v[190:193], v[18:21]
	v_mfma_f32_16x16x32_bf16 v[10:13], v[142:145], v[190:193], v[10:13]
	v_mfma_f32_16x16x32_bf16 v[62:65], v[138:141], v[164:167], v[62:65]
	v_mfma_f32_16x16x32_bf16 v[58:61], v[146:149], v[164:167], v[58:61]
	v_mfma_f32_16x16x32_bf16 v[50:53], v[138:141], v[178:181], v[50:53]
	v_mfma_f32_16x16x32_bf16 v[42:45], v[146:149], v[178:181], v[42:45]
	v_mfma_f32_16x16x32_bf16 v[34:37], v[138:141], v[186:189], v[34:37]
	v_mfma_f32_16x16x32_bf16 v[26:29], v[146:149], v[186:189], v[26:29]
	v_mfma_f32_16x16x32_bf16 v[18:21], v[138:141], v[210:213], v[18:21]
	v_mfma_f32_16x16x32_bf16 v[10:13], v[146:149], v[210:213], v[10:13]
	s_setprio 0
	s_barrier
; #define PG8_STAGE(bufoff, gbase, voff) do { _Pragma("unroll") for (int _i = 0; _i < 2; ++_i) \
;     __builtin_amdgcn_global_load_lds((const unsigned*)((const char*)(gbase) + (voff)[_i]), (LAS unsigned*)(lds + (bufoff) + ldsw + _i * 8192), 16, 0, 0); } while (0)
; #define PG8_LDA(dst, b, h) do { _Pragma("unroll") for (int m = 0; m < 4; ++m) _Pragma("unroll") for (int k = 0; k < 2; ++k) dst[m][k] = *(const LAS bf16x8*)(lds + PG8_SA(b, h) + aoff + m * 2048 + k * 1024); } while (0)
; #define PG8_LDB(dst, b, h) do { _Pragma("unroll") for (int n = 0; n < 2; ++n) _Pragma("unroll") for (int k = 0; k < 2; ++k) dst[n][k] = *(const LAS bf16x8*)(lds + PG8_SB(b, h) + boff + n * 2048 + k * 1024); } while (0)
; #define PG8_MMA(ai, bj, At, Bt) do { __builtin_amdgcn_s_setprio(1); _Pragma("unroll") for (int m = 0; m < 4; ++m) _Pragma("unroll") for (int n = 0; n < 2; ++n) _Pragma("unroll") for (int k = 0; k < 2; ++k) \
;     acc[ai][bj][m][n] = __builtin_amdgcn_mfma_f32_16x16x32_bf16(Bt[n][k], At[m][k], acc[ai][bj][m][n], 0, 0, 0); __builtin_amdgcn_s_setprio(0); } while (0)
; #define PG8_WAIT_V(n) asm volatile("s_waitcnt vmcnt(" #n ")" ::: "memory")
; #define PG8_WAIT_L(n) asm volatile("s_waitcnt lgkmcnt(" #n ")" ::: "memory")
; #define PG8_BAR __builtin_amdgcn_s_barrier()
; #define PG8_SCHED __builtin_amdgcn_sched_barrier(0)
; template <class Epi, bool SPLITA = false>
; __device__ __forceinline__ void gemm_phase(const int tid, LAS unsigned char* lds, const Gemm g, const Order& S, const Epi& E) {
;     ...
;       PG8_STAGE(PG8_SB(0, 1), b2 + hstepB, voffB);
;       PG8_WAIT_V(6); PG8_BAR; PG8_MMA(1, 1, At, B1); PG8_BAR;
;       PG8_LDB(B0, 1, 0); PG8_SCHED; PG8_LDA(At, 1, 0); PG8_STAGE(PG8_SA(0, 1), a2 + hstepA, voffA);
;       PG8_WAIT_L(8); PG8_BAR; PG8_WAIT_L(0); PG8_MMA(0, 0, At, B0); PG8_BAR; PG8_SCHED;
;       PG8_LDB(B1, 1, 1); PG8_STAGE(PG8_SB(1, 0), b3, voffB);
;       PG8_BAR; PG8_WAIT_L(0); PG8_MMA(0, 1, At, B1); PG8_BAR;
;       PG8_LDA(At, 1, 1); PG8_STAGE(PG8_SA(1, 0), a3, voffA);
;       PG8_BAR; PG8_WAIT_L(0); PG8_MMA(1, 0, At, B0); PG8_BAR; PG8_SCHED;
	s_add_u32 s20, s18, 0x160000
	s_addc_u32 s21, s19, 0
	s_add_i32 s8, s8, s3
	s_mov_b32 m0, s8
	s_nop 0
	global_load_lds_dwordx4 v0, s[20:21]
	v_lshl_add_u64 v[134:135], s[20:21], 0, v[150:151]
	s_add_i32 m0, s8, 0x2000
	s_nop 0
	global_load_lds_dwordx4 v150, s[20:21]
	s_waitcnt vmcnt(6)
	s_barrier
	s_setprio 1
	v_mfma_f32_16x16x32_bf16 v[54:57], v[214:217], v[160:163], v[54:57]
	v_mfma_f32_16x16x32_bf16 v[46:49], v[222:225], v[160:163], v[46:49]
	v_mfma_f32_16x16x32_bf16 v[38:41], v[214:217], v[174:177], v[38:41]
	v_mfma_f32_16x16x32_bf16 v[30:33], v[222:225], v[174:177], v[30:33]
	v_mfma_f32_16x16x32_bf16 v[22:25], v[214:217], v[182:185], v[22:25]
	v_mfma_f32_16x16x32_bf16 v[14:17], v[222:225], v[182:185], v[14:17]
	v_mfma_f32_16x16x32_bf16 v[6:9], v[214:217], v[190:193], v[6:9]
	v_mfma_f32_16x16x32_bf16 v[2:5], v[222:225], v[190:193], v[2:5]
	v_mfma_f32_16x16x32_bf16 v[54:57], v[218:221], v[164:167], v[54:57]
	v_mfma_f32_16x16x32_bf16 v[46:49], v[226:229], v[164:167], v[46:49]
	v_mfma_f32_16x16x32_bf16 v[38:41], v[218:221], v[178:181], v[38:41]
	v_mfma_f32_16x16x32_bf16 v[30:33], v[226:229], v[178:181], v[30:33]
	v_mfma_f32_16x16x32_bf16 v[22:25], v[218:221], v[186:189], v[22:25]
	v_mfma_f32_16x16x32_bf16 v[14:17], v[226:229], v[186:189], v[14:17]
	v_mfma_f32_16x16x32_bf16 v[6:9], v[218:221], v[210:213], v[6:9]
	v_mfma_f32_16x16x32_bf16 v[2:5], v[226:229], v[210:213], v[2:5]
	s_setprio 0
	s_add_i32 s8, 0, 0x18000
	v_add_u32_e32 v146, s8, v172
	s_barrier
	ds_read_b128 v[134:137], v146
	ds_read_b128 v[138:141], v146 offset:1024
	ds_read_b128 v[142:145], v146 offset:2048
	ds_read_b128 v[146:149], v146 offset:3072
	s_add_u32 s20, s40, 0x160000
	s_addc_u32 s21, s41, 0
	s_mov_b32 m0, s30
	ds_read_b128 v[160:163], v173 offset:32768
	ds_read_b128 v[164:167], v173 offset:33792
	ds_read_b128 v[174:177], v173 offset:34816
	ds_read_b128 v[178:181], v173 offset:35840
	ds_read_b128 v[182:185], v173 offset:36864
	ds_read_b128 v[186:189], v173 offset:37888
	ds_read_b128 v[190:193], v173 offset:38912
	ds_read_b128 v[210:213], v173 offset:39936
	global_load_lds_dwordx4 v154, s[20:21]
	s_mov_b32 m0, s31
	s_nop 0
	global_load_lds_dwordx4 v152, s[20:21]
	s_waitcnt lgkmcnt(8)
	s_barrier
	s_waitcnt lgkmcnt(0)
	s_setprio 1
	s_waitcnt lgkmcnt(0)
	v_mfma_f32_16x16x32_bf16 v[126:129], v[134:137], v[160:163], v[126:129]
	v_mfma_f32_16x16x32_bf16 v[122:125], v[142:145], v[160:163], v[122:125]
	v_mfma_f32_16x16x32_bf16 v[118:121], v[134:137], v[174:177], v[118:121]
	v_mfma_f32_16x16x32_bf16 v[114:117], v[142:145], v[174:177], v[114:117]
	v_mfma_f32_16x16x32_bf16 v[98:101], v[134:137], v[182:185], v[98:101]
	v_mfma_f32_16x16x32_bf16 v[90:93], v[142:145], v[182:185], v[90:93]
	v_mfma_f32_16x16x32_bf16 v[82:85], v[134:137], v[190:193], v[82:85]
	v_mfma_f32_16x16x32_bf16 v[74:77], v[142:145], v[190:193], v[74:77]
	v_mfma_f32_16x16x32_bf16 v[126:129], v[138:141], v[164:167], v[126:129]
	v_mfma_f32_16x16x32_bf16 v[122:125], v[146:149], v[164:167], v[122:125]
	v_mfma_f32_16x16x32_bf16 v[118:121], v[138:141], v[178:181], v[118:121]
	v_mfma_f32_16x16x32_bf16 v[114:117], v[146:149], v[178:181], v[114:117]
	v_mfma_f32_16x16x32_bf16 v[98:101], v[138:141], v[186:189], v[98:101]
	v_mfma_f32_16x16x32_bf16 v[90:93], v[146:149], v[186:189], v[90:93]
	v_mfma_f32_16x16x32_bf16 v[82:85], v[138:141], v[210:213], v[82:85]
	v_mfma_f32_16x16x32_bf16 v[74:77], v[146:149], v[210:213], v[74:77]
	s_setprio 0
	s_barrier
	s_add_i32 s9, 0, 0x1c000
	s_add_i32 s8, s8, s3
	v_add_u32_e32 v195, s9, v172
	v_lshl_add_u64 v[168:169], v[168:169], 0, s[96:97]
	s_mov_b32 m0, s8
	ds_read_b128 v[214:217], v195
	ds_read_b128 v[218:221], v195 offset:1024
	ds_read_b128 v[222:225], v195 offset:2048
	ds_read_b128 v[226:229], v195 offset:3072
	global_load_lds_dwordx4 v[168:169], off
	v_lshl_add_u64 v[168:169], v[198:199], 0, s[96:97]
	s_add_i32 m0, s8, 0x2000
	s_nop 0
	global_load_lds_dwordx4 v[168:169], off
	s_barrier
	s_waitcnt lgkmcnt(0)
	s_setprio 1
	s_waitcnt lgkmcnt(0)
	v_mfma_f32_16x16x32_bf16 v[110:113], v[214:217], v[160:163], v[110:113]
	v_mfma_f32_16x16x32_bf16 v[106:109], v[222:225], v[160:163], v[106:109]
	v_mfma_f32_16x16x32_bf16 v[102:105], v[214:217], v[174:177], v[102:105]
	v_mfma_f32_16x16x32_bf16 v[94:97], v[222:225], v[174:177], v[94:97]
	v_mfma_f32_16x16x32_bf16 v[86:89], v[214:217], v[182:185], v[86:89]
	v_mfma_f32_16x16x32_bf16 v[78:81], v[222:225], v[182:185], v[78:81]
	v_mfma_f32_16x16x32_bf16 v[70:73], v[214:217], v[190:193], v[70:73]
	v_mfma_f32_16x16x32_bf16 v[66:69], v[222:225], v[190:193], v[66:69]
	v_mfma_f32_16x16x32_bf16 v[110:113], v[218:221], v[164:167], v[110:113]
	v_mfma_f32_16x16x32_bf16 v[106:109], v[226:229], v[164:167], v[106:109]
	v_mfma_f32_16x16x32_bf16 v[102:105], v[218:221], v[178:181], v[102:105]
	v_mfma_f32_16x16x32_bf16 v[94:97], v[226:229], v[178:181], v[94:97]
	v_mfma_f32_16x16x32_bf16 v[86:89], v[218:221], v[186:189], v[86:89]
	v_mfma_f32_16x16x32_bf16 v[78:81], v[226:229], v[186:189], v[78:81]
	v_mfma_f32_16x16x32_bf16 v[70:73], v[218:221], v[210:213], v[70:73]
	v_mfma_f32_16x16x32_bf16 v[66:69], v[226:229], v[210:213], v[66:69]
	s_setprio 0
	s_mov_b32 m0, s44
	s_barrier
	ds_read_b128 v[160:163], v173 offset:49152
	ds_read_b128 v[164:167], v173 offset:50176
	ds_read_b128 v[174:177], v173 offset:51200
	ds_read_b128 v[178:181], v173 offset:52224
	ds_read_b128 v[182:185], v173 offset:53248
	ds_read_b128 v[186:189], v173 offset:54272
	ds_read_b128 v[190:193], v173 offset:55296
	ds_read_b128 v[210:213], v173 offset:56320
	global_load_lds_dwordx4 v154, s[22:23]
	s_mov_b32 m0, s45
	s_nop 0
	global_load_lds_dwordx4 v152, s[22:23]
	s_barrier
; #define PG8_STAGE(bufoff, gbase, voff) do { _Pragma("unroll") for (int _i = 0; _i < 2; ++_i) \
;     __builtin_amdgcn_global_load_lds((const unsigned*)((const char*)(gbase) + (voff)[_i]), (LAS unsigned*)(lds + (bufoff) + ldsw + _i * 8192), 16, 0, 0); } while (0)
; #define PG8_MMA(ai, bj, At, Bt) do { __builtin_amdgcn_s_setprio(1); _Pragma("unroll") for (int m = 0; m < 4; ++m) _Pragma("unroll") for (int n = 0; n < 2; ++n) _Pragma("unroll") for (int k = 0; k < 2; ++k) \
;     acc[ai][bj][m][n] = __builtin_amdgcn_mfma_f32_16x16x32_bf16(Bt[n][k], At[m][k], acc[ai][bj][m][n], 0, 0, 0); __builtin_amdgcn_s_setprio(0); } while (0)
; #define PG8_WAIT_V(n) asm volatile("s_waitcnt vmcnt(" #n ")" ::: "memory")
; #define PG8_BAR __builtin_amdgcn_s_barrier()
; template <class Epi, bool SPLITA = false>
; __device__ __forceinline__ void gemm_phase(const int tid, LAS unsigned char* lds, const Gemm g, const Order& S, const Epi& E) {
;     ...
;       PG8_STAGE(PG8_SB(1, 1), b3 + hstepB, voffB);
;       PG8_WAIT_V(6); PG8_BAR; PG8_MMA(1, 1, At, B1); PG8_BAR;
;     }
;     E(acc, cur, wr, wc, fr, fq);
;     if (!has_next) break;
;   __device__ __forceinline__ void operator()(const Acc& acc, const Unit& u, int wr, int wc, int fr_, int fq_) const {
;     int fr = fr_, fq = fq_; asm volatile("" : "+v"(fr), "+v"(fq));
;     const int lane = fq * 16 + fr;
;     const int row0 = u.pm * BM + wr * 64 + fr, col0 = u.pn * BM + wc * 32 + 8 * fq;
; #pragma unroll
;     for (int ai = 0; ai < 2; ++ai) {
;       u32x4 hv[4][2];
; #pragma unroll
;       for (int m = 0; m < 4; ++m)
; #pragma unroll
;         for (int bj = 0; bj < 2; ++bj) hv[m][bj] = *(const u32x4*)(rin + (size_t)(row0 + ai * HALF + m * 16) * DM + col0 + bj * HALF);
	s_waitcnt lgkmcnt(0)
	s_setprio 1
	s_waitcnt lgkmcnt(0)
	v_mfma_f32_16x16x32_bf16 v[62:65], v[134:137], v[160:163], v[62:65]
	v_mfma_f32_16x16x32_bf16 v[58:61], v[142:145], v[160:163], v[58:61]
	v_mfma_f32_16x16x32_bf16 v[50:53], v[134:137], v[174:177], v[50:53]
	v_mfma_f32_16x16x32_bf16 v[42:45], v[142:145], v[174:177], v[42:45]
	v_mfma_f32_16x16x32_bf16 v[34:37], v[134:137], v[182:185], v[34:37]
	v_mfma_f32_16x16x32_bf16 v[26:29], v[142:145], v[182:185], v[26:29]
	v_mfma_f32_16x16x32_bf16 v[18:21], v[134:137], v[190:193], v[18:21]
	v_mfma_f32_16x16x32_bf16 v[10:13], v[142:145], v[190:193], v[10:13]
	v_mfma_f32_16x16x32_bf16 v[62:65], v[138:141], v[164:167], v[62:65]
	v_mfma_f32_16x16x32_bf16 v[58:61], v[146:149], v[164:167], v[58:61]
	v_mfma_f32_16x16x32_bf16 v[50:53], v[138:141], v[178:181], v[50:53]
	v_mfma_f32_16x16x32_bf16 v[42:45], v[146:149], v[178:181], v[42:45]
	v_mfma_f32_16x16x32_bf16 v[34:37], v[138:141], v[186:189], v[34:37]
	v_mfma_f32_16x16x32_bf16 v[26:29], v[146:149], v[186:189], v[26:29]
	v_mfma_f32_16x16x32_bf16 v[18:21], v[138:141], v[210:213], v[18:21]
	v_mfma_f32_16x16x32_bf16 v[10:13], v[146:149], v[210:213], v[10:13]
	s_setprio 0
	s_barrier
	s_add_u32 s18, s18, 0x160080
	s_addc_u32 s19, s19, 0
	s_add_i32 s8, s9, s3
	s_mov_b32 m0, s8
	s_nop 0
	global_load_lds_dwordx4 v0, s[18:19]
	s_add_i32 m0, s8, 0x2000
	s_nop 0
	global_load_lds_dwordx4 v150, s[18:19]
	s_waitcnt vmcnt(6)
	s_barrier
	s_setprio 1
	v_mfma_f32_16x16x32_bf16 v[54:57], v[214:217], v[160:163], v[54:57]
	v_mfma_f32_16x16x32_bf16 v[46:49], v[222:225], v[160:163], v[46:49]
	v_mfma_f32_16x16x32_bf16 v[38:41], v[214:217], v[174:177], v[38:41]
	v_mfma_f32_16x16x32_bf16 v[30:33], v[222:225], v[174:177], v[30:33]
	v_mfma_f32_16x16x32_bf16 v[22:25], v[214:217], v[182:185], v[22:25]
	v_mfma_f32_16x16x32_bf16 v[14:17], v[222:225], v[182:185], v[14:17]
	v_mfma_f32_16x16x32_bf16 v[6:9], v[214:217], v[190:193], v[6:9]
	v_mfma_f32_16x16x32_bf16 v[2:5], v[222:225], v[190:193], v[2:5]
	v_mfma_f32_16x16x32_bf16 v[54:57], v[218:221], v[164:167], v[54:57]
	v_mfma_f32_16x16x32_bf16 v[46:49], v[226:229], v[164:167], v[46:49]
	v_mfma_f32_16x16x32_bf16 v[38:41], v[218:221], v[178:181], v[38:41]
	v_mfma_f32_16x16x32_bf16 v[30:33], v[226:229], v[178:181], v[30:33]
	v_mfma_f32_16x16x32_bf16 v[22:25], v[218:221], v[186:189], v[22:25]
	v_mfma_f32_16x16x32_bf16 v[14:17], v[226:229], v[186:189], v[14:17]
	v_mfma_f32_16x16x32_bf16 v[6:9], v[218:221], v[210:213], v[6:9]
	v_mfma_f32_16x16x32_bf16 v[2:5], v[226:229], v[210:213], v[2:5]
	s_setprio 0
	s_add_i32 s29, s29, 2
	s_add_u32 s16, s16, 0x100
	s_addc_u32 s17, s17, 0
	s_cmpk_gt_u32 s29, 0x55
	s_barrier
	s_cbranch_scc0 .LBB0_57
	s_lshl_b32 s6, s51, 8
	v_mov_b32_e32 v130, v171
	v_mov_b32_e32 v131, v170
	s_add_i32 s6, s6, s42
	v_readlane_b32 s40, v255, 9
	v_add_u32_e32 v160, s6, v130
	s_lshl_b32 s6, s52, 8
	s_or_b32 s6, s6, s43
	v_lshl_add_u32 v186, v131, 3, s6
	v_readlane_b32 s6, v255, 5
	v_ashrrev_i32_e32 v187, 31, v186
	v_readlane_b32 s7, v255, 6
	v_ashrrev_i32_e32 v161, 31, v160
	v_lshlrev_b64 v[130:131], 12, v[160:161]
	v_lshl_add_u64 v[162:163], v[186:187], 1, s[6:7]
	v_lshl_add_u64 v[130:131], v[162:163], 0, v[130:131]
	global_load_dwordx4 v[174:177], v[130:131], off
	global_load_dwordx4 v[178:181], v[130:131], off offset:256
	v_add_u32_e32 v168, 16, v160
	v_ashrrev_i32_e32 v169, 31, v168
	v_lshlrev_b64 v[130:131], 12, v[168:169]
	v_lshl_add_u64 v[130:131], v[162:163], 0, v[130:131]
	global_load_dwordx4 v[182:185], v[130:131], off
	global_load_dwordx4 v[146:149], v[130:131], off offset:256
	v_add_u32_e32 v166, 32, v160
	v_ashrrev_i32_e32 v167, 31, v166
	v_lshlrev_b64 v[130:131], 12, v[166:167]
	v_lshl_add_u64 v[130:131], v[162:163], 0, v[130:131]
	global_load_dwordx4 v[142:145], v[130:131], off
	global_load_dwordx4 v[138:141], v[130:131], off offset:256
	v_add_u32_e32 v164, 48, v160
	v_ashrrev_i32_e32 v165, 31, v164
	v_lshlrev_b64 v[130:131], 12, v[164:165]
	v_lshl_add_u64 v[130:131], v[162:163], 0, v[130:131]
	global_load_dwordx4 v[134:137], v[130:131], off
	s_nop 0
	global_load_dwordx4 v[130:133], v[130:131], off offset:256
	s_and_b64 vcc, exec, s[38:39]
	s_mov_b32 s52, s48
	s_mov_b32 s51, s49
	s_mov_b64 s[16:17], s[10:11]
	s_mov_b64 s[12:13], s[0:1]
	s_mov_b64 s[20:21], s[34:35]
	v_readlane_b32 s41, v255, 10
	s_waitcnt vmcnt(0)
; __device__ __forceinline__ float bflo(unsigned w) { return __uint_as_float(w << 16); }
; __device__ __forceinline__ float bfhi(unsigned w) { return __uint_as_float(w & 0xffff0000u); }
; __device__ __forceinline__ u32x4 pack8(const f32x4 v0, const f32x4 v1) { u32x4 w; w.x = cvtpk(v0[0], v0[1]); w.y = cvtpk(v0[2], v0[3]); w.z = cvtpk(v1[0], v1[1]); w.w = cvtpk(v1[2], v1[3]); return w; }
;   __device__ __forceinline__ void operator()(const Acc& acc, const Unit& u, int wr, int wc, int fr_, int fq_) const {
;     ...
;     for (int ai = 0; ai < 2; ++ai) {
;       u32x4 hv[4][2];
; #pragma unroll
;       for (int m = 0; m < 4; ++m)
; #pragma unroll
;         for (int bj = 0; bj < 2; ++bj) hv[m][bj] = *(const u32x4*)(rin + (size_t)(row0 + ai * HALF + m * 16) * DM + col0 + bj * HALF);
; #pragma unroll
;       for (int m = 0; m < 4; ++m) { const size_t ro = (size_t)(row0 + ai * HALF + m * 16) * DM + col0; float ss = 0.f;
; #pragma unroll
;         for (int bj = 0; bj < 2; ++bj) { const u32x4 h = hv[m][bj];
;           f32x4 v0 = acc[ai][bj][m][0], v1 = acc[ai][bj][m][1];
;           v0[0] += bflo(h.x); v0[1] += bfhi(h.x); v0[2] += bflo(h.y); v0[3] += bfhi(h.y);
;           v1[0] += bflo(h.z); v1[1] += bfhi(h.z); v1[2] += bflo(h.w); v1[3] += bfhi(h.w);
;           if (FINAL) { *(f32x4*)(outf + ro + bj * HALF) = v0; *(f32x4*)(outf + ro + bj * HALF + 4) = v1; }
;           else { ss += v0[0] * v0[0] + v0[1] * v0[1] + v0[2] * v0[2] + v0[3] * v0[3] + v1[0] * v1[0] + v1[1] * v1[1] + v1[2] * v1[2] + v1[3] * v1[3];
;             *(u32x4*)(outb + ro + bj * HALF) = pack8(v0, v1); } }
	v_lshlrev_b32_e32 v188, 16, v174
	v_and_b32_e32 v189, 0xffff0000, v174
	v_lshlrev_b32_e32 v174, 16, v175
	v_and_b32_e32 v175, 0xffff0000, v175
	v_pk_add_f32 v[128:129], v[128:129], v[174:175]
	v_lshlrev_b32_e32 v174, 16, v176
	v_and_b32_e32 v175, 0xffff0000, v176
	v_pk_add_f32 v[174:175], v[122:123], v[174:175]
	v_lshlrev_b32_e32 v122, 16, v177
	v_and_b32_e32 v123, 0xffff0000, v177
	v_pk_add_f32 v[176:177], v[124:125], v[122:123]
	v_lshlrev_b64 v[122:123], 13, v[160:161]
	v_lshl_add_u64 v[124:125], s[86:87], 0, v[122:123]
	v_lshlrev_b64 v[122:123], 2, v[186:187]
	v_pk_add_f32 v[126:127], v[126:127], v[188:189]
	v_lshl_add_u64 v[124:125], v[124:125], 0, v[122:123]
	global_store_dwordx4 v[124:125], v[126:129], off
	global_store_dwordx4 v[124:125], v[174:177], off offset:16
	s_nop 0
	v_lshlrev_b32_e32 v126, 16, v178
	v_and_b32_e32 v127, 0xffff0000, v178
	v_pk_add_f32 v[110:111], v[110:111], v[126:127]
	v_lshlrev_b32_e32 v126, 16, v179
	v_and_b32_e32 v127, 0xffff0000, v179
	v_pk_add_f32 v[112:113], v[112:113], v[126:127]
	v_lshlrev_b32_e32 v126, 16, v180
	v_and_b32_e32 v127, 0xffff0000, v180
	v_pk_add_f32 v[106:107], v[106:107], v[126:127]
	v_lshlrev_b32_e32 v126, 16, v181
	v_and_b32_e32 v127, 0xffff0000, v181
	v_pk_add_f32 v[108:109], v[108:109], v[126:127]
	global_store_dwordx4 v[124:125], v[110:113], off offset:512
	global_store_dwordx4 v[124:125], v[106:109], off offset:528
	s_nop 0
	v_lshlrev_b32_e32 v110, 16, v184
	v_and_b32_e32 v111, 0xffff0000, v184
	v_pk_add_f32 v[110:111], v[114:115], v[110:111]
	v_lshlrev_b64 v[114:115], 13, v[168:169]
	v_lshlrev_b32_e32 v106, 16, v182
	v_and_b32_e32 v107, 0xffff0000, v182
	v_lshlrev_b32_e32 v108, 16, v183
	v_and_b32_e32 v109, 0xffff0000, v183
	v_lshl_add_u64 v[114:115], s[86:87], 0, v[114:115]
	v_pk_add_f32 v[106:107], v[118:119], v[106:107]
	v_pk_add_f32 v[108:109], v[120:121], v[108:109]
	v_lshlrev_b32_e32 v112, 16, v185
	v_and_b32_e32 v113, 0xffff0000, v185
	v_lshl_add_u64 v[114:115], v[114:115], 0, v[122:123]
	v_pk_add_f32 v[112:113], v[116:117], v[112:113]
	global_store_dwordx4 v[114:115], v[106:109], off
	global_store_dwordx4 v[114:115], v[110:113], off offset:16
	s_nop 0
	v_lshlrev_b32_e32 v106, 16, v146
	v_and_b32_e32 v107, 0xffff0000, v146
	v_pk_add_f32 v[102:103], v[102:103], v[106:107]
	v_lshlrev_b32_e32 v106, 16, v147
	v_and_b32_e32 v107, 0xffff0000, v147
	v_pk_add_f32 v[104:105], v[104:105], v[106:107]
	v_lshlrev_b32_e32 v106, 16, v148
	v_and_b32_e32 v107, 0xffff0000, v148
	v_pk_add_f32 v[94:95], v[94:95], v[106:107]
	v_lshlrev_b32_e32 v106, 16, v149
	v_and_b32_e32 v107, 0xffff0000, v149
	v_pk_add_f32 v[96:97], v[96:97], v[106:107]
	global_store_dwordx4 v[114:115], v[102:105], off offset:512
	global_store_dwordx4 v[114:115], v[94:97], off offset:528
	s_nop 0
	v_add_u32_e32 v102, 0xa0, v160
	v_lshlrev_b32_e32 v94, 16, v142
	v_and_b32_e32 v95, 0xffff0000, v142
	v_pk_add_f32 v[94:95], v[98:99], v[94:95]
	v_lshlrev_b32_e32 v98, 16, v144
	v_and_b32_e32 v99, 0xffff0000, v144
	v_pk_add_f32 v[90:91], v[90:91], v[98:99]
	v_lshlrev_b32_e32 v98, 16, v145
	v_and_b32_e32 v99, 0xffff0000, v145
	v_pk_add_f32 v[92:93], v[92:93], v[98:99]
	v_lshlrev_b64 v[98:99], 13, v[166:167]
	v_lshlrev_b32_e32 v96, 16, v143
	v_and_b32_e32 v97, 0xffff0000, v143
	v_lshl_add_u64 v[98:99], s[86:87], 0, v[98:99]
	v_pk_add_f32 v[96:97], v[100:101], v[96:97]
	v_lshl_add_u64 v[98:99], v[98:99], 0, v[122:123]
	global_store_dwordx4 v[98:99], v[94:97], off
	global_store_dwordx4 v[98:99], v[90:93], off offset:16
	v_add_u32_e32 v100, 0x90, v160
	v_ashrrev_i32_e32 v101, 31, v100
	v_lshlrev_b32_e32 v90, 16, v138
	v_and_b32_e32 v91, 0xffff0000, v138
	v_pk_add_f32 v[86:87], v[86:87], v[90:91]
	v_lshlrev_b32_e32 v90, 16, v139
	v_and_b32_e32 v91, 0xffff0000, v139
	v_pk_add_f32 v[88:89], v[88:89], v[90:91]
	v_lshlrev_b32_e32 v90, 16, v140
	v_and_b32_e32 v91, 0xffff0000, v140
	v_pk_add_f32 v[78:79], v[78:79], v[90:91]
	v_lshlrev_b32_e32 v90, 16, v141
	v_and_b32_e32 v91, 0xffff0000, v141
	v_pk_add_f32 v[80:81], v[80:81], v[90:91]
	global_store_dwordx4 v[98:99], v[86:89], off offset:512
	global_store_dwordx4 v[98:99], v[78:81], off offset:528
	v_add_u32_e32 v98, 0x80, v160
	v_ashrrev_i32_e32 v99, 31, v98
	v_lshlrev_b32_e32 v78, 16, v134
	v_and_b32_e32 v79, 0xffff0000, v134
	v_pk_add_f32 v[78:79], v[82:83], v[78:79]
	v_lshlrev_b32_e32 v82, 16, v136
	v_and_b32_e32 v83, 0xffff0000, v136
	v_pk_add_f32 v[74:75], v[74:75], v[82:83]
	v_lshlrev_b32_e32 v82, 16, v137
	v_and_b32_e32 v83, 0xffff0000, v137
	v_pk_add_f32 v[76:77], v[76:77], v[82:83]
	v_lshlrev_b64 v[82:83], 13, v[164:165]
	v_lshlrev_b32_e32 v80, 16, v135
	v_and_b32_e32 v81, 0xffff0000, v135
	v_lshl_add_u64 v[82:83], s[86:87], 0, v[82:83]
	v_pk_add_f32 v[80:81], v[84:85], v[80:81]
	v_lshl_add_u64 v[82:83], v[82:83], 0, v[122:123]
	global_store_dwordx4 v[82:83], v[78:81], off
	global_store_dwordx4 v[82:83], v[74:77], off offset:16
	v_ashrrev_i32_e32 v103, 31, v102
	v_add_u32_e32 v104, 0xb0, v160
	v_lshlrev_b32_e32 v74, 16, v130
	v_and_b32_e32 v75, 0xffff0000, v130
	v_pk_add_f32 v[70:71], v[70:71], v[74:75]
	v_lshlrev_b32_e32 v74, 16, v131
	v_and_b32_e32 v75, 0xffff0000, v131
	v_pk_add_f32 v[72:73], v[72:73], v[74:75]
	v_lshlrev_b32_e32 v74, 16, v132
	v_and_b32_e32 v75, 0xffff0000, v132
	v_pk_add_f32 v[66:67], v[66:67], v[74:75]
	v_lshlrev_b32_e32 v74, 16, v133
	v_and_b32_e32 v75, 0xffff0000, v133
	v_pk_add_f32 v[68:69], v[68:69], v[74:75]
	global_store_dwordx4 v[82:83], v[70:73], off offset:512
	global_store_dwordx4 v[82:83], v[66:69], off offset:528
	v_ashrrev_i32_e32 v105, 31, v104
	s_nop 0
	v_lshlrev_b64 v[66:67], 12, v[98:99]
	v_lshl_add_u64 v[66:67], v[162:163], 0, v[66:67]
	global_load_dwordx4 v[70:73], v[66:67], off
	global_load_dwordx4 v[74:77], v[66:67], off offset:256
	v_lshlrev_b64 v[66:67], 12, v[100:101]
	v_lshl_add_u64 v[66:67], v[162:163], 0, v[66:67]
	global_load_dwordx4 v[78:81], v[66:67], off
	global_load_dwordx4 v[82:85], v[66:67], off offset:256
	v_lshlrev_b64 v[66:67], 12, v[102:103]
	v_lshl_add_u64 v[66:67], v[162:163], 0, v[66:67]
	global_load_dwordx4 v[86:89], v[66:67], off
	global_load_dwordx4 v[90:93], v[66:67], off offset:256
	v_lshlrev_b64 v[66:67], 12, v[104:105]
	v_lshl_add_u64 v[66:67], v[162:163], 0, v[66:67]
	global_load_dwordx4 v[94:97], v[66:67], off
	s_nop 0
	global_load_dwordx4 v[66:69], v[66:67], off offset:256
	s_waitcnt vmcnt(0)
; __device__ __forceinline__ float bflo(unsigned w) { return __uint_as_float(w << 16); }
; __device__ __forceinline__ float bfhi(unsigned w) { return __uint_as_float(w & 0xffff0000u); }
; __device__ __forceinline__ u32x4 pack8(const f32x4 v0, const f32x4 v1) { u32x4 w; w.x = cvtpk(v0[0], v0[1]); w.y = cvtpk(v0[2], v0[3]); w.z = cvtpk(v1[0], v1[1]); w.w = cvtpk(v1[2], v1[3]); return w; }
;   __device__ __forceinline__ void operator()(const Acc& acc, const Unit& u, int wr, int wc, int fr_, int fq_) const {
;     ...
;     for (int ai = 0; ai < 2; ++ai) {
;       u32x4 hv[4][2];
; #pragma unroll
;       for (int m = 0; m < 4; ++m)
; #pragma unroll
;         for (int bj = 0; bj < 2; ++bj) hv[m][bj] = *(const u32x4*)(rin + (size_t)(row0 + ai * HALF + m * 16) * DM + col0 + bj * HALF);
; #pragma unroll
;       for (int m = 0; m < 4; ++m) { const size_t ro = (size_t)(row0 + ai * HALF + m * 16) * DM + col0; float ss = 0.f;
; #pragma unroll
;         for (int bj = 0; bj < 2; ++bj) { const u32x4 h = hv[m][bj];
;           f32x4 v0 = acc[ai][bj][m][0], v1 = acc[ai][bj][m][1];
;           v0[0] += bflo(h.x); v0[1] += bfhi(h.x); v0[2] += bflo(h.y); v0[3] += bfhi(h.y);
;           v1[0] += bflo(h.z); v1[1] += bfhi(h.z); v1[2] += bflo(h.w); v1[3] += bfhi(h.w);
;           if (FINAL) { *(f32x4*)(outf + ro + bj * HALF) = v0; *(f32x4*)(outf + ro + bj * HALF + 4) = v1; }
;           else { ss += v0[0] * v0[0] + v0[1] * v0[1] + v0[2] * v0[2] + v0[3] * v0[3] + v1[0] * v1[0] + v1[1] * v1[1] + v1[2] * v1[2] + v1[3] * v1[3];
;             *(u32x4*)(outb + ro + bj * HALF) = pack8(v0, v1); } }
	v_lshlrev_b32_e32 v106, 16, v70
	v_and_b32_e32 v107, 0xffff0000, v70
	v_lshlrev_b32_e32 v70, 16, v71
	v_and_b32_e32 v71, 0xffff0000, v71
	v_pk_add_f32 v[64:65], v[64:65], v[70:71]
	v_lshlrev_b32_e32 v70, 16, v72
	v_and_b32_e32 v71, 0xffff0000, v72
	v_pk_add_f32 v[58:59], v[58:59], v[70:71]
	v_lshlrev_b32_e32 v70, 16, v73
	v_and_b32_e32 v71, 0xffff0000, v73
	v_pk_add_f32 v[60:61], v[60:61], v[70:71]
	v_lshlrev_b64 v[70:71], 13, v[98:99]
	v_lshl_add_u64 v[70:71], s[86:87], 0, v[70:71]
	v_pk_add_f32 v[62:63], v[62:63], v[106:107]
	v_lshl_add_u64 v[70:71], v[70:71], 0, v[122:123]
	global_store_dwordx4 v[70:71], v[62:65], off
	global_store_dwordx4 v[70:71], v[58:61], off offset:16
	s_nop 1
	v_lshlrev_b32_e32 v58, 16, v74
	v_and_b32_e32 v59, 0xffff0000, v74
	v_pk_add_f32 v[54:55], v[54:55], v[58:59]
	v_lshlrev_b32_e32 v58, 16, v75
	v_and_b32_e32 v59, 0xffff0000, v75
	v_pk_add_f32 v[56:57], v[56:57], v[58:59]
	v_lshlrev_b32_e32 v58, 16, v76
	v_and_b32_e32 v59, 0xffff0000, v76
	v_pk_add_f32 v[46:47], v[46:47], v[58:59]
	v_lshlrev_b32_e32 v58, 16, v77
	v_and_b32_e32 v59, 0xffff0000, v77
	v_pk_add_f32 v[48:49], v[48:49], v[58:59]
	global_store_dwordx4 v[70:71], v[54:57], off offset:512
	global_store_dwordx4 v[70:71], v[46:49], off offset:528
	s_nop 1
	v_lshlrev_b32_e32 v46, 16, v78
	v_and_b32_e32 v47, 0xffff0000, v78
	v_pk_add_f32 v[46:47], v[50:51], v[46:47]
	v_lshlrev_b32_e32 v50, 16, v80
	v_and_b32_e32 v51, 0xffff0000, v80
	v_pk_add_f32 v[42:43], v[42:43], v[50:51]
	v_lshlrev_b32_e32 v50, 16, v81
	v_and_b32_e32 v51, 0xffff0000, v81
	v_pk_add_f32 v[44:45], v[44:45], v[50:51]
	v_lshlrev_b64 v[50:51], 13, v[100:101]
	v_lshlrev_b32_e32 v48, 16, v79
	v_and_b32_e32 v49, 0xffff0000, v79
	v_lshl_add_u64 v[50:51], s[86:87], 0, v[50:51]
	v_pk_add_f32 v[48:49], v[52:53], v[48:49]
	v_lshl_add_u64 v[50:51], v[50:51], 0, v[122:123]
	global_store_dwordx4 v[50:51], v[46:49], off
	global_store_dwordx4 v[50:51], v[42:45], off offset:16
	s_nop 1
	v_lshlrev_b32_e32 v42, 16, v82
	v_and_b32_e32 v43, 0xffff0000, v82
	v_pk_add_f32 v[38:39], v[38:39], v[42:43]
	v_lshlrev_b32_e32 v42, 16, v83
	v_and_b32_e32 v43, 0xffff0000, v83
	v_pk_add_f32 v[40:41], v[40:41], v[42:43]
	v_lshlrev_b32_e32 v42, 16, v84
	v_and_b32_e32 v43, 0xffff0000, v84
	v_pk_add_f32 v[30:31], v[30:31], v[42:43]
	v_lshlrev_b32_e32 v42, 16, v85
	v_and_b32_e32 v43, 0xffff0000, v85
	v_pk_add_f32 v[32:33], v[32:33], v[42:43]
	global_store_dwordx4 v[50:51], v[38:41], off offset:512
	global_store_dwordx4 v[50:51], v[30:33], off offset:528
	s_nop 1
	v_lshlrev_b32_e32 v30, 16, v86
	v_and_b32_e32 v31, 0xffff0000, v86
	v_pk_add_f32 v[30:31], v[34:35], v[30:31]
	v_lshlrev_b32_e32 v34, 16, v88
	v_and_b32_e32 v35, 0xffff0000, v88
	v_pk_add_f32 v[26:27], v[26:27], v[34:35]
	v_lshlrev_b32_e32 v34, 16, v89
	v_and_b32_e32 v35, 0xffff0000, v89
	v_pk_add_f32 v[28:29], v[28:29], v[34:35]
	v_lshlrev_b64 v[34:35], 13, v[102:103]
	v_lshlrev_b32_e32 v32, 16, v87
	v_and_b32_e32 v33, 0xffff0000, v87
	v_lshl_add_u64 v[34:35], s[86:87], 0, v[34:35]
	v_pk_add_f32 v[32:33], v[36:37], v[32:33]
	v_lshl_add_u64 v[34:35], v[34:35], 0, v[122:123]
	global_store_dwordx4 v[34:35], v[30:33], off
	global_store_dwordx4 v[34:35], v[26:29], off offset:16
	s_nop 1
	v_lshlrev_b32_e32 v26, 16, v90
	v_and_b32_e32 v27, 0xffff0000, v90
	v_pk_add_f32 v[22:23], v[22:23], v[26:27]
	v_lshlrev_b32_e32 v26, 16, v91
	v_and_b32_e32 v27, 0xffff0000, v91
	v_pk_add_f32 v[24:25], v[24:25], v[26:27]
	v_lshlrev_b32_e32 v26, 16, v92
	v_and_b32_e32 v27, 0xffff0000, v92
	v_pk_add_f32 v[14:15], v[14:15], v[26:27]
	v_lshlrev_b32_e32 v26, 16, v93
	v_and_b32_e32 v27, 0xffff0000, v93
	v_pk_add_f32 v[16:17], v[16:17], v[26:27]
	global_store_dwordx4 v[34:35], v[22:25], off offset:512
	global_store_dwordx4 v[34:35], v[14:17], off offset:528
	s_nop 1
	v_lshlrev_b32_e32 v14, 16, v94
	v_and_b32_e32 v15, 0xffff0000, v94
	v_pk_add_f32 v[14:15], v[18:19], v[14:15]
	v_lshlrev_b32_e32 v18, 16, v96
	v_and_b32_e32 v19, 0xffff0000, v96
	v_pk_add_f32 v[10:11], v[10:11], v[18:19]
	v_lshlrev_b32_e32 v18, 16, v97
	v_and_b32_e32 v19, 0xffff0000, v97
	v_pk_add_f32 v[12:13], v[12:13], v[18:19]
	v_lshlrev_b64 v[18:19], 13, v[104:105]
	v_lshlrev_b32_e32 v16, 16, v95
	v_and_b32_e32 v17, 0xffff0000, v95
	v_lshl_add_u64 v[18:19], s[86:87], 0, v[18:19]
	v_pk_add_f32 v[16:17], v[20:21], v[16:17]
	v_lshl_add_u64 v[18:19], v[18:19], 0, v[122:123]
	global_store_dwordx4 v[18:19], v[14:17], off
	global_store_dwordx4 v[18:19], v[10:13], off offset:16
	s_nop 1
	v_lshlrev_b32_e32 v10, 16, v66
	v_and_b32_e32 v11, 0xffff0000, v66
	v_pk_add_f32 v[6:7], v[6:7], v[10:11]
	v_lshlrev_b32_e32 v10, 16, v67
	v_and_b32_e32 v11, 0xffff0000, v67
	v_pk_add_f32 v[8:9], v[8:9], v[10:11]
	v_lshlrev_b32_e32 v10, 16, v68
	v_and_b32_e32 v11, 0xffff0000, v68
	v_pk_add_f32 v[2:3], v[2:3], v[10:11]
	v_lshlrev_b32_e32 v10, 16, v69
	v_and_b32_e32 v11, 0xffff0000, v69
	v_pk_add_f32 v[4:5], v[4:5], v[10:11]
	global_store_dwordx4 v[18:19], v[6:9], off offset:512
	global_store_dwordx4 v[18:19], v[2:5], off offset:528
	s_cbranch_vccz .LBB0_46
	s_waitcnt vmcnt(0)
	v_mov_b32_e32 v219, v196
	s_cmpk_gt_u32 s2, 0xff
	s_cbranch_scc1 .LBB0_61
	s_barrier

; #define PG8_STAGE(bufoff, gbase, voff) do { _Pragma("unroll") for (int _i = 0; _i < 2; ++_i) \
;     __builtin_amdgcn_global_load_lds((const unsigned*)((const char*)(gbase) + (voff)[_i]), (LAS unsigned*)(lds + (bufoff) + ldsw + _i * 8192), 16, 0, 0); } while (0)
; #define PG8_WAIT_V(n) asm volatile("s_waitcnt vmcnt(" #n ")" ::: "memory")
; #define PG8_BAR __builtin_amdgcn_s_barrier()
; template <class Epi, bool SPLITA = false>
; __device__ __forceinline__ void gemm_phase(const int tid, LAS unsigned char* lds, const Gemm g, const Order& S, const Epi& E) {
;     ...
;   PG8_STAGE(PG8_SB(0, 0), cB, voffB); PG8_STAGE(PG8_SA(0, 0), cA, voffA); PG8_STAGE(PG8_SB(0, 1), cB + hstepB, voffB); PG8_STAGE(PG8_SA(0, 1), cA + hstepA, voffA);
;   if (wr == 1) PG8_BAR;
;   PG8_WAIT_V(4); PG8_BAR;
;   PG8_STAGE(PG8_SB(1, 0), cB + kstep, voffB); PG8_STAGE(PG8_SA(1, 0), cA + kstep, voffA); PG8_STAGE(PG8_SB(1, 1), cB + hstepB + kstep, voffB);
;   PG8_WAIT_V(6); PG8_BAR;
.LBB0_74:
	v_bfe_u32 v186, v210, 4, 2
	v_and_b32_e32 v187, 15, v210
	v_lshlrev_b32_e32 v18, 4, v186
	v_lshlrev_b32_e32 v19, 2, v210
	s_and_b32 s44, s0, 3
	v_lshl_or_b32 v18, v187, 6, v18
	s_lshl_b32 s0, s1, 13
	v_and_b32_e32 v19, 32, v19
	s_add_i32 m0, s30, 0x18000
	v_lshl_add_u64 v[8:9], v[8:9], 0, s[96:97]
	s_lshl_b32 s45, s1, 6
	v_bitop3_b32 v20, v18, s0, v19 bitop3:0xde
	s_lshl_b32 s46, s44, 5
	s_lshl_b32 s0, s44, 12
	s_waitcnt vmcnt(4)
	s_barrier
	global_load_lds_dwordx4 v[8:9], off
	v_lshl_add_u64 v[6:7], v[6:7], 0, s[96:97]
	s_add_i32 m0, s30, 0x1a000
	s_add_i32 s47, s30, 0x8000
	s_add_i32 s48, s30, 0xa000
	v_bitop3_b32 v188, v18, s0, v19 bitop3:0xde
	global_load_lds_dwordx4 v[6:7], off
	v_lshl_add_u64 v[4:5], v[4:5], 0, s[96:97]
	s_mov_b32 m0, s47
	s_add_u32 s0, s16, 0x160080
	global_load_lds_dwordx4 v[4:5], off
	v_lshl_add_u64 v[2:3], v[2:3], 0, s[96:97]
	s_mov_b32 m0, s48
	s_addc_u32 s1, s17, 0
	global_load_lds_dwordx4 v[2:3], off
	s_add_i32 m0, s30, 0x1c000
	s_nop 0
	global_load_lds_dwordx4 v0, s[0:1]
	v_lshl_add_u64 v[2:3], s[0:1], 0, v[162:163]
	s_add_i32 m0, s30, 0x1e000
	s_movk_i32 s6, 0x1600
	global_load_lds_dwordx4 v162, s[0:1]
	v_lshrrev_b32_e32 v3, 1, v10
	v_mul_lo_u32 v2, v12, s6
	s_mov_b32 s7, 0x16000
	v_mad_u64_u32 v[2:3], s[0:1], v3, s7, v[2:3]
	v_or_b32_e32 v2, v2, v11
	v_add_lshl_u32 v164, v2, v13, 1
	v_lshrrev_b32_e32 v3, 1, v14
	v_mul_lo_u32 v2, v16, s6
	s_waitcnt vmcnt(6)
	v_mad_u64_u32 v[2:3], s[0:1], v3, s7, v[2:3]
	v_or_b32_e32 v2, v2, v15
	s_ashr_i32 s49, s92, 31
	v_mov_b32_e32 v165, v1
	v_add_lshl_u32 v166, v2, v17, 1
	v_mov_b32_e32 v167, v1
	s_mov_b32 s51, 0
	v_add_u32_e32 v189, 0, v20
	s_barrier
	s_branch .LBB0_76

; #define PG8_STAGE(bufoff, gbase, voff) do { _Pragma("unroll") for (int _i = 0; _i < 2; ++_i) \
;     __builtin_amdgcn_global_load_lds((const unsigned*)((const char*)(gbase) + (voff)[_i]), (LAS unsigned*)(lds + (bufoff) + ldsw + _i * 8192), 16, 0, 0); } while (0)
; #define PG8_LDA(dst, b, h) do { _Pragma("unroll") for (int m = 0; m < 4; ++m) _Pragma("unroll") for (int k = 0; k < 2; ++k) dst[m][k] = *(const LAS bf16x8*)(lds + PG8_SA(b, h) + aoff + m * 2048 + k * 1024); } while (0)
; #define PG8_LDB(dst, b, h) do { _Pragma("unroll") for (int n = 0; n < 2; ++n) _Pragma("unroll") for (int k = 0; k < 2; ++k) dst[n][k] = *(const LAS bf16x8*)(lds + PG8_SB(b, h) + boff + n * 2048 + k * 1024); } while (0)
; #define PG8_MMA(ai, bj, At, Bt) do { __builtin_amdgcn_s_setprio(1); _Pragma("unroll") for (int m = 0; m < 4; ++m) _Pragma("unroll") for (int n = 0; n < 2; ++n) _Pragma("unroll") for (int k = 0; k < 2; ++k) \
;     acc[ai][bj][m][n] = __builtin_amdgcn_mfma_f32_16x16x32_bf16(Bt[n][k], At[m][k], acc[ai][bj][m][n], 0, 0, 0); __builtin_amdgcn_s_setprio(0); } while (0)
; #define PG8_WAIT_L(n) asm volatile("s_waitcnt lgkmcnt(" #n ")" ::: "memory")
; #define PG8_BAR __builtin_amdgcn_s_barrier()
; #define PG8_SCHED __builtin_amdgcn_sched_barrier(0)
; template <class Epi, bool SPLITA = false>
; __device__ __forceinline__ void gemm_phase(const int tid, LAS unsigned char* lds, const Gemm g, const Order& S, const Epi& E) {
;     ...
;     for (int t = 0; t < nt; t += 2) {
;       const bool last = (t == nt - 2);
;       if constexpr (SPLITA) { if (t == nt1) E.mid(acc, cur, wr, wc, fr, fq); }
;       const char* a1 = PG8_TA(t + 1);
;       const char* a2 = last ? nA : PG8_TA(t + 2); const char* b2 = last ? nB : cB + (size_t)(t + 2) * kstep;
;       const char* a3 = last ? nA + kstep : PG8_TA(t + 3); const char* b3 = b2 + kstep;
;       PG8_LDB(B0, 0, 0); PG8_SCHED; PG8_LDA(At, 0, 0); PG8_STAGE(PG8_SA(1, 1), a1 + hstepA, voffA);
;       PG8_WAIT_L(8); PG8_BAR; PG8_WAIT_L(0); PG8_MMA(0, 0, At, B0); PG8_BAR; PG8_SCHED;
;       PG8_LDB(B1, 0, 1); PG8_STAGE(PG8_SB(0, 0), b2, voffB);
;       PG8_BAR; PG8_WAIT_L(0); PG8_MMA(0, 1, At, B1); PG8_BAR;
;       PG8_LDA(At, 0, 1); PG8_STAGE(PG8_SA(0, 0), a2, voffA);
;       PG8_BAR; PG8_WAIT_L(0); PG8_MMA(1, 0, At, B0); PG8_BAR; PG8_SCHED;
.LBB0_87:
	s_add_u32 s8, s12, s16
	s_addc_u32 s9, s13, s17
	s_add_u32 s20, s8, 0x100
	s_addc_u32 s21, s9, 0
	s_add_u32 s18, s54, s16
	s_addc_u32 s19, s55, s17
	s_add_u32 s8, s8, 0x180
	s_addc_u32 s9, s9, 0
	s_add_i32 s90, 0, 0x10000
	v_add_u32_e32 v146, s90, v188
	ds_read_b128 v[134:137], v146
	ds_read_b128 v[138:141], v146 offset:1024
	ds_read_b128 v[142:145], v146 offset:2048
	ds_read_b128 v[146:149], v146 offset:3072
	s_cmpk_eq_i32 s16, 0x2b00
	s_cselect_b32 s23, s7, s9
	s_cselect_b32 s22, s6, s8
	s_cselect_b32 s19, s11, s19
	s_cselect_b32 s18, s10, s18
	s_cselect_b32 s41, s1, s21
	s_cselect_b32 s40, s0, s20
	v_lshl_add_u64 v[184:185], v[130:131], 0, s[16:17]
	s_add_i32 m0, s30, 0xc000
	ds_read_b128 v[150:153], v189
	ds_read_b128 v[154:157], v189 offset:1024
	ds_read_b128 v[168:171], v189 offset:2048
	ds_read_b128 v[172:175], v189 offset:3072
	ds_read_b128 v[176:179], v189 offset:4096
	ds_read_b128 v[180:183], v189 offset:5120
	ds_read_b128 v[190:193], v189 offset:6144
	ds_read_b128 v[212:215], v189 offset:7168
	global_load_lds_dwordx4 v[184:185], off
	v_lshl_add_u64 v[184:185], v[132:133], 0, s[16:17]
	s_add_i32 m0, s30, 0xe000
	s_nop 0
	global_load_lds_dwordx4 v[184:185], off
	s_waitcnt lgkmcnt(8)
	s_barrier
	s_waitcnt lgkmcnt(0)
	s_setprio 1
	s_waitcnt lgkmcnt(0)
	v_mfma_f32_16x16x32_bf16 v[126:129], v[134:137], v[150:153], v[126:129]
	v_mfma_f32_16x16x32_bf16 v[122:125], v[142:145], v[150:153], v[122:125]
	v_mfma_f32_16x16x32_bf16 v[110:113], v[134:137], v[168:171], v[110:113]
	v_mfma_f32_16x16x32_bf16 v[106:109], v[142:145], v[168:171], v[106:109]
	v_mfma_f32_16x16x32_bf16 v[94:97], v[134:137], v[176:179], v[94:97]
	v_mfma_f32_16x16x32_bf16 v[90:93], v[142:145], v[176:179], v[90:93]
	v_mfma_f32_16x16x32_bf16 v[78:81], v[134:137], v[190:193], v[78:81]
	v_mfma_f32_16x16x32_bf16 v[74:77], v[142:145], v[190:193], v[74:77]
	v_mfma_f32_16x16x32_bf16 v[126:129], v[138:141], v[154:157], v[126:129]
	v_mfma_f32_16x16x32_bf16 v[122:125], v[146:149], v[154:157], v[122:125]
	v_mfma_f32_16x16x32_bf16 v[110:113], v[138:141], v[172:175], v[110:113]
	v_mfma_f32_16x16x32_bf16 v[106:109], v[146:149], v[172:175], v[106:109]
	v_mfma_f32_16x16x32_bf16 v[94:97], v[138:141], v[180:183], v[94:97]
	v_mfma_f32_16x16x32_bf16 v[90:93], v[146:149], v[180:183], v[90:93]
	v_mfma_f32_16x16x32_bf16 v[78:81], v[138:141], v[212:215], v[78:81]
	v_mfma_f32_16x16x32_bf16 v[74:77], v[146:149], v[212:215], v[74:77]
	s_setprio 0
	s_barrier
	s_add_i32 s8, 0, 0x14000
	v_add_u32_e32 v184, s8, v188
	s_add_i32 s9, s90, s3
	ds_read_b128 v[216:219], v184
	ds_read_b128 v[220:223], v184 offset:1024
	ds_read_b128 v[224:227], v184 offset:2048
	ds_read_b128 v[228:231], v184 offset:3072
	v_lshl_add_u64 v[184:185], s[18:19], 0, v[0:1]
	s_mov_b32 m0, s9
	v_lshl_add_u64 v[198:199], s[18:19], 0, v[162:163]
	global_load_lds_dwordx4 v0, s[18:19]
	s_add_i32 m0, s9, 0x2000
	s_nop 0
	global_load_lds_dwordx4 v162, s[18:19]
	s_barrier
	s_waitcnt lgkmcnt(0)
	s_setprio 1
	s_waitcnt lgkmcnt(0)
	v_mfma_f32_16x16x32_bf16 v[118:121], v[216:219], v[150:153], v[118:121]
	v_mfma_f32_16x16x32_bf16 v[114:117], v[224:227], v[150:153], v[114:117]
	v_mfma_f32_16x16x32_bf16 v[102:105], v[216:219], v[168:171], v[102:105]
	v_mfma_f32_16x16x32_bf16 v[98:101], v[224:227], v[168:171], v[98:101]
	v_mfma_f32_16x16x32_bf16 v[86:89], v[216:219], v[176:179], v[86:89]
	v_mfma_f32_16x16x32_bf16 v[82:85], v[224:227], v[176:179], v[82:85]
	v_mfma_f32_16x16x32_bf16 v[70:73], v[216:219], v[190:193], v[70:73]
	v_mfma_f32_16x16x32_bf16 v[66:69], v[224:227], v[190:193], v[66:69]
	v_mfma_f32_16x16x32_bf16 v[118:121], v[220:223], v[154:157], v[118:121]
	v_mfma_f32_16x16x32_bf16 v[114:117], v[228:231], v[154:157], v[114:117]
	v_mfma_f32_16x16x32_bf16 v[102:105], v[220:223], v[172:175], v[102:105]
	v_mfma_f32_16x16x32_bf16 v[98:101], v[228:231], v[172:175], v[98:101]
	v_mfma_f32_16x16x32_bf16 v[86:89], v[220:223], v[180:183], v[86:89]
	v_mfma_f32_16x16x32_bf16 v[82:85], v[228:231], v[180:183], v[82:85]
	v_mfma_f32_16x16x32_bf16 v[70:73], v[220:223], v[212:215], v[70:73]
	v_mfma_f32_16x16x32_bf16 v[66:69], v[228:231], v[212:215], v[66:69]
	s_setprio 0
	s_mov_b32 m0, s30
	s_barrier
	ds_read_b128 v[150:153], v189 offset:16384
	ds_read_b128 v[154:157], v189 offset:17408
	ds_read_b128 v[168:171], v189 offset:18432
	ds_read_b128 v[172:175], v189 offset:19456
	ds_read_b128 v[176:179], v189 offset:20480
	ds_read_b128 v[180:183], v189 offset:21504
	ds_read_b128 v[190:193], v189 offset:22528
	ds_read_b128 v[212:215], v189 offset:23552
	global_load_lds_dwordx4 v158, s[40:41]
	s_mov_b32 m0, s31
	s_nop 0
	global_load_lds_dwordx4 v160, s[40:41]
	s_barrier
	s_waitcnt lgkmcnt(0)
	s_setprio 1
	s_waitcnt lgkmcnt(0)
	v_mfma_f32_16x16x32_bf16 v[62:65], v[134:137], v[150:153], v[62:65]
	v_mfma_f32_16x16x32_bf16 v[58:61], v[142:145], v[150:153], v[58:61]
	v_mfma_f32_16x16x32_bf16 v[46:49], v[134:137], v[168:171], v[46:49]
	v_mfma_f32_16x16x32_bf16 v[42:45], v[142:145], v[168:171], v[42:45]
	v_mfma_f32_16x16x32_bf16 v[30:33], v[134:137], v[176:179], v[30:33]
	v_mfma_f32_16x16x32_bf16 v[26:29], v[142:145], v[176:179], v[26:29]
	v_mfma_f32_16x16x32_bf16 v[14:17], v[134:137], v[190:193], v[14:17]
	v_mfma_f32_16x16x32_bf16 v[10:13], v[142:145], v[190:193], v[10:13]
	v_mfma_f32_16x16x32_bf16 v[62:65], v[138:141], v[154:157], v[62:65]
	v_mfma_f32_16x16x32_bf16 v[58:61], v[146:149], v[154:157], v[58:61]
	v_mfma_f32_16x16x32_bf16 v[46:49], v[138:141], v[172:175], v[46:49]
	v_mfma_f32_16x16x32_bf16 v[42:45], v[146:149], v[172:175], v[42:45]
	v_mfma_f32_16x16x32_bf16 v[30:33], v[138:141], v[180:183], v[30:33]
	v_mfma_f32_16x16x32_bf16 v[26:29], v[146:149], v[180:183], v[26:29]
	v_mfma_f32_16x16x32_bf16 v[14:17], v[138:141], v[212:215], v[14:17]
	v_mfma_f32_16x16x32_bf16 v[10:13], v[146:149], v[212:215], v[10:13]
	s_setprio 0
	s_barrier
; #define PG8_STAGE(bufoff, gbase, voff) do { _Pragma("unroll") for (int _i = 0; _i < 2; ++_i) \
;     __builtin_amdgcn_global_load_lds((const unsigned*)((const char*)(gbase) + (voff)[_i]), (LAS unsigned*)(lds + (bufoff) + ldsw + _i * 8192), 16, 0, 0); } while (0)
; #define PG8_LDA(dst, b, h) do { _Pragma("unroll") for (int m = 0; m < 4; ++m) _Pragma("unroll") for (int k = 0; k < 2; ++k) dst[m][k] = *(const LAS bf16x8*)(lds + PG8_SA(b, h) + aoff + m * 2048 + k * 1024); } while (0)
; #define PG8_LDB(dst, b, h) do { _Pragma("unroll") for (int n = 0; n < 2; ++n) _Pragma("unroll") for (int k = 0; k < 2; ++k) dst[n][k] = *(const LAS bf16x8*)(lds + PG8_SB(b, h) + boff + n * 2048 + k * 1024); } while (0)
; #define PG8_MMA(ai, bj, At, Bt) do { __builtin_amdgcn_s_setprio(1); _Pragma("unroll") for (int m = 0; m < 4; ++m) _Pragma("unroll") for (int n = 0; n < 2; ++n) _Pragma("unroll") for (int k = 0; k < 2; ++k) \
;     acc[ai][bj][m][n] = __builtin_amdgcn_mfma_f32_16x16x32_bf16(Bt[n][k], At[m][k], acc[ai][bj][m][n], 0, 0, 0); __builtin_amdgcn_s_setprio(0); } while (0)
; #define PG8_WAIT_V(n) asm volatile("s_waitcnt vmcnt(" #n ")" ::: "memory")
; #define PG8_WAIT_L(n) asm volatile("s_waitcnt lgkmcnt(" #n ")" ::: "memory")
; #define PG8_BAR __builtin_amdgcn_s_barrier()
; #define PG8_SCHED __builtin_amdgcn_sched_barrier(0)
; template <class Epi, bool SPLITA = false>
; __device__ __forceinline__ void gemm_phase(const int tid, LAS unsigned char* lds, const Gemm g, const Order& S, const Epi& E) {
;     ...
;       PG8_BAR; PG8_WAIT_L(0); PG8_MMA(1, 0, At, B0); PG8_BAR; PG8_SCHED;
;       PG8_STAGE(PG8_SB(0, 1), b2 + hstepB, voffB);
;       PG8_WAIT_V(6); PG8_BAR; PG8_MMA(1, 1, At, B1); PG8_BAR;
;       PG8_LDB(B0, 1, 0); PG8_SCHED; PG8_LDA(At, 1, 0); PG8_STAGE(PG8_SA(0, 1), a2 + hstepA, voffA);
;       PG8_WAIT_L(8); PG8_BAR; PG8_WAIT_L(0); PG8_MMA(0, 0, At, B0); PG8_BAR; PG8_SCHED;
;       PG8_LDB(B1, 1, 1); PG8_STAGE(PG8_SB(1, 0), b3, voffB);
;       PG8_BAR; PG8_WAIT_L(0); PG8_MMA(0, 1, At, B1); PG8_BAR;
;       PG8_LDA(At, 1, 1); PG8_STAGE(PG8_SA(1, 0), a3, voffA);
;       PG8_BAR; PG8_WAIT_L(0); PG8_MMA(1, 0, At, B0); PG8_BAR; PG8_SCHED;
	s_add_u32 s20, s18, 0x160000
	s_addc_u32 s21, s19, 0
	s_add_i32 s8, s8, s3
	s_mov_b32 m0, s8
	s_nop 0
	global_load_lds_dwordx4 v0, s[20:21]
	v_lshl_add_u64 v[134:135], s[20:21], 0, v[162:163]
	s_add_i32 m0, s8, 0x2000
	s_nop 0
	global_load_lds_dwordx4 v162, s[20:21]
	s_waitcnt vmcnt(6)
	s_barrier
	s_setprio 1
	v_mfma_f32_16x16x32_bf16 v[54:57], v[216:219], v[150:153], v[54:57]
	v_mfma_f32_16x16x32_bf16 v[50:53], v[224:227], v[150:153], v[50:53]
	v_mfma_f32_16x16x32_bf16 v[38:41], v[216:219], v[168:171], v[38:41]
	v_mfma_f32_16x16x32_bf16 v[34:37], v[224:227], v[168:171], v[34:37]
	v_mfma_f32_16x16x32_bf16 v[22:25], v[216:219], v[176:179], v[22:25]
	v_mfma_f32_16x16x32_bf16 v[18:21], v[224:227], v[176:179], v[18:21]
	v_mfma_f32_16x16x32_bf16 v[6:9], v[216:219], v[190:193], v[6:9]
	v_mfma_f32_16x16x32_bf16 v[2:5], v[224:227], v[190:193], v[2:5]
	v_mfma_f32_16x16x32_bf16 v[54:57], v[220:223], v[154:157], v[54:57]
	v_mfma_f32_16x16x32_bf16 v[50:53], v[228:231], v[154:157], v[50:53]
	v_mfma_f32_16x16x32_bf16 v[38:41], v[220:223], v[172:175], v[38:41]
	v_mfma_f32_16x16x32_bf16 v[34:37], v[228:231], v[172:175], v[34:37]
	v_mfma_f32_16x16x32_bf16 v[22:25], v[220:223], v[180:183], v[22:25]
	v_mfma_f32_16x16x32_bf16 v[18:21], v[228:231], v[180:183], v[18:21]
	v_mfma_f32_16x16x32_bf16 v[6:9], v[220:223], v[212:215], v[6:9]
	v_mfma_f32_16x16x32_bf16 v[2:5], v[228:231], v[212:215], v[2:5]
	s_setprio 0
	s_add_i32 s8, 0, 0x18000
	v_add_u32_e32 v146, s8, v188
	s_barrier
	ds_read_b128 v[134:137], v146
	ds_read_b128 v[138:141], v146 offset:1024
	ds_read_b128 v[142:145], v146 offset:2048
	ds_read_b128 v[146:149], v146 offset:3072
	s_add_u32 s20, s40, 0x160000
	s_addc_u32 s21, s41, 0
	s_mov_b32 m0, s42
	ds_read_b128 v[150:153], v189 offset:32768
	ds_read_b128 v[154:157], v189 offset:33792
	ds_read_b128 v[168:171], v189 offset:34816
	ds_read_b128 v[172:175], v189 offset:35840
	ds_read_b128 v[176:179], v189 offset:36864
	ds_read_b128 v[180:183], v189 offset:37888
	ds_read_b128 v[190:193], v189 offset:38912
	ds_read_b128 v[212:215], v189 offset:39936
	global_load_lds_dwordx4 v158, s[20:21]
	s_mov_b32 m0, s43
	s_nop 0
	global_load_lds_dwordx4 v160, s[20:21]
	s_waitcnt lgkmcnt(8)
	s_barrier
	s_waitcnt lgkmcnt(0)
	s_setprio 1
	s_waitcnt lgkmcnt(0)
	v_mfma_f32_16x16x32_bf16 v[126:129], v[134:137], v[150:153], v[126:129]
	v_mfma_f32_16x16x32_bf16 v[122:125], v[142:145], v[150:153], v[122:125]
	v_mfma_f32_16x16x32_bf16 v[110:113], v[134:137], v[168:171], v[110:113]
	v_mfma_f32_16x16x32_bf16 v[106:109], v[142:145], v[168:171], v[106:109]
	v_mfma_f32_16x16x32_bf16 v[94:97], v[134:137], v[176:179], v[94:97]
	v_mfma_f32_16x16x32_bf16 v[90:93], v[142:145], v[176:179], v[90:93]
	v_mfma_f32_16x16x32_bf16 v[78:81], v[134:137], v[190:193], v[78:81]
	v_mfma_f32_16x16x32_bf16 v[74:77], v[142:145], v[190:193], v[74:77]
	v_mfma_f32_16x16x32_bf16 v[126:129], v[138:141], v[154:157], v[126:129]
	v_mfma_f32_16x16x32_bf16 v[122:125], v[146:149], v[154:157], v[122:125]
	v_mfma_f32_16x16x32_bf16 v[110:113], v[138:141], v[172:175], v[110:113]
	v_mfma_f32_16x16x32_bf16 v[106:109], v[146:149], v[172:175], v[106:109]
	v_mfma_f32_16x16x32_bf16 v[94:97], v[138:141], v[180:183], v[94:97]
	v_mfma_f32_16x16x32_bf16 v[90:93], v[146:149], v[180:183], v[90:93]
	v_mfma_f32_16x16x32_bf16 v[78:81], v[138:141], v[212:215], v[78:81]
	v_mfma_f32_16x16x32_bf16 v[74:77], v[146:149], v[212:215], v[74:77]
	s_setprio 0
	s_barrier
	s_add_i32 s9, 0, 0x1c000
	s_add_i32 s8, s8, s3
	v_add_u32_e32 v195, s9, v188
	v_lshl_add_u64 v[184:185], v[184:185], 0, s[96:97]
	s_mov_b32 m0, s8
	ds_read_b128 v[216:219], v195
	ds_read_b128 v[220:223], v195 offset:1024
	ds_read_b128 v[224:227], v195 offset:2048
	ds_read_b128 v[228:231], v195 offset:3072
	global_load_lds_dwordx4 v[184:185], off
	v_lshl_add_u64 v[184:185], v[198:199], 0, s[96:97]
	s_add_i32 m0, s8, 0x2000
	s_nop 0
	global_load_lds_dwordx4 v[184:185], off
	s_barrier
	s_waitcnt lgkmcnt(0)
	s_setprio 1
	s_waitcnt lgkmcnt(0)
	v_mfma_f32_16x16x32_bf16 v[118:121], v[216:219], v[150:153], v[118:121]
	v_mfma_f32_16x16x32_bf16 v[114:117], v[224:227], v[150:153], v[114:117]
	v_mfma_f32_16x16x32_bf16 v[102:105], v[216:219], v[168:171], v[102:105]
	v_mfma_f32_16x16x32_bf16 v[98:101], v[224:227], v[168:171], v[98:101]
	v_mfma_f32_16x16x32_bf16 v[86:89], v[216:219], v[176:179], v[86:89]
	v_mfma_f32_16x16x32_bf16 v[82:85], v[224:227], v[176:179], v[82:85]
	v_mfma_f32_16x16x32_bf16 v[70:73], v[216:219], v[190:193], v[70:73]
	v_mfma_f32_16x16x32_bf16 v[66:69], v[224:227], v[190:193], v[66:69]
	v_mfma_f32_16x16x32_bf16 v[118:121], v[220:223], v[154:157], v[118:121]
	v_mfma_f32_16x16x32_bf16 v[114:117], v[228:231], v[154:157], v[114:117]
	v_mfma_f32_16x16x32_bf16 v[102:105], v[220:223], v[172:175], v[102:105]
	v_mfma_f32_16x16x32_bf16 v[98:101], v[228:231], v[172:175], v[98:101]
	v_mfma_f32_16x16x32_bf16 v[86:89], v[220:223], v[180:183], v[86:89]
	v_mfma_f32_16x16x32_bf16 v[82:85], v[228:231], v[180:183], v[82:85]
	v_mfma_f32_16x16x32_bf16 v[70:73], v[220:223], v[212:215], v[70:73]
	v_mfma_f32_16x16x32_bf16 v[66:69], v[228:231], v[212:215], v[66:69]
	s_setprio 0
	s_mov_b32 m0, s47
	s_barrier
	ds_read_b128 v[150:153], v189 offset:49152
	ds_read_b128 v[154:157], v189 offset:50176
	ds_read_b128 v[168:171], v189 offset:51200
	ds_read_b128 v[172:175], v189 offset:52224
	ds_read_b128 v[176:179], v189 offset:53248
	ds_read_b128 v[180:183], v189 offset:54272
	ds_read_b128 v[190:193], v189 offset:55296
	ds_read_b128 v[212:215], v189 offset:56320
	global_load_lds_dwordx4 v158, s[22:23]
	s_mov_b32 m0, s48
	s_nop 0
	global_load_lds_dwordx4 v160, s[22:23]
	s_barrier
; #define PG8_STAGE(bufoff, gbase, voff) do { _Pragma("unroll") for (int _i = 0; _i < 2; ++_i) \
;     __builtin_amdgcn_global_load_lds((const unsigned*)((const char*)(gbase) + (voff)[_i]), (LAS unsigned*)(lds + (bufoff) + ldsw + _i * 8192), 16, 0, 0); } while (0)
; #define PG8_MMA(ai, bj, At, Bt) do { __builtin_amdgcn_s_setprio(1); _Pragma("unroll") for (int m = 0; m < 4; ++m) _Pragma("unroll") for (int n = 0; n < 2; ++n) _Pragma("unroll") for (int k = 0; k < 2; ++k) \
;     acc[ai][bj][m][n] = __builtin_amdgcn_mfma_f32_16x16x32_bf16(Bt[n][k], At[m][k], acc[ai][bj][m][n], 0, 0, 0); __builtin_amdgcn_s_setprio(0); } while (0)
; #define PG8_WAIT_V(n) asm volatile("s_waitcnt vmcnt(" #n ")" ::: "memory")
; #define PG8_WAIT_L(n) asm volatile("s_waitcnt lgkmcnt(" #n ")" ::: "memory")
; #define PG8_BAR __builtin_amdgcn_s_barrier()
; #define PG8_SCHED __builtin_amdgcn_sched_barrier(0)
; template <class Epi, bool SPLITA = false>
; __device__ __forceinline__ void gemm_phase(const int tid, LAS unsigned char* lds, const Gemm g, const Order& S, const Epi& E) {
;     ...
;       PG8_BAR; PG8_WAIT_L(0); PG8_MMA(1, 0, At, B0); PG8_BAR; PG8_SCHED;
;       PG8_STAGE(PG8_SB(1, 1), b3 + hstepB, voffB);
;       PG8_WAIT_V(6); PG8_BAR; PG8_MMA(1, 1, At, B1); PG8_BAR;
	s_waitcnt lgkmcnt(0)
	s_setprio 1
	s_waitcnt lgkmcnt(0)
	v_mfma_f32_16x16x32_bf16 v[62:65], v[134:137], v[150:153], v[62:65]
	v_mfma_f32_16x16x32_bf16 v[58:61], v[142:145], v[150:153], v[58:61]
	v_mfma_f32_16x16x32_bf16 v[46:49], v[134:137], v[168:171], v[46:49]
	v_mfma_f32_16x16x32_bf16 v[42:45], v[142:145], v[168:171], v[42:45]
	v_mfma_f32_16x16x32_bf16 v[30:33], v[134:137], v[176:179], v[30:33]
	v_mfma_f32_16x16x32_bf16 v[26:29], v[142:145], v[176:179], v[26:29]
	v_mfma_f32_16x16x32_bf16 v[14:17], v[134:137], v[190:193], v[14:17]
	v_mfma_f32_16x16x32_bf16 v[10:13], v[142:145], v[190:193], v[10:13]
	v_mfma_f32_16x16x32_bf16 v[62:65], v[138:141], v[154:157], v[62:65]
	v_mfma_f32_16x16x32_bf16 v[58:61], v[146:149], v[154:157], v[58:61]
	v_mfma_f32_16x16x32_bf16 v[46:49], v[138:141], v[172:175], v[46:49]
	v_mfma_f32_16x16x32_bf16 v[42:45], v[146:149], v[172:175], v[42:45]
	v_mfma_f32_16x16x32_bf16 v[30:33], v[138:141], v[180:183], v[30:33]
	v_mfma_f32_16x16x32_bf16 v[26:29], v[146:149], v[180:183], v[26:29]
	v_mfma_f32_16x16x32_bf16 v[14:17], v[138:141], v[212:215], v[14:17]
	v_mfma_f32_16x16x32_bf16 v[10:13], v[146:149], v[212:215], v[10:13]
	s_setprio 0
	s_barrier
	s_add_u32 s18, s18, 0x160080
	s_addc_u32 s19, s19, 0
	s_add_i32 s8, s9, s3
	s_mov_b32 m0, s8
	s_nop 0
	global_load_lds_dwordx4 v0, s[18:19]
	s_add_i32 m0, s8, 0x2000
	s_nop 0
	global_load_lds_dwordx4 v162, s[18:19]
	s_waitcnt vmcnt(6)
	s_barrier
	s_setprio 1
	v_mfma_f32_16x16x32_bf16 v[54:57], v[216:219], v[150:153], v[54:57]
	v_mfma_f32_16x16x32_bf16 v[50:53], v[224:227], v[150:153], v[50:53]
	v_mfma_f32_16x16x32_bf16 v[38:41], v[216:219], v[168:171], v[38:41]
	v_mfma_f32_16x16x32_bf16 v[34:37], v[224:227], v[168:171], v[34:37]
	v_mfma_f32_16x16x32_bf16 v[22:25], v[216:219], v[176:179], v[22:25]
	v_mfma_f32_16x16x32_bf16 v[18:21], v[224:227], v[176:179], v[18:21]
	v_mfma_f32_16x16x32_bf16 v[6:9], v[216:219], v[190:193], v[6:9]
	v_mfma_f32_16x16x32_bf16 v[2:5], v[224:227], v[190:193], v[2:5]
	v_mfma_f32_16x16x32_bf16 v[54:57], v[220:223], v[154:157], v[54:57]
	v_mfma_f32_16x16x32_bf16 v[50:53], v[228:231], v[154:157], v[50:53]
	v_mfma_f32_16x16x32_bf16 v[38:41], v[220:223], v[172:175], v[38:41]
	v_mfma_f32_16x16x32_bf16 v[34:37], v[228:231], v[172:175], v[34:37]
	v_mfma_f32_16x16x32_bf16 v[22:25], v[220:223], v[180:183], v[22:25]
	v_mfma_f32_16x16x32_bf16 v[18:21], v[228:231], v[180:183], v[18:21]
	v_mfma_f32_16x16x32_bf16 v[6:9], v[220:223], v[212:215], v[6:9]
	v_mfma_f32_16x16x32_bf16 v[2:5], v[228:231], v[212:215], v[2:5]
	s_setprio 0
	s_add_i32 s29, s29, 2
	s_add_u32 s16, s16, 0x100
	s_addc_u32 s17, s17, 0
	s_cmpk_gt_u32 s29, 0x55
	s_barrier
	s_cbranch_scc0 .LBB0_87
; __device__ __forceinline__ float bflo(unsigned w) { return __uint_as_float(w << 16); }
; __device__ __forceinline__ float bfhi(unsigned w) { return __uint_as_float(w & 0xffff0000u); }
; __device__ __forceinline__ float lane_read(float v, int src) { return __int_as_float(__builtin_amdgcn_ds_bpermute(src << 2, __float_as_int(v))); }
; __device__ __forceinline__ u32x4 pack8(const f32x4 v0, const f32x4 v1) { u32x4 w; w.x = cvtpk(v0[0], v0[1]); w.y = cvtpk(v0[2], v0[3]); w.z = cvtpk(v1[0], v1[1]); w.w = cvtpk(v1[2], v1[3]); return w; }
;   __device__ __forceinline__ void operator()(const Acc& acc, const Unit& u, int wr, int wc, int fr_, int fq_) const {
;     int fr = fr_, fq = fq_; asm volatile("" : "+v"(fr), "+v"(fq));
;     const int lane = fq * 16 + fr;
;     const int row0 = u.pm * BM + wr * 64 + fr, col0 = u.pn * BM + wc * 32 + 8 * fq;
; #pragma unroll
;     for (int ai = 0; ai < 2; ++ai) {
;       u32x4 hv[4][2];
; #pragma unroll
;       for (int m = 0; m < 4; ++m)
; #pragma unroll
;         for (int bj = 0; bj < 2; ++bj) hv[m][bj] = *(const u32x4*)(rin + (size_t)(row0 + ai * HALF + m * 16) * DM + col0 + bj * HALF);
; #pragma unroll
;       for (int m = 0; m < 4; ++m) { const size_t ro = (size_t)(row0 + ai * HALF + m * 16) * DM + col0; float ss = 0.f;
; #pragma unroll
;         for (int bj = 0; bj < 2; ++bj) { const u32x4 h = hv[m][bj];
;           f32x4 v0 = acc[ai][bj][m][0], v1 = acc[ai][bj][m][1];
;           v0[0] += bflo(h.x); v0[1] += bfhi(h.x); v0[2] += bflo(h.y); v0[3] += bfhi(h.y);
;           v1[0] += bflo(h.z); v1[1] += bfhi(h.z); v1[2] += bflo(h.w); v1[3] += bfhi(h.w);
;           if (FINAL) { *(f32x4*)(outf + ro + bj * HALF) = v0; *(f32x4*)(outf + ro + bj * HALF + 4) = v1; }
;           else { ss += v0[0] * v0[0] + v0[1] * v0[1] + v0[2] * v0[2] + v0[3] * v0[3] + v1[0] * v1[0] + v1[1] * v1[1] + v1[2] * v1[2] + v1[3] * v1[3];
;             *(u32x4*)(outb + ro + bj * HALF) = pack8(v0, v1); } }
;         if (!FINAL) { ss += lane_read(ss, lane ^ 16); ss += lane_read(ss, lane ^ 32);
;           if (fq == 0) rss[(size_t)(row0 + ai * HALF + m * 16) * 32 + u.pn * 4 + wc] = ss; } }
	s_lshl_b32 s6, s53, 8
	v_mov_b32_e32 v130, v187
	v_mov_b32_e32 v131, v186
	s_add_i32 s6, s6, s45
	s_lshl_b32 s12, s4, 2
	v_add_u32_e32 v170, s6, v130
	s_lshl_b32 s6, s4, 8
	s_or_b32 s6, s6, s46
	v_lshl_add_u32 v168, v131, 3, s6
	v_ashrrev_i32_e32 v169, 31, v168
	v_lshlrev_b32_e32 v130, 2, v130
	v_lshlrev_b64 v[192:193], 1, v[168:169]
	v_ashrrev_i32_e32 v171, 31, v170
	v_lshl_add_u32 v130, v131, 6, v130
	v_lshl_add_u64 v[172:173], s[86:87], 0, v[192:193]
	v_lshlrev_b64 v[198:199], 12, v[170:171]
	v_xor_b32_e32 v191, 64, v130
	v_xor_b32_e32 v190, 0x80, v130
	v_cmp_eq_u32_e32 vcc, 0, v131
	v_lshl_add_u64 v[130:131], v[172:173], 0, v[198:199]
	global_load_dwordx4 v[212:215], v[130:131], off
	global_load_dwordx4 v[154:157], v[130:131], off offset:256
	v_add_u32_e32 v182, 16, v170
	v_ashrrev_i32_e32 v183, 31, v182
	v_add_u32_e32 v178, 32, v170
	v_lshlrev_b64 v[184:185], 12, v[182:183]
	v_ashrrev_i32_e32 v179, 31, v178
	v_add_u32_e32 v174, 48, v170
	v_lshl_add_u64 v[130:131], v[172:173], 0, v[184:185]
	v_lshlrev_b64 v[180:181], 12, v[178:179]
	v_ashrrev_i32_e32 v175, 31, v174
	global_load_dwordx4 v[150:153], v[130:131], off
	global_load_dwordx4 v[146:149], v[130:131], off offset:256
	v_lshl_add_u64 v[130:131], v[172:173], 0, v[180:181]
	v_lshlrev_b64 v[176:177], 12, v[174:175]
	global_load_dwordx4 v[142:145], v[130:131], off
	global_load_dwordx4 v[138:141], v[130:131], off offset:256
	v_lshl_add_u64 v[130:131], v[172:173], 0, v[176:177]
	global_load_dwordx4 v[134:137], v[130:131], off
	s_nop 0
	global_load_dwordx4 v[130:133], v[130:131], off offset:256
	s_ashr_i32 s13, s12, 31
	s_waitcnt vmcnt(0)
	v_lshlrev_b32_e32 v200, 16, v212
	v_and_b32_e32 v201, 0xffff0000, v212
	v_pk_add_f32 v[126:127], v[126:127], v[200:201]
	v_lshlrev_b32_e32 v200, 16, v213
	v_and_b32_e32 v201, 0xffff0000, v213
	v_pk_add_f32 v[128:129], v[128:129], v[200:201]
	v_lshlrev_b32_e32 v200, 16, v214
	v_and_b32_e32 v201, 0xffff0000, v214
	v_pk_add_f32 v[200:201], v[122:123], v[200:201]
	v_lshlrev_b32_e32 v122, 16, v215
	v_and_b32_e32 v123, 0xffff0000, v215
	v_pk_add_f32 v[202:203], v[124:125], v[122:123]
	v_pk_mul_f32 v[204:205], v[126:127], v[126:127]
	v_cvt_pk_bf16_f32 v122, v126, v127
	v_lshl_add_u64 v[126:127], s[86:87], 0, v[198:199]
	v_cvt_pk_bf16_f32 v123, v128, v129
	v_cvt_pk_bf16_f32 v124, v200, v201
	v_cvt_pk_bf16_f32 v125, v202, v203
	v_lshl_add_u64 v[126:127], v[126:127], 0, v[192:193]
	global_store_dwordx4 v[126:127], v[122:125], off
	v_pk_mul_f32 v[206:207], v[128:129], v[128:129]
	v_pk_mul_f32 v[212:213], v[200:201], v[200:201]
	v_lshlrev_b32_e32 v122, 16, v154
	v_and_b32_e32 v123, 0xffff0000, v154
	v_pk_add_f32 v[118:119], v[118:119], v[122:123]
	v_lshlrev_b32_e32 v122, 16, v155
	v_and_b32_e32 v123, 0xffff0000, v155
	v_pk_add_f32 v[120:121], v[120:121], v[122:123]
	v_lshlrev_b32_e32 v122, 16, v156
	v_and_b32_e32 v123, 0xffff0000, v156
	v_pk_add_f32 v[122:123], v[114:115], v[122:123]
	v_lshlrev_b32_e32 v114, 16, v157
	v_and_b32_e32 v115, 0xffff0000, v157
	v_pk_add_f32 v[124:125], v[116:117], v[114:115]
	v_pk_mul_f32 v[114:115], v[118:119], v[118:119]
	v_pk_mul_f32 v[116:117], v[120:121], v[120:121]
	v_add_f32_e32 v114, v114, v115
	v_add_f32_e32 v115, v204, v205
	v_add_f32_e32 v114, v116, v114
	v_add_f32_e32 v115, v206, v115
	v_pk_mul_f32 v[128:129], v[122:123], v[122:123]
	v_add_f32_e32 v114, v117, v114
	v_add_f32_e32 v115, v207, v115
	v_add_f32_e32 v114, v128, v114
	v_add_f32_e32 v115, v212, v115
	v_pk_mul_f32 v[214:215], v[202:203], v[202:203]
	v_pk_mul_f32 v[154:155], v[124:125], v[124:125]
	v_add_f32_e32 v114, v129, v114
	v_add_f32_e32 v115, v213, v115
	v_add_f32_e32 v114, v154, v114
	v_add_f32_e32 v115, v214, v115
	v_add_f32_e32 v114, v155, v114
	v_add_f32_e32 v115, v215, v115
	v_add_f32_e32 v128, v115, v114
	v_cvt_pk_bf16_f32 v114, v118, v119
	v_cvt_pk_bf16_f32 v115, v120, v121
	v_cvt_pk_bf16_f32 v116, v122, v123
	v_cvt_pk_bf16_f32 v117, v124, v125
	global_store_dwordx4 v[126:127], v[114:117], off offset:256
	ds_bpermute_b32 v114, v191, v128
	s_waitcnt lgkmcnt(0)
	v_add_f32_e32 v114, v128, v114
	ds_bpermute_b32 v115, v190, v114
	s_and_saveexec_b64 s[6:7], vcc
	s_cbranch_execz .LBB0_90
	v_readlane_b32 s8, v255, 1
	v_lshlrev_b64 v[116:117], 7, v[170:171]
	v_readlane_b32 s9, v255, 2
	s_lshl_b32 s4, s44, 2
	s_waitcnt lgkmcnt(0)
	v_add_f32_e32 v114, v114, v115
	v_lshl_add_u64 v[116:117], s[8:9], 0, v[116:117]
	v_lshl_add_u64 v[116:117], s[12:13], 2, v[116:117]
	v_lshl_add_u64 v[116:117], v[116:117], 0, s[4:5]
	global_store_dword v[116:117], v114, off

; #define PG8_STAGE(bufoff, gbase, voff) do { _Pragma("unroll") for (int _i = 0; _i < 2; ++_i) \
;     __builtin_amdgcn_global_load_lds((const unsigned*)((const char*)(gbase) + (voff)[_i]), (LAS unsigned*)(lds + (bufoff) + ldsw + _i * 8192), 16, 0, 0); } while (0)
; #define PG8_WAIT_V(n) asm volatile("s_waitcnt vmcnt(" #n ")" ::: "memory")
; #define PG8_BAR __builtin_amdgcn_s_barrier()
; template <class Epi, bool SPLITA = false>
; __device__ __forceinline__ void gemm_phase(const int tid, LAS unsigned char* lds, const Gemm g, const Order& S, const Epi& E) {
;     ...
;   PG8_STAGE(PG8_SB(0, 0), cB, voffB); PG8_STAGE(PG8_SA(0, 0), cA, voffA); PG8_STAGE(PG8_SB(0, 1), cB + hstepB, voffB); PG8_STAGE(PG8_SA(0, 1), cA + hstepA, voffA);
;   if (wr == 1) PG8_BAR;
;   PG8_WAIT_V(4); PG8_BAR;
;   PG8_STAGE(PG8_SB(1, 0), cB + kstep, voffB); PG8_STAGE(PG8_SA(1, 0), cA + kstep, voffA); PG8_STAGE(PG8_SB(1, 1), cB + hstepB + kstep, voffB);
;   PG8_WAIT_V(6); PG8_BAR;
.LBB0_139:
	v_bfe_u32 v177, v210, 4, 2
	v_and_b32_e32 v179, 15, v210
	v_lshlrev_b32_e32 v16, 4, v177
	v_lshlrev_b32_e32 v17, 2, v210
	v_lshl_or_b32 v16, v179, 6, v16
	s_lshl_b32 s8, s7, 13
	v_and_b32_e32 v17, 32, v17
	v_bitop3_b32 v18, v16, s8, v17 bitop3:0xde
	s_lshl_b32 s8, s10, 5
	s_and_b32 s54, s8, 0x60
	s_add_i32 m0, s31, 0x18000
	v_lshl_add_u64 v[8:9], v[8:9], 0, s[96:97]
	s_and_b32 s90, 0xffff, s6
	s_and_b32 s6, 0xffff, s4
	s_lshl_b32 s4, s7, 6
	s_lshl_b32 s8, s54, 7
	s_waitcnt vmcnt(4)
	s_barrier
	global_load_lds_dwordx4 v[8:9], off
	v_lshl_add_u64 v[6:7], v[6:7], 0, s[96:97]
	s_add_i32 m0, s31, 0x1a000
	s_add_i32 s55, s31, 0x8000
	s_add_i32 s93, s31, 0xa000
	global_load_lds_dwordx4 v[6:7], off
	v_lshl_add_u64 v[4:5], v[4:5], 0, s[96:97]
	s_mov_b32 m0, s55
	s_add_u32 s10, s42, 0x80080
	global_load_lds_dwordx4 v[4:5], off
	v_lshl_add_u64 v[2:3], v[2:3], 0, s[96:97]
	s_mov_b32 m0, s93
	s_addc_u32 s11, s43, 0
	global_load_lds_dwordx4 v[2:3], off
	s_add_i32 m0, s31, 0x1c000
	s_nop 0
	global_load_lds_dwordx4 v0, s[10:11]
	v_lshl_add_u64 v[2:3], s[10:11], 0, v[162:163]
	s_add_i32 m0, s31, 0x1e000
	v_bitop3_b32 v183, s8, v16, v17 bitop3:0xf6
	global_load_lds_dwordx4 v162, s[10:11]
	s_ashr_i32 s8, s4, 31
	s_lshl_b32 s7, s7, 1
	v_writelane_b32 v255, s8, 33
	s_cmpk_lt_u32 s3, 0x100
	v_lshlrev_b32_e32 v2, 15, v14
	v_writelane_b32 v255, s7, 44
	s_cselect_b64 s[8:9], -1, 0
	v_and_b32_e32 v2, 0xffff0000, v2
	v_writelane_b32 v255, s8, 38
	s_ashr_i32 s3, s92, 31
	v_lshl_add_u32 v2, v13, 12, v2
	v_and_b32_e32 v3, 1, v14
	v_writelane_b32 v255, s9, 39
	s_add_u32 s48, s14, 0x5800
	v_lshl_or_b32 v2, v3, 6, v2
	v_writelane_b32 v255, s3, 35
	s_addc_u32 s49, s15, 0
	v_lshl_add_u32 v168, v15, 1, v2
	v_lshlrev_b32_e32 v2, 15, v10
	s_add_u32 s8, s14, 0xb000
	v_writelane_b32 v255, s14, 40
	v_and_b32_e32 v2, 0xffff0000, v2
	s_waitcnt vmcnt(6)
	s_addc_u32 s9, s15, 0
	v_writelane_b32 v255, s15, 41
	v_lshl_add_u32 v2, v11, 12, v2
	v_and_b32_e32 v3, 1, v10
	v_writelane_b32 v255, s8, 45
	v_lshl_or_b32 v2, v3, 6, v2
	v_mov_b32_e32 v169, v1
	v_writelane_b32 v255, s9, 46
	v_lshl_add_u32 v170, v12, 1, v2
	v_mov_b32_e32 v171, v1
	s_mov_b32 s15, 0
	v_add_u32_e32 v195, 0, v18
	s_barrier
	s_branch .LBB0_141

; #define PG8_STAGE(bufoff, gbase, voff) do { _Pragma("unroll") for (int _i = 0; _i < 2; ++_i) \
;     __builtin_amdgcn_global_load_lds((const unsigned*)((const char*)(gbase) + (voff)[_i]), (LAS unsigned*)(lds + (bufoff) + ldsw + _i * 8192), 16, 0, 0); } while (0)
; #define PG8_LDA(dst, b, h) do { _Pragma("unroll") for (int m = 0; m < 4; ++m) _Pragma("unroll") for (int k = 0; k < 2; ++k) dst[m][k] = *(const LAS bf16x8*)(lds + PG8_SA(b, h) + aoff + m * 2048 + k * 1024); } while (0)
; #define PG8_LDB(dst, b, h) do { _Pragma("unroll") for (int n = 0; n < 2; ++n) _Pragma("unroll") for (int k = 0; k < 2; ++k) dst[n][k] = *(const LAS bf16x8*)(lds + PG8_SB(b, h) + boff + n * 2048 + k * 1024); } while (0)
; #define PG8_MMA(ai, bj, At, Bt) do { __builtin_amdgcn_s_setprio(1); _Pragma("unroll") for (int m = 0; m < 4; ++m) _Pragma("unroll") for (int n = 0; n < 2; ++n) _Pragma("unroll") for (int k = 0; k < 2; ++k) \
;     acc[ai][bj][m][n] = __builtin_amdgcn_mfma_f32_16x16x32_bf16(Bt[n][k], At[m][k], acc[ai][bj][m][n], 0, 0, 0); __builtin_amdgcn_s_setprio(0); } while (0)
; #define PG8_WAIT_L(n) asm volatile("s_waitcnt lgkmcnt(" #n ")" ::: "memory")
; #define PG8_BAR __builtin_amdgcn_s_barrier()
; #define PG8_SCHED __builtin_amdgcn_sched_barrier(0)
; template <class Epi, bool SPLITA = false>
; __device__ __forceinline__ void gemm_phase(const int tid, LAS unsigned char* lds, const Gemm g, const Order& S, const Epi& E) {
;     ...
;     for (int t = 0; t < nt; t += 2) {
;       const bool last = (t == nt - 2);
;       if constexpr (SPLITA) { if (t == nt1) E.mid(acc, cur, wr, wc, fr, fq); }
;       const char* a1 = PG8_TA(t + 1);
;       const char* a2 = last ? nA : PG8_TA(t + 2); const char* b2 = last ? nB : cB + (size_t)(t + 2) * kstep;
;       const char* a3 = last ? nA + kstep : PG8_TA(t + 3); const char* b3 = b2 + kstep;
;       PG8_LDB(B0, 0, 0); PG8_SCHED; PG8_LDA(At, 0, 0); PG8_STAGE(PG8_SA(1, 1), a1 + hstepA, voffA);
;       PG8_WAIT_L(8); PG8_BAR; PG8_WAIT_L(0); PG8_MMA(0, 0, At, B0); PG8_BAR; PG8_SCHED;
;       PG8_LDB(B1, 0, 1); PG8_STAGE(PG8_SB(0, 0), b2, voffB);
;       PG8_BAR; PG8_WAIT_L(0); PG8_MMA(0, 1, At, B1); PG8_BAR;
;       PG8_LDA(At, 0, 1); PG8_STAGE(PG8_SA(0, 0), a2, voffA);
;       PG8_BAR; PG8_WAIT_L(0); PG8_MMA(1, 0, At, B0); PG8_BAR; PG8_SCHED;
.LBB0_144:
	s_add_u32 s8, s40, s42
	s_addc_u32 s9, s41, s43
	s_add_u32 s20, s8, 0x100
	s_addc_u32 s21, s9, 0
	s_add_u32 s44, s30, s42
	s_addc_u32 s45, s14, s43
	s_add_u32 s8, s8, 0x180
	s_addc_u32 s9, s9, 0
	s_add_i32 s94, 0, 0x10000
	v_add_u32_e32 v90, s94, v183
	ds_read_b128 v[78:81], v90
	ds_read_b128 v[82:85], v90 offset:1024
	ds_read_b128 v[86:89], v90 offset:2048
	ds_read_b128 v[90:93], v90 offset:3072
	s_cmpk_eq_i32 s42, 0xf00
	s_cselect_b32 s47, s3, s9
	s_cselect_b32 s46, s91, s8
	s_cselect_b32 s45, s23, s45
	s_cselect_b32 s44, s28, s44
	s_cselect_b32 vcc_hi, s7, s21
	s_cselect_b32 vcc_lo, s19, s20
	v_lshl_add_u64 v[180:181], v[74:75], 0, s[42:43]
	s_add_i32 m0, s31, 0xc000
	ds_read_b128 v[94:97], v195
	ds_read_b128 v[98:101], v195 offset:1024
	ds_read_b128 v[102:105], v195 offset:2048
	ds_read_b128 v[172:175], v195 offset:3072
	ds_read_b128 v[184:187], v195 offset:4096
	ds_read_b128 v[188:191], v195 offset:5120
	ds_read_b128 v[212:215], v195 offset:6144
	ds_read_b128 v[216:219], v195 offset:7168
	global_load_lds_dwordx4 v[180:181], off
	v_lshl_add_u64 v[180:181], v[76:77], 0, s[42:43]
	s_add_i32 m0, s31, 0xe000
	s_nop 0
	global_load_lds_dwordx4 v[180:181], off
	s_waitcnt lgkmcnt(8)
	s_barrier
	s_waitcnt lgkmcnt(0)
	s_setprio 1
	s_waitcnt lgkmcnt(0)
	v_mfma_f32_16x16x32_bf16 v[30:33], v[78:81], v[94:97], v[30:33]
	v_mfma_f32_16x16x32_bf16 v[26:29], v[86:89], v[94:97], v[26:29]
	v_mfma_f32_16x16x32_bf16 v[14:17], v[78:81], v[102:105], v[14:17]
	v_mfma_f32_16x16x32_bf16 v[10:13], v[86:89], v[102:105], v[10:13]
	v_mfma_f32_16x16x32_bf16 v[158:161], v[78:81], v[184:187], v[158:161]
	v_mfma_f32_16x16x32_bf16 v[154:157], v[86:89], v[184:187], v[154:157]
	v_mfma_f32_16x16x32_bf16 v[150:153], v[78:81], v[212:215], v[150:153]
	v_mfma_f32_16x16x32_bf16 v[146:149], v[86:89], v[212:215], v[146:149]
	v_mfma_f32_16x16x32_bf16 v[30:33], v[82:85], v[98:101], v[30:33]
	v_mfma_f32_16x16x32_bf16 v[26:29], v[90:93], v[98:101], v[26:29]
	v_mfma_f32_16x16x32_bf16 v[14:17], v[82:85], v[172:175], v[14:17]
	v_mfma_f32_16x16x32_bf16 v[10:13], v[90:93], v[172:175], v[10:13]
	v_mfma_f32_16x16x32_bf16 v[158:161], v[82:85], v[188:191], v[158:161]
	v_mfma_f32_16x16x32_bf16 v[154:157], v[90:93], v[188:191], v[154:157]
	v_mfma_f32_16x16x32_bf16 v[150:153], v[82:85], v[216:219], v[150:153]
	v_mfma_f32_16x16x32_bf16 v[146:149], v[90:93], v[216:219], v[146:149]
	s_setprio 0
	s_barrier
	s_add_i32 s8, 0, 0x14000
	s_add_i32 s9, s94, s2
	v_add_u32_e32 v176, s8, v183
	v_lshl_add_u64 v[180:181], s[44:45], 0, v[0:1]
	s_mov_b32 m0, s9
	ds_read_b128 v[220:223], v176
	ds_read_b128 v[224:227], v176 offset:1024
	ds_read_b128 v[228:231], v176 offset:2048
	ds_read_b128 v[232:235], v176 offset:3072
	global_load_lds_dwordx4 v0, s[44:45]
	v_lshl_add_u64 v[192:193], s[44:45], 0, v[162:163]
	s_add_i32 m0, s9, 0x2000
	s_nop 0
	global_load_lds_dwordx4 v162, s[44:45]
	s_barrier
	s_waitcnt lgkmcnt(0)
	s_setprio 1
	s_waitcnt lgkmcnt(0)
	v_mfma_f32_16x16x32_bf16 v[22:25], v[220:223], v[94:97], v[22:25]
	v_mfma_f32_16x16x32_bf16 v[18:21], v[228:231], v[94:97], v[18:21]
	v_mfma_f32_16x16x32_bf16 v[6:9], v[220:223], v[102:105], v[6:9]
	v_mfma_f32_16x16x32_bf16 v[2:5], v[228:231], v[102:105], v[2:5]
	v_mfma_f32_16x16x32_bf16 v[130:133], v[228:231], v[212:215], v[130:133]
	v_mfma_f32_16x16x32_bf16 v[22:25], v[224:227], v[98:101], v[22:25]
	v_mfma_f32_16x16x32_bf16 v[18:21], v[232:235], v[98:101], v[18:21]
	v_mfma_f32_16x16x32_bf16 v[6:9], v[224:227], v[172:175], v[6:9]
	v_mfma_f32_16x16x32_bf16 v[2:5], v[232:235], v[172:175], v[2:5]
	v_mfma_f32_16x16x32_bf16 v[94:97], v[220:223], v[184:187], v[142:145]
	v_mfma_f32_16x16x32_bf16 v[98:101], v[228:231], v[184:187], v[138:141]
	v_mfma_f32_16x16x32_bf16 v[102:105], v[220:223], v[212:215], v[134:137]
	v_mfma_f32_16x16x32_bf16 v[130:133], v[232:235], v[216:219], v[130:133]
	v_mfma_f32_16x16x32_bf16 v[94:97], v[224:227], v[188:191], v[94:97]
	v_mfma_f32_16x16x32_bf16 v[98:101], v[232:235], v[188:191], v[98:101]
	v_mfma_f32_16x16x32_bf16 v[102:105], v[224:227], v[216:219], v[102:105]
	s_setprio 0
	s_mov_b32 m0, s31
	v_lshl_add_u64 v[198:199], vcc, 0, v[166:167]
	s_barrier
	ds_read_b128 v[134:137], v195 offset:16384
	ds_read_b128 v[138:141], v195 offset:17408
	ds_read_b128 v[142:145], v195 offset:18432
	ds_read_b128 v[172:175], v195 offset:19456
	ds_read_b128 v[184:187], v195 offset:20480
	ds_read_b128 v[188:191], v195 offset:21504
	ds_read_b128 v[212:215], v195 offset:22528
	ds_read_b128 v[216:219], v195 offset:23552
	global_load_lds_dwordx4 v[198:199], off
	v_lshl_add_u64 v[198:199], vcc, 0, v[164:165]
	s_mov_b32 m0, s51
	s_nop 0
	global_load_lds_dwordx4 v[198:199], off
	s_barrier
	s_waitcnt lgkmcnt(0)
	s_setprio 1
	s_waitcnt lgkmcnt(0)
	v_mfma_f32_16x16x32_bf16 v[126:129], v[78:81], v[134:137], v[126:129]
	v_mfma_f32_16x16x32_bf16 v[122:125], v[86:89], v[134:137], v[122:125]
	v_mfma_f32_16x16x32_bf16 v[118:121], v[78:81], v[142:145], v[118:121]
	v_mfma_f32_16x16x32_bf16 v[114:117], v[86:89], v[142:145], v[114:117]
	v_mfma_f32_16x16x32_bf16 v[70:73], v[78:81], v[184:187], v[70:73]
	v_mfma_f32_16x16x32_bf16 v[66:69], v[86:89], v[184:187], v[66:69]
	v_mfma_f32_16x16x32_bf16 v[54:57], v[78:81], v[212:215], v[54:57]
	v_mfma_f32_16x16x32_bf16 v[50:53], v[86:89], v[212:215], v[50:53]
	v_mfma_f32_16x16x32_bf16 v[126:129], v[82:85], v[138:141], v[126:129]
	v_mfma_f32_16x16x32_bf16 v[122:125], v[90:93], v[138:141], v[122:125]
	v_mfma_f32_16x16x32_bf16 v[118:121], v[82:85], v[172:175], v[118:121]
	v_mfma_f32_16x16x32_bf16 v[114:117], v[90:93], v[172:175], v[114:117]
	v_mfma_f32_16x16x32_bf16 v[70:73], v[82:85], v[188:191], v[70:73]
	v_mfma_f32_16x16x32_bf16 v[66:69], v[90:93], v[188:191], v[66:69]
	v_mfma_f32_16x16x32_bf16 v[54:57], v[82:85], v[216:219], v[54:57]
	v_mfma_f32_16x16x32_bf16 v[50:53], v[90:93], v[216:219], v[50:53]
	s_setprio 0
	s_barrier
; #define PG8_STAGE(bufoff, gbase, voff) do { _Pragma("unroll") for (int _i = 0; _i < 2; ++_i) \
;     __builtin_amdgcn_global_load_lds((const unsigned*)((const char*)(gbase) + (voff)[_i]), (LAS unsigned*)(lds + (bufoff) + ldsw + _i * 8192), 16, 0, 0); } while (0)
; #define PG8_LDA(dst, b, h) do { _Pragma("unroll") for (int m = 0; m < 4; ++m) _Pragma("unroll") for (int k = 0; k < 2; ++k) dst[m][k] = *(const LAS bf16x8*)(lds + PG8_SA(b, h) + aoff + m * 2048 + k * 1024); } while (0)
; #define PG8_LDB(dst, b, h) do { _Pragma("unroll") for (int n = 0; n < 2; ++n) _Pragma("unroll") for (int k = 0; k < 2; ++k) dst[n][k] = *(const LAS bf16x8*)(lds + PG8_SB(b, h) + boff + n * 2048 + k * 1024); } while (0)
; #define PG8_MMA(ai, bj, At, Bt) do { __builtin_amdgcn_s_setprio(1); _Pragma("unroll") for (int m = 0; m < 4; ++m) _Pragma("unroll") for (int n = 0; n < 2; ++n) _Pragma("unroll") for (int k = 0; k < 2; ++k) \
;     acc[ai][bj][m][n] = __builtin_amdgcn_mfma_f32_16x16x32_bf16(Bt[n][k], At[m][k], acc[ai][bj][m][n], 0, 0, 0); __builtin_amdgcn_s_setprio(0); } while (0)
; #define PG8_WAIT_V(n) asm volatile("s_waitcnt vmcnt(" #n ")" ::: "memory")
; #define PG8_WAIT_L(n) asm volatile("s_waitcnt lgkmcnt(" #n ")" ::: "memory")
; #define PG8_BAR __builtin_amdgcn_s_barrier()
; #define PG8_SCHED __builtin_amdgcn_sched_barrier(0)
; template <class Epi, bool SPLITA = false>
; __device__ __forceinline__ void gemm_phase(const int tid, LAS unsigned char* lds, const Gemm g, const Order& S, const Epi& E) {
;     ...
;       PG8_BAR; PG8_WAIT_L(0); PG8_MMA(1, 0, At, B0); PG8_BAR; PG8_SCHED;
;       PG8_STAGE(PG8_SB(0, 1), b2 + hstepB, voffB);
;       PG8_WAIT_V(6); PG8_BAR; PG8_MMA(1, 1, At, B1); PG8_BAR;
;       PG8_LDB(B0, 1, 0); PG8_SCHED; PG8_LDA(At, 1, 0); PG8_STAGE(PG8_SA(0, 1), a2 + hstepA, voffA);
;       PG8_WAIT_L(8); PG8_BAR; PG8_WAIT_L(0); PG8_MMA(0, 0, At, B0); PG8_BAR; PG8_SCHED;
;       PG8_LDB(B1, 1, 1); PG8_STAGE(PG8_SB(1, 0), b3, voffB);
;       PG8_BAR; PG8_WAIT_L(0); PG8_MMA(0, 1, At, B1); PG8_BAR;
;       PG8_LDA(At, 1, 1); PG8_STAGE(PG8_SA(1, 0), a3, voffA);
;       PG8_BAR; PG8_WAIT_L(0); PG8_MMA(1, 0, At, B0); PG8_BAR; PG8_SCHED;
	s_add_u32 s20, s44, 0x80000
	s_addc_u32 s21, s45, 0
	s_add_i32 s8, s8, s2
	s_mov_b32 m0, s8
	s_nop 0
	global_load_lds_dwordx4 v0, s[20:21]
	v_lshl_add_u64 v[78:79], s[20:21], 0, v[162:163]
	s_add_i32 m0, s8, 0x2000
	s_nop 0
	global_load_lds_dwordx4 v162, s[20:21]
	s_waitcnt vmcnt(6)
	s_barrier
	s_setprio 1
	v_mfma_f32_16x16x32_bf16 v[62:65], v[220:223], v[142:145], v[62:65]
	v_mfma_f32_16x16x32_bf16 v[58:61], v[228:231], v[142:145], v[58:61]
	v_mfma_f32_16x16x32_bf16 v[46:49], v[220:223], v[184:187], v[46:49]
	v_mfma_f32_16x16x32_bf16 v[42:45], v[228:231], v[184:187], v[42:45]
	v_mfma_f32_16x16x32_bf16 v[38:41], v[220:223], v[212:215], v[38:41]
	v_mfma_f32_16x16x32_bf16 v[34:37], v[228:231], v[212:215], v[34:37]
	v_mfma_f32_16x16x32_bf16 v[78:81], v[220:223], v[134:137], v[110:113]
	v_mfma_f32_16x16x32_bf16 v[82:85], v[228:231], v[134:137], v[106:109]
	v_mfma_f32_16x16x32_bf16 v[62:65], v[224:227], v[172:175], v[62:65]
	v_mfma_f32_16x16x32_bf16 v[58:61], v[232:235], v[172:175], v[58:61]
	v_mfma_f32_16x16x32_bf16 v[46:49], v[224:227], v[188:191], v[46:49]
	v_mfma_f32_16x16x32_bf16 v[42:45], v[232:235], v[188:191], v[42:45]
	v_mfma_f32_16x16x32_bf16 v[38:41], v[224:227], v[216:219], v[38:41]
	v_mfma_f32_16x16x32_bf16 v[34:37], v[232:235], v[216:219], v[34:37]
	v_mfma_f32_16x16x32_bf16 v[78:81], v[224:227], v[138:141], v[78:81]
	v_mfma_f32_16x16x32_bf16 v[82:85], v[232:235], v[138:141], v[82:85]
	s_setprio 0
	s_add_i32 s8, 0, 0x18000
	v_add_u32_e32 v110, s8, v183
	s_barrier
	ds_read_b128 v[86:89], v110
	ds_read_b128 v[90:93], v110 offset:1024
	ds_read_b128 v[106:109], v110 offset:2048
	ds_read_b128 v[110:113], v110 offset:3072
	s_add_u32 s20, vcc_lo, 0x80000
	s_addc_u32 s21, vcc_hi, 0
	s_mov_b32 m0, s52
	ds_read_b128 v[134:137], v195 offset:32768
	ds_read_b128 v[138:141], v195 offset:33792
	ds_read_b128 v[142:145], v195 offset:34816
	ds_read_b128 v[172:175], v195 offset:35840
	ds_read_b128 v[184:187], v195 offset:36864
	ds_read_b128 v[188:191], v195 offset:37888
	ds_read_b128 v[212:215], v195 offset:38912
	ds_read_b128 v[216:219], v195 offset:39936
	global_load_lds_dwordx4 v166, s[20:21]
	s_mov_b32 m0, s53
	s_nop 0
	global_load_lds_dwordx4 v164, s[20:21]
	s_waitcnt lgkmcnt(8)
	s_barrier
	s_waitcnt lgkmcnt(0)
	s_setprio 1
	s_waitcnt lgkmcnt(0)
	v_mfma_f32_16x16x32_bf16 v[30:33], v[86:89], v[134:137], v[30:33]
	v_mfma_f32_16x16x32_bf16 v[26:29], v[106:109], v[134:137], v[26:29]
	v_mfma_f32_16x16x32_bf16 v[14:17], v[86:89], v[142:145], v[14:17]
	v_mfma_f32_16x16x32_bf16 v[10:13], v[106:109], v[142:145], v[10:13]
	v_mfma_f32_16x16x32_bf16 v[158:161], v[86:89], v[184:187], v[158:161]
	v_mfma_f32_16x16x32_bf16 v[154:157], v[106:109], v[184:187], v[154:157]
	v_mfma_f32_16x16x32_bf16 v[150:153], v[86:89], v[212:215], v[150:153]
	v_mfma_f32_16x16x32_bf16 v[146:149], v[106:109], v[212:215], v[146:149]
	v_mfma_f32_16x16x32_bf16 v[30:33], v[90:93], v[138:141], v[30:33]
	v_mfma_f32_16x16x32_bf16 v[26:29], v[110:113], v[138:141], v[26:29]
	v_mfma_f32_16x16x32_bf16 v[14:17], v[90:93], v[172:175], v[14:17]
	v_mfma_f32_16x16x32_bf16 v[10:13], v[110:113], v[172:175], v[10:13]
	v_mfma_f32_16x16x32_bf16 v[158:161], v[90:93], v[188:191], v[158:161]
	v_mfma_f32_16x16x32_bf16 v[154:157], v[110:113], v[188:191], v[154:157]
	v_mfma_f32_16x16x32_bf16 v[150:153], v[90:93], v[216:219], v[150:153]
	v_mfma_f32_16x16x32_bf16 v[146:149], v[110:113], v[216:219], v[146:149]
	s_setprio 0
	s_barrier
	s_add_i32 s9, 0, 0x1c000
	s_add_i32 s8, s8, s2
	v_add_u32_e32 v176, s9, v183
	v_lshl_add_u64 v[180:181], v[180:181], 0, s[96:97]
	s_mov_b32 m0, s8
	ds_read_b128 v[220:223], v176
	ds_read_b128 v[224:227], v176 offset:1024
	ds_read_b128 v[228:231], v176 offset:2048
	ds_read_b128 v[232:235], v176 offset:3072
	global_load_lds_dwordx4 v[180:181], off
	v_lshl_add_u64 v[180:181], v[192:193], 0, s[96:97]
	s_add_i32 m0, s8, 0x2000
	s_nop 0
	global_load_lds_dwordx4 v[180:181], off
	s_barrier
	s_waitcnt lgkmcnt(0)
	s_setprio 1
	s_waitcnt lgkmcnt(0)
	v_mfma_f32_16x16x32_bf16 v[94:97], v[220:223], v[184:187], v[94:97]
	v_mfma_f32_16x16x32_bf16 v[22:25], v[220:223], v[134:137], v[22:25]
	v_mfma_f32_16x16x32_bf16 v[18:21], v[228:231], v[134:137], v[18:21]
	v_mfma_f32_16x16x32_bf16 v[6:9], v[220:223], v[142:145], v[6:9]
	v_mfma_f32_16x16x32_bf16 v[2:5], v[228:231], v[142:145], v[2:5]
	v_mfma_f32_16x16x32_bf16 v[142:145], v[224:227], v[188:191], v[94:97]
	v_mfma_f32_16x16x32_bf16 v[94:97], v[228:231], v[184:187], v[98:101]
	v_mfma_f32_16x16x32_bf16 v[22:25], v[224:227], v[138:141], v[22:25]
	v_mfma_f32_16x16x32_bf16 v[18:21], v[232:235], v[138:141], v[18:21]
	v_mfma_f32_16x16x32_bf16 v[138:141], v[232:235], v[188:191], v[94:97]
	v_mfma_f32_16x16x32_bf16 v[94:97], v[220:223], v[212:215], v[102:105]
	v_mfma_f32_16x16x32_bf16 v[134:137], v[224:227], v[216:219], v[94:97]
	v_mfma_f32_16x16x32_bf16 v[94:97], v[228:231], v[212:215], v[130:133]
	v_mfma_f32_16x16x32_bf16 v[6:9], v[224:227], v[172:175], v[6:9]
	v_mfma_f32_16x16x32_bf16 v[2:5], v[232:235], v[172:175], v[2:5]
	v_mfma_f32_16x16x32_bf16 v[130:133], v[232:235], v[216:219], v[94:97]
	s_setprio 0
	s_mov_b32 m0, s55
	s_barrier
	s_nop 0
	ds_read_b128 v[94:97], v195 offset:49152
	ds_read_b128 v[98:101], v195 offset:50176
	ds_read_b128 v[102:105], v195 offset:51200
	ds_read_b128 v[172:175], v195 offset:52224
	ds_read_b128 v[184:187], v195 offset:53248
	ds_read_b128 v[188:191], v195 offset:54272
	ds_read_b128 v[212:215], v195 offset:55296
	ds_read_b128 v[216:219], v195 offset:56320
	global_load_lds_dwordx4 v166, s[46:47]
	s_mov_b32 m0, s93
	s_nop 0
	global_load_lds_dwordx4 v164, s[46:47]
	s_barrier
; #define PG8_STAGE(bufoff, gbase, voff) do { _Pragma("unroll") for (int _i = 0; _i < 2; ++_i) \
;     __builtin_amdgcn_global_load_lds((const unsigned*)((const char*)(gbase) + (voff)[_i]), (LAS unsigned*)(lds + (bufoff) + ldsw + _i * 8192), 16, 0, 0); } while (0)
; #define PG8_LDA(dst, b, h) do { _Pragma("unroll") for (int m = 0; m < 4; ++m) _Pragma("unroll") for (int k = 0; k < 2; ++k) dst[m][k] = *(const LAS bf16x8*)(lds + PG8_SA(b, h) + aoff + m * 2048 + k * 1024); } while (0)
; #define PG8_WAIT_V(n) asm volatile("s_waitcnt vmcnt(" #n ")" ::: "memory")
; #define PG8_WAIT_L(n) asm volatile("s_waitcnt lgkmcnt(" #n ")" ::: "memory")
; template <class Epi, bool SPLITA = false>
; __device__ __forceinline__ void gemm_phase(const int tid, LAS unsigned char* lds, const Gemm g, const Order& S, const Epi& E) {
;     ...
;       PG8_LDB(B1, 1, 1); PG8_STAGE(PG8_SB(1, 0), b3, voffB);
;       PG8_BAR; PG8_WAIT_L(0); PG8_MMA(0, 1, At, B1); PG8_BAR;
;       PG8_LDA(At, 1, 1); PG8_STAGE(PG8_SA(1, 0), a3, voffA);
;       PG8_BAR; PG8_WAIT_L(0); PG8_MMA(1, 0, At, B0); PG8_BAR; PG8_SCHED;
;       PG8_STAGE(PG8_SB(1, 1), b3 + hstepB, voffB);
;       PG8_WAIT_V(6); PG8_BAR; PG8_MMA(1, 1, At, B1); PG8_BAR;
;   __device__ __forceinline__ void operator()(Acc& acc, const Unit& u, int wr, int wc, int fr_, int fq_) const {
;     ...
;     const int lane = fq * 16 + fr;
;     const int ch0 = u.pn * 128 + wc * 32 + 8 * fq;
;     f32x4 w0[2], w1[2], w2[2], bb[2];
; #pragma unroll
;     for (int n = 0; n < 2; ++n) { w0[n] = *(const f32x4*)(wconv + ch0 + 4 * n); w1[n] = *(const f32x4*)(wconv + DFF + ch0 + 4 * n);
;       w2[n] = *(const f32x4*)(wconv + 2 * DFF + ch0 + 4 * n); bb[n] = *(const f32x4*)(bconv + ch0 + 4 * n); }
;     if (u.pm == 128) {
;       if (wr == 0) {
; #pragma unroll
;         for (int m = 0; m < 2; ++m) { const int rec = 1024 + m * 16 + fr; bf16_t* rp = EDGE + (size_t)rec * 3 * DFF + ch0;
;           f32x4 p0 = w1[0] * acc[0][0][m][0] + bb[0], p1 = w1[1] * acc[0][0][m][1] + bb[1];
;           *(u32x4*)(rp) = pack8(p0, p1); *(u32x4*)(rp + DFF) = pack8(acc[0][0][m][0], acc[0][0][m][1]); *(u32x4*)(rp + 2 * DFF) = pack8(acc[0][1][m][0], acc[0][1][m][1]); }
;       }
;       return;
;     }
; #pragma unroll
;     for (int ai = 0; ai < 2; ++ai)
; #pragma unroll
;       for (int m = 0; m < 4; ++m) { const float rstd = rss[u.pm * BM + ai * HALF + wr * 64 + m * 16 + fr];
	s_waitcnt lgkmcnt(0)
	s_setprio 1
	s_waitcnt lgkmcnt(0)
	v_mfma_f32_16x16x32_bf16 v[126:129], v[86:89], v[94:97], v[126:129]
	v_mfma_f32_16x16x32_bf16 v[122:125], v[106:109], v[94:97], v[122:125]
	v_mfma_f32_16x16x32_bf16 v[118:121], v[86:89], v[102:105], v[118:121]
	v_mfma_f32_16x16x32_bf16 v[114:117], v[106:109], v[102:105], v[114:117]
	v_mfma_f32_16x16x32_bf16 v[70:73], v[86:89], v[184:187], v[70:73]
	v_mfma_f32_16x16x32_bf16 v[66:69], v[106:109], v[184:187], v[66:69]
	v_mfma_f32_16x16x32_bf16 v[54:57], v[86:89], v[212:215], v[54:57]
	v_mfma_f32_16x16x32_bf16 v[50:53], v[106:109], v[212:215], v[50:53]
	v_mfma_f32_16x16x32_bf16 v[126:129], v[90:93], v[98:101], v[126:129]
	v_mfma_f32_16x16x32_bf16 v[122:125], v[110:113], v[98:101], v[122:125]
	v_mfma_f32_16x16x32_bf16 v[118:121], v[90:93], v[172:175], v[118:121]
	v_mfma_f32_16x16x32_bf16 v[114:117], v[110:113], v[172:175], v[114:117]
	v_mfma_f32_16x16x32_bf16 v[70:73], v[90:93], v[188:191], v[70:73]
	v_mfma_f32_16x16x32_bf16 v[66:69], v[110:113], v[188:191], v[66:69]
	v_mfma_f32_16x16x32_bf16 v[54:57], v[90:93], v[216:219], v[54:57]
	v_mfma_f32_16x16x32_bf16 v[50:53], v[110:113], v[216:219], v[50:53]
	s_setprio 0
	s_barrier
	s_add_u32 s20, s44, 0x80080
	s_addc_u32 s21, s45, 0
	s_add_i32 s8, s9, s2
	s_mov_b32 m0, s8
	s_nop 0
	global_load_lds_dwordx4 v0, s[20:21]
	s_add_i32 m0, s8, 0x2000
	s_nop 0
	global_load_lds_dwordx4 v162, s[20:21]
	s_waitcnt vmcnt(6)
	s_barrier
	s_setprio 1
	v_mfma_f32_16x16x32_bf16 v[78:81], v[220:223], v[94:97], v[78:81]
	v_mfma_f32_16x16x32_bf16 v[110:113], v[224:227], v[98:101], v[78:81]
	v_mfma_f32_16x16x32_bf16 v[78:81], v[228:231], v[94:97], v[82:85]
	v_mfma_f32_16x16x32_bf16 v[62:65], v[220:223], v[102:105], v[62:65]
	v_mfma_f32_16x16x32_bf16 v[58:61], v[228:231], v[102:105], v[58:61]
	v_mfma_f32_16x16x32_bf16 v[46:49], v[220:223], v[184:187], v[46:49]
	v_mfma_f32_16x16x32_bf16 v[42:45], v[228:231], v[184:187], v[42:45]
	v_mfma_f32_16x16x32_bf16 v[38:41], v[220:223], v[212:215], v[38:41]
	v_mfma_f32_16x16x32_bf16 v[34:37], v[228:231], v[212:215], v[34:37]
	v_mfma_f32_16x16x32_bf16 v[106:109], v[232:235], v[98:101], v[78:81]
	v_mfma_f32_16x16x32_bf16 v[62:65], v[224:227], v[172:175], v[62:65]
	v_mfma_f32_16x16x32_bf16 v[58:61], v[232:235], v[172:175], v[58:61]
	v_mfma_f32_16x16x32_bf16 v[46:49], v[224:227], v[188:191], v[46:49]
	v_mfma_f32_16x16x32_bf16 v[42:45], v[232:235], v[188:191], v[42:45]
	v_mfma_f32_16x16x32_bf16 v[38:41], v[224:227], v[216:219], v[38:41]
	v_mfma_f32_16x16x32_bf16 v[34:37], v[232:235], v[216:219], v[34:37]
	s_setprio 0
	s_add_i32 s29, s29, 2
	s_add_u32 s42, s42, 0x100
	s_addc_u32 s43, s43, 0
	s_cmp_gt_u32 s29, 29
	s_barrier
	s_cbranch_scc0 .LBB0_144
	s_lshl_b32 s3, s6, 7
	v_mov_b32_e32 v172, v179
	v_mov_b32_e32 v74, v177
	s_or_b32 s3, s3, s54
	s_cmpk_eq_i32 s90, 0x80
	v_lshl_add_u32 v174, v74, 3, s3
	v_ashrrev_i32_e32 v175, 31, v174
	v_lshlrev_b64 v[90:91], 2, v[174:175]
	v_lshl_add_u64 v[78:79], s[48:49], 0, v[90:91]
	v_lshl_add_u64 v[86:87], s[16:17], 0, v[90:91]
	global_load_dwordx4 v[74:77], v[78:79], off offset:16
	s_nop 0
	global_load_dwordx4 v[78:81], v[78:79], off
	s_nop 0
	global_load_dwordx4 v[82:85], v[86:87], off offset:16
	s_nop 0
	global_load_dwordx4 v[86:89], v[86:87], off
	s_mov_b64 s[6:7], -1
	s_movk_i32 s94, 0x1000
	v_mov_b32_e32 v219, v178
	s_cbranch_scc1 .LBB0_163
	v_readlane_b32 s6, v255, 40
	v_readlane_b32 s7, v255, 41
	s_lshl_b32 s3, s90, 8
	s_add_i32 s3, s3, s4
	v_lshl_add_u64 v[92:93], s[6:7], 0, v[90:91]
	v_readlane_b32 s6, v255, 45
	v_readlane_b32 s7, v255, 46
	v_add_u32_e32 v180, s3, v172
	v_ashrrev_i32_e32 v181, 31, v180
	v_lshl_add_u64 v[98:99], s[6:7], 0, v[90:91]
	v_readlane_b32 s6, v255, 36
	v_readlane_b32 s7, v255, 37
	global_load_dwordx4 v[94:97], v[92:93], off offset:16
	global_load_dwordx4 v[102:105], v[92:93], off
	s_nop 0
	global_load_dwordx4 v[90:93], v[98:99], off offset:16
	s_nop 0
	global_load_dwordx4 v[98:101], v[98:99], off
	v_lshl_add_u64 v[198:199], v[180:181], 2, s[6:7]
	global_load_dword v176, v[198:199], off
	global_load_dword v220, v[198:199], off offset:64
	s_ashr_i32 s91, s90, 31
	s_lshl_b64 s[6:7], s[90:91], 8
	s_add_u32 s6, s6, s4
	v_readlane_b32 s3, v255, 33
	s_addc_u32 s7, s7, s3
	v_ashrrev_i32_e32 v173, 31, v172
	v_lshl_add_u64 v[228:229], s[6:7], 0, v[172:173]
	v_mov_b32_e32 v173, v1
	v_cmp_eq_u32_e64 s[42:43], 0, v172
	v_mov_b32_e32 v181, v1
	v_cmp_eq_u32_e64 s[44:45], 15, v172
	v_cmp_ne_u32_e64 s[46:47], 0, v172
	v_cmp_ne_u32_e64 s[40:41], 15, v172
	s_waitcnt vmcnt(0)
; __device__ __forceinline__ float sigmoidf_(float v) { return __builtin_amdgcn_rcpf(1.f + __builtin_amdgcn_exp2f(v * -1.4426950408889634f)); }
; __device__ __forceinline__ float dpp_ror1(float v) { return __int_as_float(__builtin_amdgcn_update_dpp(0, __float_as_int(v), 0x121, 0xf, 0xf, false)); }
; __device__ __forceinline__ float dpp_ror15(float v) { return __int_as_float(__builtin_amdgcn_update_dpp(0, __float_as_int(v), 0x12F, 0xf, 0xf, false)); }
; __device__ __forceinline__ u32x4 pack8(const f32x4 v0, const f32x4 v1) { u32x4 w; w.x = cvtpk(v0[0], v0[1]); w.y = cvtpk(v0[2], v0[3]); w.z = cvtpk(v1[0], v1[1]); w.w = cvtpk(v1[2], v1[3]); return w; }
;   __device__ __forceinline__ void operator()(Acc& acc, const Unit& u, int wr, int wc, int fr_, int fq_) const {
;     ...
;     for (int ai = 0; ai < 2; ++ai) {
;       const int strip = u.pm * 4 + ai * 2 + wr;
; #pragma unroll
;       for (int m = 0; m < 4; ++m) {
;         f32x4 uv[2];
; #pragma unroll
;         for (int n = 0; n < 2; ++n) {
;           const f32x4 cur = acc[ai][0][m][n]; f32x4 prev, next;
; #pragma unroll
;           for (int e = 0; e < 4; ++e) {
;             const float x = dpp_ror1(cur[e]), y = m > 0 ? dpp_ror1(acc[ai][0][m > 0 ? m - 1 : 0][n][e]) : 0.f;
;             prev[e] = fr == 0 ? y : x;
;             const float x2 = dpp_ror15(cur[e]), y2 = m < 3 ? dpp_ror15(acc[ai][0][m < 3 ? m + 1 : 3][n][e]) : 0.f;
;             next[e] = fr == 15 ? y2 : x2;
;           }
;           uv[n] = w0[n] * prev + w1[n] * cur + w2[n] * next + bb[n];
;         }
;         const bool first = (m == 0 && fr == 0), lastr = (m == 3 && fr == 15);
;         if (first || lastr) {
;           const int rec = strip * 2 + (lastr ? 1 : 0); bf16_t* rp = EDGE + (size_t)rec * 3 * DFF + ch0;
;           *(u32x4*)(rp) = pack8(uv[0], uv[1]); *(u32x4*)(rp + DFF) = pack8(acc[ai][0][m][0], acc[ai][0][m][1]); *(u32x4*)(rp + 2 * DFF) = pack8(acc[ai][1][m][0], acc[ai][1][m][1]);
;         } else {
;           f32x4 o0, o1;
; #pragma unroll
;           for (int e = 0; e < 4; ++e) { o0[e] = uv[0][e] * sigmoidf_(uv[0][e]) * acc[ai][1][m][0][e]; o1[e] = uv[1][e] * sigmoidf_(uv[1][e]) * acc[ai][1][m][1][e]; }
;           const size_t row = (size_t)u.pm * BM + ai * HALF + wr * 64 + m * 16 + fr;
;           *(u32x4*)(ACT + row * DFF + ch0) = pack8(o0, o1);
	v_pk_mul_f32 v[192:193], v[32:33], v[176:177] op_sel_hi:[1,0]
	v_pk_mul_f32 v[212:213], v[30:31], v[176:177] op_sel_hi:[1,0]
	v_pk_mul_f32 v[184:185], v[28:29], v[176:177] op_sel_hi:[1,0]
	v_pk_mul_f32 v[186:187], v[26:27], v[176:177] op_sel_hi:[1,0]
	v_pk_mul_f32 v[224:225], v[24:25], v[176:177] op_sel_hi:[1,0]
	v_pk_mul_f32 v[230:231], v[22:23], v[176:177] op_sel_hi:[1,0]
	v_pk_mul_f32 v[222:223], v[20:21], v[176:177] op_sel_hi:[1,0]
	v_pk_mul_f32 v[226:227], v[18:19], v[176:177] op_sel_hi:[1,0]
	global_load_dword v218, v[198:199], off offset:128
	global_load_dword v196, v[198:199], off offset:192
	global_load_dword v182, v[198:199], off offset:512
	global_load_dword v180, v[198:199], off offset:576
	global_load_dword v178, v[198:199], off offset:640
	global_load_dword v176, v[198:199], off offset:704
	v_mov_b32_dpp v173, v212 row_ror:1 row_mask:0xf bank_mask:0xf
	v_pk_mul_f32 v[216:217], v[14:15], v[220:221] op_sel_hi:[1,0]
	v_cndmask_b32_e64 v198, v173, 0, s[42:43]
	v_mov_b32_e32 v173, v1
	v_mov_b32_dpp v181, v216 row_ror:15 row_mask:0xf bank_mask:0xf
	v_pk_mul_f32 v[214:215], v[16:17], v[220:221] op_sel_hi:[1,0]
	v_mov_b32_dpp v173, v212 row_ror:15 row_mask:0xf bank_mask:0xf
	v_cndmask_b32_e64 v200, v173, v181, s[44:45]
	v_mov_b32_e32 v173, v1
	v_mov_b32_e32 v181, v1
	v_pk_mul_f32 v[190:191], v[10:11], v[220:221] op_sel_hi:[1,0]
	v_mov_b32_dpp v173, v213 row_ror:1 row_mask:0xf bank_mask:0xf
	v_cndmask_b32_e64 v199, v173, 0, s[42:43]
	v_mov_b32_e32 v173, v1
	v_mov_b32_dpp v181, v217 row_ror:15 row_mask:0xf bank_mask:0xf
	v_pk_mul_f32 v[198:199], v[102:103], v[198:199]
	v_mov_b32_dpp v173, v213 row_ror:15 row_mask:0xf bank_mask:0xf
	v_cndmask_b32_e64 v201, v173, v181, s[44:45]
	v_mov_b32_e32 v173, v1
	v_mov_b32_e32 v181, v1
	v_pk_fma_f32 v[198:199], v[78:79], v[212:213], v[198:199]
	v_mov_b32_dpp v173, v192 row_ror:1 row_mask:0xf bank_mask:0xf
	v_cndmask_b32_e64 v202, v173, 0, s[42:43]
	v_mov_b32_e32 v173, v1
	v_mov_b32_dpp v181, v214 row_ror:15 row_mask:0xf bank_mask:0xf
	v_pk_fma_f32 v[198:199], v[98:99], v[200:201], v[198:199]
	v_mov_b32_dpp v173, v192 row_ror:15 row_mask:0xf bank_mask:0xf
	v_cndmask_b32_e64 v204, v173, v181, s[44:45]
	v_mov_b32_e32 v173, v1
	v_mov_b32_e32 v181, v1
	v_pk_mul_f32 v[188:189], v[12:13], v[220:221] op_sel_hi:[1,0]
	v_mov_b32_dpp v173, v193 row_ror:1 row_mask:0xf bank_mask:0xf
	v_cndmask_b32_e64 v203, v173, 0, s[42:43]
	v_mov_b32_e32 v173, v1
	v_mov_b32_dpp v181, v215 row_ror:15 row_mask:0xf bank_mask:0xf
	v_pk_mul_f32 v[202:203], v[104:105], v[202:203]
	v_mov_b32_dpp v173, v193 row_ror:15 row_mask:0xf bank_mask:0xf
	v_cndmask_b32_e64 v205, v173, v181, s[44:45]
	v_mov_b32_e32 v173, v1
	v_mov_b32_e32 v181, v1
	v_pk_fma_f32 v[202:203], v[80:81], v[192:193], v[202:203]
	v_mov_b32_dpp v173, v186 row_ror:1 row_mask:0xf bank_mask:0xf
	v_cndmask_b32_e64 v236, v173, 0, s[42:43]
	v_mov_b32_e32 v173, v1
	v_mov_b32_dpp v181, v190 row_ror:15 row_mask:0xf bank_mask:0xf
	v_pk_add_f32 v[234:235], v[86:87], v[198:199]
	v_mov_b32_dpp v173, v186 row_ror:15 row_mask:0xf bank_mask:0xf
	v_cndmask_b32_e64 v238, v173, v181, s[44:45]
	v_mov_b32_e32 v173, v1
	v_mov_b32_e32 v181, v1
	v_pk_fma_f32 v[200:201], v[100:101], v[204:205], v[202:203]
	v_mov_b32_dpp v173, v187 row_ror:1 row_mask:0xf bank_mask:0xf
	v_cndmask_b32_e64 v237, v173, 0, s[42:43]
	v_mov_b32_e32 v173, v1
	v_mov_b32_dpp v181, v191 row_ror:15 row_mask:0xf bank_mask:0xf
	v_pk_add_f32 v[232:233], v[88:89], v[200:201]
	v_mov_b32_dpp v173, v187 row_ror:15 row_mask:0xf bank_mask:0xf
	v_cndmask_b32_e64 v239, v173, v181, s[44:45]
	v_mov_b32_e32 v173, v1
	v_mov_b32_e32 v181, v1
	v_pk_mul_f32 v[202:203], v[94:95], v[236:237]
	v_mov_b32_dpp v173, v184 row_ror:1 row_mask:0xf bank_mask:0xf
	v_cndmask_b32_e64 v198, v173, 0, s[42:43]
	v_mov_b32_e32 v173, v1
	v_mov_b32_dpp v181, v188 row_ror:15 row_mask:0xf bank_mask:0xf
	v_pk_fma_f32 v[202:203], v[74:75], v[186:187], v[202:203]
	v_mov_b32_dpp v173, v184 row_ror:15 row_mask:0xf bank_mask:0xf
	v_cndmask_b32_e64 v200, v173, v181, s[44:45]
	v_mov_b32_e32 v173, v1
	v_mov_b32_e32 v181, v1
	v_pk_fma_f32 v[202:203], v[90:91], v[238:239], v[202:203]
	v_mov_b32_dpp v173, v185 row_ror:1 row_mask:0xf bank_mask:0xf
	v_cndmask_b32_e64 v199, v173, 0, s[42:43]
	v_mov_b32_e32 v173, v1
	v_mov_b32_dpp v181, v189 row_ror:15 row_mask:0xf bank_mask:0xf
	v_pk_mul_f32 v[198:199], v[96:97], v[198:199]
	v_mov_b32_dpp v173, v185 row_ror:15 row_mask:0xf bank_mask:0xf
	v_cndmask_b32_e64 v201, v173, v181, s[44:45]
	v_pk_fma_f32 v[198:199], v[76:77], v[184:185], v[198:199]
	v_pk_add_f32 v[240:241], v[82:83], v[202:203]
	v_pk_fma_f32 v[198:199], v[92:93], v[200:201], v[198:199]
	s_nop 0
	v_pk_add_f32 v[238:239], v[84:85], v[198:199]
	s_and_saveexec_b64 s[6:7], s[46:47]
	s_xor_b64 vcc, exec, s[6:7]
	s_cbranch_execz .LBB0_148
	v_mul_f32_e32 v173, 0xbfb8aa3b, v234
	v_exp_f32_e32 v173, v173
	v_mad_u64_u32 v[236:237], s[6:7], v228, s24, 0
	v_mad_i32_i24 v237, v229, s24, v237
	v_add_f32_e32 v173, 1.0, v173
	v_rcp_f32_e32 v198, v173
	v_mul_f32_e32 v173, 0xbfb8aa3b, v240
	v_exp_f32_e32 v173, v173
	s_nop 0
	v_add_f32_e32 v173, 1.0, v173
	v_rcp_f32_e32 v200, v173
	v_mul_f32_e32 v173, 0xbfb8aa3b, v235
	v_exp_f32_e32 v173, v173
	s_nop 0
	v_add_f32_e32 v173, 1.0, v173
	v_rcp_f32_e32 v199, v173
	v_mul_f32_e32 v173, 0xbfb8aa3b, v241
	v_exp_f32_e32 v173, v173
	v_pk_mul_f32 v[198:199], v[234:235], v[198:199]
	s_nop 0
	v_pk_mul_f32 v[198:199], v[230:231], v[198:199]
	v_add_f32_e32 v173, 1.0, v173
	v_rcp_f32_e32 v201, v173
	v_mul_f32_e32 v173, 0xbfb8aa3b, v232
	v_exp_f32_e32 v173, v173
	v_pk_mul_f32 v[200:201], v[240:241], v[200:201]
	s_nop 0
	v_pk_mul_f32 v[200:201], v[226:227], v[200:201]
	v_add_f32_e32 v173, 1.0, v173
	v_rcp_f32_e32 v202, v173
	v_mul_f32_e32 v173, 0xbfb8aa3b, v238
	v_exp_f32_e32 v173, v173
	s_nop 0
	v_add_f32_e32 v173, 1.0, v173
	v_rcp_f32_e32 v204, v173
	v_mul_f32_e32 v173, 0xbfb8aa3b, v233
	v_exp_f32_e32 v173, v173
	s_nop 0
	v_add_f32_e32 v173, 1.0, v173
	v_rcp_f32_e32 v203, v173
	v_mul_f32_e32 v173, 0xbfb8aa3b, v239
	v_exp_f32_e32 v173, v173
	v_pk_mul_f32 v[202:203], v[232:233], v[202:203]
	s_nop 0
	v_pk_mul_f32 v[202:203], v[224:225], v[202:203]
	v_add_f32_e32 v173, 1.0, v173
	v_rcp_f32_e32 v205, v173
	v_cvt_pk_bf16_f32 v224, v200, v201
	v_pk_mul_f32 v[204:205], v[238:239], v[204:205]
	s_nop 0
	v_pk_mul_f32 v[204:205], v[222:223], v[204:205]
	v_cvt_pk_bf16_f32 v222, v198, v199
	v_mov_b64_e32 v[198:199], s[34:35]
	v_mad_u64_u32 v[198:199], s[6:7], v228, s24, v[198:199]
	v_mad_i32_i24 v199, v229, s24, v199
	v_cvt_pk_bf16_f32 v223, v202, v203
	v_cvt_pk_bf16_f32 v225, v204, v205
	v_lshl_add_u64 v[198:199], v[174:175], 1, v[198:199]
	global_store_dwordx4 v[198:199], v[222:225], off

; #define PG8_STAGE(bufoff, gbase, voff) do { _Pragma("unroll") for (int _i = 0; _i < 2; ++_i) \
;     __builtin_amdgcn_global_load_lds((const unsigned*)((const char*)(gbase) + (voff)[_i]), (LAS unsigned*)(lds + (bufoff) + ldsw + _i * 8192), 16, 0, 0); } while (0)
; #define PG8_WAIT_V(n) asm volatile("s_waitcnt vmcnt(" #n ")" ::: "memory")
; #define PG8_BAR __builtin_amdgcn_s_barrier()
; template <class Epi, bool SPLITA = false>
; __device__ __forceinline__ void gemm_phase(const int tid, LAS unsigned char* lds, const Gemm g, const Order& S, const Epi& E) {
;     ...
;   PG8_STAGE(PG8_SB(0, 0), cB, voffB); PG8_STAGE(PG8_SA(0, 0), cA, voffA); PG8_STAGE(PG8_SB(0, 1), cB + hstepB, voffB); PG8_STAGE(PG8_SA(0, 1), cA + hstepA, voffA);
;   if (wr == 1) PG8_BAR;
;   PG8_WAIT_V(4); PG8_BAR;
;   PG8_STAGE(PG8_SB(1, 0), cB + kstep, voffB); PG8_STAGE(PG8_SA(1, 0), cA + kstep, voffA); PG8_STAGE(PG8_SB(1, 1), cB + hstepB + kstep, voffB);
;   PG8_WAIT_V(6); PG8_BAR;
.LBB0_183:
	v_bfe_u32 v186, v210, 4, 2
	v_lshl_add_u64 v[8:9], s[42:43], 0, v[0:1]
	v_mov_b32_e32 v163, v1
	v_and_b32_e32 v187, 15, v210
	v_lshlrev_b32_e32 v16, 4, v186
	v_lshlrev_b32_e32 v17, 2, v210
	v_lshl_add_u64 v[10:11], s[42:43], 0, v[162:163]
	v_mov_b32_e32 v159, v1
	s_and_b32 s54, s2, 3
	v_lshl_or_b32 v16, v187, 6, v16
	s_lshl_b32 s2, s4, 13
	v_and_b32_e32 v17, 32, v17
	s_add_i32 m0, s23, 0x18000
	v_lshl_add_u64 v[8:9], v[8:9], 0, s[96:97]
	v_lshl_add_u64 v[12:13], s[40:41], 0, v[158:159]
	v_mov_b32_e32 v161, v1
	s_lshl_b32 s55, s4, 6
	v_bitop3_b32 v18, v16, s2, v17 bitop3:0xde
	s_lshl_b32 s90, s54, 5
	s_lshl_b32 s2, s54, 12
	s_waitcnt vmcnt(4)
	s_barrier
	global_load_lds_dwordx4 v[8:9], off
	v_lshl_add_u64 v[8:9], v[10:11], 0, s[96:97]
	s_add_i32 m0, s23, 0x1a000
	s_add_i32 s91, s23, 0x8000
	s_add_i32 s93, s23, 0xa000
	v_lshl_add_u64 v[14:15], s[40:41], 0, v[160:161]
	global_load_lds_dwordx4 v[8:9], off
	v_lshl_add_u64 v[8:9], v[12:13], 0, s[96:97]
	s_mov_b32 m0, s91
	s_add_u32 s6, s42, 0x80080
	global_load_lds_dwordx4 v[8:9], off
	v_lshl_add_u64 v[8:9], v[14:15], 0, s[96:97]
	s_mov_b32 m0, s93
	s_addc_u32 s7, s43, 0
	global_load_lds_dwordx4 v[8:9], off
	s_add_i32 m0, s23, 0x1c000
	s_nop 0
	global_load_lds_dwordx4 v0, s[6:7]
	v_lshl_add_u64 v[8:9], s[6:7], 0, v[162:163]
	s_add_i32 m0, s23, 0x1e000
	v_bitop3_b32 v188, v16, s2, v17 bitop3:0xde
	global_load_lds_dwordx4 v162, s[6:7]
	v_lshlrev_b32_e32 v8, 15, v2
	v_and_b32_e32 v8, 0xffff0000, v8
	v_lshl_add_u32 v3, v3, 12, v8
	v_and_b32_e32 v2, 1, v2
	v_lshl_or_b32 v2, v2, 6, v3
	v_lshl_add_u32 v164, v4, 1, v2
	v_lshlrev_b32_e32 v2, 15, v5
	v_and_b32_e32 v2, 0xffff0000, v2
	s_waitcnt vmcnt(6)
	v_lshl_add_u32 v2, v6, 12, v2
	v_and_b32_e32 v3, 1, v5
	v_lshl_or_b32 v2, v3, 6, v2
	s_ashr_i32 s2, s92, 31
	v_mov_b32_e32 v165, v1
	v_lshl_add_u32 v166, v7, 1, v2
	v_mov_b32_e32 v167, v1
	s_mov_b32 s28, 0
	v_add_u32_e32 v189, 0, v18
	s_barrier
	s_branch .LBB0_185

; #define PG8_STAGE(bufoff, gbase, voff) do { _Pragma("unroll") for (int _i = 0; _i < 2; ++_i) \
;     __builtin_amdgcn_global_load_lds((const unsigned*)((const char*)(gbase) + (voff)[_i]), (LAS unsigned*)(lds + (bufoff) + ldsw + _i * 8192), 16, 0, 0); } while (0)
; #define PG8_LDA(dst, b, h) do { _Pragma("unroll") for (int m = 0; m < 4; ++m) _Pragma("unroll") for (int k = 0; k < 2; ++k) dst[m][k] = *(const LAS bf16x8*)(lds + PG8_SA(b, h) + aoff + m * 2048 + k * 1024); } while (0)
; #define PG8_LDB(dst, b, h) do { _Pragma("unroll") for (int n = 0; n < 2; ++n) _Pragma("unroll") for (int k = 0; k < 2; ++k) dst[n][k] = *(const LAS bf16x8*)(lds + PG8_SB(b, h) + boff + n * 2048 + k * 1024); } while (0)
; #define PG8_MMA(ai, bj, At, Bt) do { __builtin_amdgcn_s_setprio(1); _Pragma("unroll") for (int m = 0; m < 4; ++m) _Pragma("unroll") for (int n = 0; n < 2; ++n) _Pragma("unroll") for (int k = 0; k < 2; ++k) \
;     acc[ai][bj][m][n] = __builtin_amdgcn_mfma_f32_16x16x32_bf16(Bt[n][k], At[m][k], acc[ai][bj][m][n], 0, 0, 0); __builtin_amdgcn_s_setprio(0); } while (0)
; #define PG8_WAIT_L(n) asm volatile("s_waitcnt lgkmcnt(" #n ")" ::: "memory")
; #define PG8_BAR __builtin_amdgcn_s_barrier()
; #define PG8_SCHED __builtin_amdgcn_sched_barrier(0)
; template <class Epi, bool SPLITA = false>
; __device__ __forceinline__ void gemm_phase(const int tid, LAS unsigned char* lds, const Gemm g, const Order& S, const Epi& E) {
;     ...
;     for (int t = 0; t < nt; t += 2) {
;       const bool last = (t == nt - 2);
;       if constexpr (SPLITA) { if (t == nt1) E.mid(acc, cur, wr, wc, fr, fq); }
;       const char* a1 = PG8_TA(t + 1);
;       const char* a2 = last ? nA : PG8_TA(t + 2); const char* b2 = last ? nB : cB + (size_t)(t + 2) * kstep;
;       const char* a3 = last ? nA + kstep : PG8_TA(t + 3); const char* b3 = b2 + kstep;
;       PG8_LDB(B0, 0, 0); PG8_SCHED; PG8_LDA(At, 0, 0); PG8_STAGE(PG8_SA(1, 1), a1 + hstepA, voffA);
;       PG8_WAIT_L(8); PG8_BAR; PG8_WAIT_L(0); PG8_MMA(0, 0, At, B0); PG8_BAR; PG8_SCHED;
;       PG8_LDB(B1, 0, 1); PG8_STAGE(PG8_SB(0, 0), b2, voffB);
;       PG8_BAR; PG8_WAIT_L(0); PG8_MMA(0, 1, At, B1); PG8_BAR;
;       PG8_LDA(At, 0, 1); PG8_STAGE(PG8_SA(0, 0), a2, voffA);
;       PG8_BAR; PG8_WAIT_L(0); PG8_MMA(1, 0, At, B0); PG8_BAR; PG8_SCHED;
.LBB0_192:
	s_add_u32 s20, s40, s42
	s_addc_u32 s21, s41, s43
	s_add_u32 s48, s20, 0x100
	s_addc_u32 s49, s21, 0
	s_add_u32 s44, vcc_lo, s42
	s_addc_u32 s45, vcc_hi, s43
	s_add_u32 s20, s20, 0x180
	s_addc_u32 s21, s21, 0
	s_add_i32 s94, 0, 0x10000
	v_add_u32_e32 v146, s94, v188
	ds_read_b128 v[134:137], v146
	ds_read_b128 v[138:141], v146 offset:1024
	ds_read_b128 v[142:145], v146 offset:2048
	ds_read_b128 v[146:149], v146 offset:3072
	s_cmpk_eq_i32 s42, 0xf00
	s_cselect_b32 s47, s19, s21
	s_cselect_b32 s46, s13, s20
	s_cselect_b32 s45, s7, s45
	s_cselect_b32 s44, s11, s44
	s_cselect_b32 s49, s4, s49
	s_cselect_b32 s48, s6, s48
	v_lshl_add_u64 v[184:185], v[130:131], 0, s[42:43]
	s_add_i32 m0, s23, 0xc000
	ds_read_b128 v[150:153], v189
	ds_read_b128 v[154:157], v189 offset:1024
	ds_read_b128 v[168:171], v189 offset:2048
	ds_read_b128 v[172:175], v189 offset:3072
	ds_read_b128 v[176:179], v189 offset:4096
	ds_read_b128 v[180:183], v189 offset:5120
	ds_read_b128 v[190:193], v189 offset:6144
	ds_read_b128 v[212:215], v189 offset:7168
	global_load_lds_dwordx4 v[184:185], off
	v_lshl_add_u64 v[184:185], v[132:133], 0, s[42:43]
	s_add_i32 m0, s23, 0xe000
	s_nop 0
	global_load_lds_dwordx4 v[184:185], off
	s_waitcnt lgkmcnt(8)
	s_barrier
	s_waitcnt lgkmcnt(0)
	s_setprio 1
	s_waitcnt lgkmcnt(0)
	v_mfma_f32_16x16x32_bf16 v[126:129], v[134:137], v[150:153], v[126:129]
	v_mfma_f32_16x16x32_bf16 v[122:125], v[142:145], v[150:153], v[122:125]
	v_mfma_f32_16x16x32_bf16 v[110:113], v[134:137], v[168:171], v[110:113]
	v_mfma_f32_16x16x32_bf16 v[106:109], v[142:145], v[168:171], v[106:109]
	v_mfma_f32_16x16x32_bf16 v[94:97], v[134:137], v[176:179], v[94:97]
	v_mfma_f32_16x16x32_bf16 v[90:93], v[142:145], v[176:179], v[90:93]
	v_mfma_f32_16x16x32_bf16 v[78:81], v[134:137], v[190:193], v[78:81]
	v_mfma_f32_16x16x32_bf16 v[74:77], v[142:145], v[190:193], v[74:77]
	v_mfma_f32_16x16x32_bf16 v[126:129], v[138:141], v[154:157], v[126:129]
	v_mfma_f32_16x16x32_bf16 v[122:125], v[146:149], v[154:157], v[122:125]
	v_mfma_f32_16x16x32_bf16 v[110:113], v[138:141], v[172:175], v[110:113]
	v_mfma_f32_16x16x32_bf16 v[106:109], v[146:149], v[172:175], v[106:109]
	v_mfma_f32_16x16x32_bf16 v[94:97], v[138:141], v[180:183], v[94:97]
	v_mfma_f32_16x16x32_bf16 v[90:93], v[146:149], v[180:183], v[90:93]
	v_mfma_f32_16x16x32_bf16 v[78:81], v[138:141], v[212:215], v[78:81]
	v_mfma_f32_16x16x32_bf16 v[74:77], v[146:149], v[212:215], v[74:77]
	s_setprio 0
	s_barrier
	s_add_i32 s8, 0, 0x14000
	v_add_u32_e32 v184, s8, v188
	s_add_i32 s9, s94, s3
	ds_read_b128 v[216:219], v184
	ds_read_b128 v[220:223], v184 offset:1024
	ds_read_b128 v[224:227], v184 offset:2048
	ds_read_b128 v[228:231], v184 offset:3072
	v_lshl_add_u64 v[184:185], s[44:45], 0, v[0:1]
	s_mov_b32 m0, s9
	v_lshl_add_u64 v[198:199], s[44:45], 0, v[162:163]
	global_load_lds_dwordx4 v0, s[44:45]
	s_add_i32 m0, s9, 0x2000
	s_nop 0
	global_load_lds_dwordx4 v162, s[44:45]
	s_barrier
	s_waitcnt lgkmcnt(0)
	s_setprio 1
	s_waitcnt lgkmcnt(0)
	v_mfma_f32_16x16x32_bf16 v[118:121], v[216:219], v[150:153], v[118:121]
	v_mfma_f32_16x16x32_bf16 v[114:117], v[224:227], v[150:153], v[114:117]
	v_mfma_f32_16x16x32_bf16 v[102:105], v[216:219], v[168:171], v[102:105]
	v_mfma_f32_16x16x32_bf16 v[98:101], v[224:227], v[168:171], v[98:101]
	v_mfma_f32_16x16x32_bf16 v[86:89], v[216:219], v[176:179], v[86:89]
	v_mfma_f32_16x16x32_bf16 v[82:85], v[224:227], v[176:179], v[82:85]
	v_mfma_f32_16x16x32_bf16 v[70:73], v[216:219], v[190:193], v[70:73]
	v_mfma_f32_16x16x32_bf16 v[66:69], v[224:227], v[190:193], v[66:69]
	v_mfma_f32_16x16x32_bf16 v[118:121], v[220:223], v[154:157], v[118:121]
	v_mfma_f32_16x16x32_bf16 v[114:117], v[228:231], v[154:157], v[114:117]
	v_mfma_f32_16x16x32_bf16 v[102:105], v[220:223], v[172:175], v[102:105]
	v_mfma_f32_16x16x32_bf16 v[98:101], v[228:231], v[172:175], v[98:101]
	v_mfma_f32_16x16x32_bf16 v[86:89], v[220:223], v[180:183], v[86:89]
	v_mfma_f32_16x16x32_bf16 v[82:85], v[228:231], v[180:183], v[82:85]
	v_mfma_f32_16x16x32_bf16 v[70:73], v[220:223], v[212:215], v[70:73]
	v_mfma_f32_16x16x32_bf16 v[66:69], v[228:231], v[212:215], v[66:69]
	s_setprio 0
	s_mov_b32 m0, s23
	s_barrier
	ds_read_b128 v[150:153], v189 offset:16384
	ds_read_b128 v[154:157], v189 offset:17408
	ds_read_b128 v[168:171], v189 offset:18432
	ds_read_b128 v[172:175], v189 offset:19456
	ds_read_b128 v[176:179], v189 offset:20480
	ds_read_b128 v[180:183], v189 offset:21504
	ds_read_b128 v[190:193], v189 offset:22528
	ds_read_b128 v[212:215], v189 offset:23552
	global_load_lds_dwordx4 v158, s[48:49]
	s_mov_b32 m0, s51
	s_nop 0
	global_load_lds_dwordx4 v160, s[48:49]
	s_barrier
	s_waitcnt lgkmcnt(0)
	s_setprio 1
	s_waitcnt lgkmcnt(0)
	v_mfma_f32_16x16x32_bf16 v[62:65], v[134:137], v[150:153], v[62:65]
	v_mfma_f32_16x16x32_bf16 v[58:61], v[142:145], v[150:153], v[58:61]
	v_mfma_f32_16x16x32_bf16 v[46:49], v[134:137], v[168:171], v[46:49]
	v_mfma_f32_16x16x32_bf16 v[42:45], v[142:145], v[168:171], v[42:45]
	v_mfma_f32_16x16x32_bf16 v[30:33], v[134:137], v[176:179], v[30:33]
	v_mfma_f32_16x16x32_bf16 v[26:29], v[142:145], v[176:179], v[26:29]
	v_mfma_f32_16x16x32_bf16 v[14:17], v[134:137], v[190:193], v[14:17]
	v_mfma_f32_16x16x32_bf16 v[10:13], v[142:145], v[190:193], v[10:13]
	v_mfma_f32_16x16x32_bf16 v[62:65], v[138:141], v[154:157], v[62:65]
	v_mfma_f32_16x16x32_bf16 v[58:61], v[146:149], v[154:157], v[58:61]
	v_mfma_f32_16x16x32_bf16 v[46:49], v[138:141], v[172:175], v[46:49]
	v_mfma_f32_16x16x32_bf16 v[42:45], v[146:149], v[172:175], v[42:45]
	v_mfma_f32_16x16x32_bf16 v[30:33], v[138:141], v[180:183], v[30:33]
	v_mfma_f32_16x16x32_bf16 v[26:29], v[146:149], v[180:183], v[26:29]
	v_mfma_f32_16x16x32_bf16 v[14:17], v[138:141], v[212:215], v[14:17]
	v_mfma_f32_16x16x32_bf16 v[10:13], v[146:149], v[212:215], v[10:13]
	s_setprio 0
	s_barrier
; #define PG8_STAGE(bufoff, gbase, voff) do { _Pragma("unroll") for (int _i = 0; _i < 2; ++_i) \
;     __builtin_amdgcn_global_load_lds((const unsigned*)((const char*)(gbase) + (voff)[_i]), (LAS unsigned*)(lds + (bufoff) + ldsw + _i * 8192), 16, 0, 0); } while (0)
; #define PG8_LDA(dst, b, h) do { _Pragma("unroll") for (int m = 0; m < 4; ++m) _Pragma("unroll") for (int k = 0; k < 2; ++k) dst[m][k] = *(const LAS bf16x8*)(lds + PG8_SA(b, h) + aoff + m * 2048 + k * 1024); } while (0)
; #define PG8_LDB(dst, b, h) do { _Pragma("unroll") for (int n = 0; n < 2; ++n) _Pragma("unroll") for (int k = 0; k < 2; ++k) dst[n][k] = *(const LAS bf16x8*)(lds + PG8_SB(b, h) + boff + n * 2048 + k * 1024); } while (0)
; #define PG8_MMA(ai, bj, At, Bt) do { __builtin_amdgcn_s_setprio(1); _Pragma("unroll") for (int m = 0; m < 4; ++m) _Pragma("unroll") for (int n = 0; n < 2; ++n) _Pragma("unroll") for (int k = 0; k < 2; ++k) \
;     acc[ai][bj][m][n] = __builtin_amdgcn_mfma_f32_16x16x32_bf16(Bt[n][k], At[m][k], acc[ai][bj][m][n], 0, 0, 0); __builtin_amdgcn_s_setprio(0); } while (0)
; #define PG8_WAIT_V(n) asm volatile("s_waitcnt vmcnt(" #n ")" ::: "memory")
; #define PG8_WAIT_L(n) asm volatile("s_waitcnt lgkmcnt(" #n ")" ::: "memory")
; #define PG8_BAR __builtin_amdgcn_s_barrier()
; #define PG8_SCHED __builtin_amdgcn_sched_barrier(0)
; template <class Epi, bool SPLITA = false>
; __device__ __forceinline__ void gemm_phase(const int tid, LAS unsigned char* lds, const Gemm g, const Order& S, const Epi& E) {
;     ...
;       PG8_BAR; PG8_WAIT_L(0); PG8_MMA(1, 0, At, B0); PG8_BAR; PG8_SCHED;
;       PG8_STAGE(PG8_SB(0, 1), b2 + hstepB, voffB);
;       PG8_WAIT_V(6); PG8_BAR; PG8_MMA(1, 1, At, B1); PG8_BAR;
;       PG8_LDB(B0, 1, 0); PG8_SCHED; PG8_LDA(At, 1, 0); PG8_STAGE(PG8_SA(0, 1), a2 + hstepA, voffA);
;       PG8_WAIT_L(8); PG8_BAR; PG8_WAIT_L(0); PG8_MMA(0, 0, At, B0); PG8_BAR; PG8_SCHED;
;       PG8_LDB(B1, 1, 1); PG8_STAGE(PG8_SB(1, 0), b3, voffB);
;       PG8_BAR; PG8_WAIT_L(0); PG8_MMA(0, 1, At, B1); PG8_BAR;
;       PG8_LDA(At, 1, 1); PG8_STAGE(PG8_SA(1, 0), a3, voffA);
;       PG8_BAR; PG8_WAIT_L(0); PG8_MMA(1, 0, At, B0); PG8_BAR; PG8_SCHED;
	s_add_u32 s20, s44, 0x80000
	s_addc_u32 s21, s45, 0
	s_add_i32 s8, s8, s3
	s_mov_b32 m0, s8
	s_nop 0
	global_load_lds_dwordx4 v0, s[20:21]
	v_lshl_add_u64 v[134:135], s[20:21], 0, v[162:163]
	s_add_i32 m0, s8, 0x2000
	s_nop 0
	global_load_lds_dwordx4 v162, s[20:21]
	s_waitcnt vmcnt(6)
	s_barrier
	s_setprio 1
	v_mfma_f32_16x16x32_bf16 v[54:57], v[216:219], v[150:153], v[54:57]
	v_mfma_f32_16x16x32_bf16 v[50:53], v[224:227], v[150:153], v[50:53]
	v_mfma_f32_16x16x32_bf16 v[38:41], v[216:219], v[168:171], v[38:41]
	v_mfma_f32_16x16x32_bf16 v[34:37], v[224:227], v[168:171], v[34:37]
	v_mfma_f32_16x16x32_bf16 v[22:25], v[216:219], v[176:179], v[22:25]
	v_mfma_f32_16x16x32_bf16 v[18:21], v[224:227], v[176:179], v[18:21]
	v_mfma_f32_16x16x32_bf16 v[6:9], v[216:219], v[190:193], v[6:9]
	v_mfma_f32_16x16x32_bf16 v[2:5], v[224:227], v[190:193], v[2:5]
	v_mfma_f32_16x16x32_bf16 v[54:57], v[220:223], v[154:157], v[54:57]
	v_mfma_f32_16x16x32_bf16 v[50:53], v[228:231], v[154:157], v[50:53]
	v_mfma_f32_16x16x32_bf16 v[38:41], v[220:223], v[172:175], v[38:41]
	v_mfma_f32_16x16x32_bf16 v[34:37], v[228:231], v[172:175], v[34:37]
	v_mfma_f32_16x16x32_bf16 v[22:25], v[220:223], v[180:183], v[22:25]
	v_mfma_f32_16x16x32_bf16 v[18:21], v[228:231], v[180:183], v[18:21]
	v_mfma_f32_16x16x32_bf16 v[6:9], v[220:223], v[212:215], v[6:9]
	v_mfma_f32_16x16x32_bf16 v[2:5], v[228:231], v[212:215], v[2:5]
	s_setprio 0
	s_add_i32 s8, 0, 0x18000
	v_add_u32_e32 v146, s8, v188
	s_barrier
	ds_read_b128 v[134:137], v146
	ds_read_b128 v[138:141], v146 offset:1024
	ds_read_b128 v[142:145], v146 offset:2048
	ds_read_b128 v[146:149], v146 offset:3072
	s_add_u32 s20, s48, 0x80000
	s_addc_u32 s21, s49, 0
	s_mov_b32 m0, s52
	ds_read_b128 v[150:153], v189 offset:32768
	ds_read_b128 v[154:157], v189 offset:33792
	ds_read_b128 v[168:171], v189 offset:34816
	ds_read_b128 v[172:175], v189 offset:35840
	ds_read_b128 v[176:179], v189 offset:36864
	ds_read_b128 v[180:183], v189 offset:37888
	ds_read_b128 v[190:193], v189 offset:38912
	ds_read_b128 v[212:215], v189 offset:39936
	global_load_lds_dwordx4 v158, s[20:21]
	s_mov_b32 m0, s53
	s_nop 0
	global_load_lds_dwordx4 v160, s[20:21]
	s_waitcnt lgkmcnt(8)
	s_barrier
	s_waitcnt lgkmcnt(0)
	s_setprio 1
	s_waitcnt lgkmcnt(0)
	v_mfma_f32_16x16x32_bf16 v[126:129], v[134:137], v[150:153], v[126:129]
	v_mfma_f32_16x16x32_bf16 v[122:125], v[142:145], v[150:153], v[122:125]
	v_mfma_f32_16x16x32_bf16 v[110:113], v[134:137], v[168:171], v[110:113]
	v_mfma_f32_16x16x32_bf16 v[106:109], v[142:145], v[168:171], v[106:109]
	v_mfma_f32_16x16x32_bf16 v[94:97], v[134:137], v[176:179], v[94:97]
	v_mfma_f32_16x16x32_bf16 v[90:93], v[142:145], v[176:179], v[90:93]
	v_mfma_f32_16x16x32_bf16 v[78:81], v[134:137], v[190:193], v[78:81]
	v_mfma_f32_16x16x32_bf16 v[74:77], v[142:145], v[190:193], v[74:77]
	v_mfma_f32_16x16x32_bf16 v[126:129], v[138:141], v[154:157], v[126:129]
	v_mfma_f32_16x16x32_bf16 v[122:125], v[146:149], v[154:157], v[122:125]
	v_mfma_f32_16x16x32_bf16 v[110:113], v[138:141], v[172:175], v[110:113]
	v_mfma_f32_16x16x32_bf16 v[106:109], v[146:149], v[172:175], v[106:109]
	v_mfma_f32_16x16x32_bf16 v[94:97], v[138:141], v[180:183], v[94:97]
	v_mfma_f32_16x16x32_bf16 v[90:93], v[146:149], v[180:183], v[90:93]
	v_mfma_f32_16x16x32_bf16 v[78:81], v[138:141], v[212:215], v[78:81]
	v_mfma_f32_16x16x32_bf16 v[74:77], v[146:149], v[212:215], v[74:77]
	s_setprio 0
	s_barrier
	s_add_i32 s9, 0, 0x1c000
	s_add_i32 s8, s8, s3
	v_add_u32_e32 v195, s9, v188
	v_lshl_add_u64 v[184:185], v[184:185], 0, s[96:97]
	s_mov_b32 m0, s8
	ds_read_b128 v[216:219], v195
	ds_read_b128 v[220:223], v195 offset:1024
	ds_read_b128 v[224:227], v195 offset:2048
	ds_read_b128 v[228:231], v195 offset:3072
	global_load_lds_dwordx4 v[184:185], off
	v_lshl_add_u64 v[184:185], v[198:199], 0, s[96:97]
	s_add_i32 m0, s8, 0x2000
	s_nop 0
	global_load_lds_dwordx4 v[184:185], off
	s_barrier
	s_waitcnt lgkmcnt(0)
	s_setprio 1
	s_waitcnt lgkmcnt(0)
	v_mfma_f32_16x16x32_bf16 v[118:121], v[216:219], v[150:153], v[118:121]
	v_mfma_f32_16x16x32_bf16 v[114:117], v[224:227], v[150:153], v[114:117]
	v_mfma_f32_16x16x32_bf16 v[102:105], v[216:219], v[168:171], v[102:105]
	v_mfma_f32_16x16x32_bf16 v[98:101], v[224:227], v[168:171], v[98:101]
	v_mfma_f32_16x16x32_bf16 v[86:89], v[216:219], v[176:179], v[86:89]
	v_mfma_f32_16x16x32_bf16 v[82:85], v[224:227], v[176:179], v[82:85]
	v_mfma_f32_16x16x32_bf16 v[70:73], v[216:219], v[190:193], v[70:73]
	v_mfma_f32_16x16x32_bf16 v[66:69], v[224:227], v[190:193], v[66:69]
	v_mfma_f32_16x16x32_bf16 v[118:121], v[220:223], v[154:157], v[118:121]
	v_mfma_f32_16x16x32_bf16 v[114:117], v[228:231], v[154:157], v[114:117]
	v_mfma_f32_16x16x32_bf16 v[102:105], v[220:223], v[172:175], v[102:105]
	v_mfma_f32_16x16x32_bf16 v[98:101], v[228:231], v[172:175], v[98:101]
	v_mfma_f32_16x16x32_bf16 v[86:89], v[220:223], v[180:183], v[86:89]
	v_mfma_f32_16x16x32_bf16 v[82:85], v[228:231], v[180:183], v[82:85]
	v_mfma_f32_16x16x32_bf16 v[70:73], v[220:223], v[212:215], v[70:73]
	v_mfma_f32_16x16x32_bf16 v[66:69], v[228:231], v[212:215], v[66:69]
	s_setprio 0
	s_mov_b32 m0, s91
	s_barrier
	ds_read_b128 v[150:153], v189 offset:49152
	ds_read_b128 v[154:157], v189 offset:50176
	ds_read_b128 v[168:171], v189 offset:51200
	ds_read_b128 v[172:175], v189 offset:52224
	ds_read_b128 v[176:179], v189 offset:53248
	ds_read_b128 v[180:183], v189 offset:54272
	ds_read_b128 v[190:193], v189 offset:55296
	ds_read_b128 v[212:215], v189 offset:56320
	global_load_lds_dwordx4 v158, s[46:47]
	s_mov_b32 m0, s93
	s_nop 0
	global_load_lds_dwordx4 v160, s[46:47]
	s_barrier
; #define PG8_STAGE(bufoff, gbase, voff) do { _Pragma("unroll") for (int _i = 0; _i < 2; ++_i) \
;     __builtin_amdgcn_global_load_lds((const unsigned*)((const char*)(gbase) + (voff)[_i]), (LAS unsigned*)(lds + (bufoff) + ldsw + _i * 8192), 16, 0, 0); } while (0)
; #define PG8_MMA(ai, bj, At, Bt) do { __builtin_amdgcn_s_setprio(1); _Pragma("unroll") for (int m = 0; m < 4; ++m) _Pragma("unroll") for (int n = 0; n < 2; ++n) _Pragma("unroll") for (int k = 0; k < 2; ++k) \
;     acc[ai][bj][m][n] = __builtin_amdgcn_mfma_f32_16x16x32_bf16(Bt[n][k], At[m][k], acc[ai][bj][m][n], 0, 0, 0); __builtin_amdgcn_s_setprio(0); } while (0)
; #define PG8_WAIT_V(n) asm volatile("s_waitcnt vmcnt(" #n ")" ::: "memory")
; #define PG8_WAIT_L(n) asm volatile("s_waitcnt lgkmcnt(" #n ")" ::: "memory")
; #define PG8_BAR __builtin_amdgcn_s_barrier()
; #define PG8_SCHED __builtin_amdgcn_sched_barrier(0)
; template <class Epi, bool SPLITA = false>
; __device__ __forceinline__ void gemm_phase(const int tid, LAS unsigned char* lds, const Gemm g, const Order& S, const Epi& E) {
;     ...
;       PG8_BAR; PG8_WAIT_L(0); PG8_MMA(1, 0, At, B0); PG8_BAR; PG8_SCHED;
;       PG8_STAGE(PG8_SB(1, 1), b3 + hstepB, voffB);
;       PG8_WAIT_V(6); PG8_BAR; PG8_MMA(1, 1, At, B1); PG8_BAR;
	s_waitcnt lgkmcnt(0)
	s_setprio 1
	s_waitcnt lgkmcnt(0)
	v_mfma_f32_16x16x32_bf16 v[62:65], v[134:137], v[150:153], v[62:65]
	v_mfma_f32_16x16x32_bf16 v[58:61], v[142:145], v[150:153], v[58:61]
	v_mfma_f32_16x16x32_bf16 v[46:49], v[134:137], v[168:171], v[46:49]
	v_mfma_f32_16x16x32_bf16 v[42:45], v[142:145], v[168:171], v[42:45]
	v_mfma_f32_16x16x32_bf16 v[30:33], v[134:137], v[176:179], v[30:33]
	v_mfma_f32_16x16x32_bf16 v[26:29], v[142:145], v[176:179], v[26:29]
	v_mfma_f32_16x16x32_bf16 v[14:17], v[134:137], v[190:193], v[14:17]
	v_mfma_f32_16x16x32_bf16 v[10:13], v[142:145], v[190:193], v[10:13]
	v_mfma_f32_16x16x32_bf16 v[62:65], v[138:141], v[154:157], v[62:65]
	v_mfma_f32_16x16x32_bf16 v[58:61], v[146:149], v[154:157], v[58:61]
	v_mfma_f32_16x16x32_bf16 v[46:49], v[138:141], v[172:175], v[46:49]
	v_mfma_f32_16x16x32_bf16 v[42:45], v[146:149], v[172:175], v[42:45]
	v_mfma_f32_16x16x32_bf16 v[30:33], v[138:141], v[180:183], v[30:33]
	v_mfma_f32_16x16x32_bf16 v[26:29], v[146:149], v[180:183], v[26:29]
	v_mfma_f32_16x16x32_bf16 v[14:17], v[138:141], v[212:215], v[14:17]
	v_mfma_f32_16x16x32_bf16 v[10:13], v[146:149], v[212:215], v[10:13]
	s_setprio 0
	s_barrier
	s_add_u32 s20, s44, 0x80080
	s_addc_u32 s21, s45, 0
	s_add_i32 s8, s9, s3
	s_mov_b32 m0, s8
	s_nop 0
	global_load_lds_dwordx4 v0, s[20:21]
	s_add_i32 m0, s8, 0x2000
	s_nop 0
	global_load_lds_dwordx4 v162, s[20:21]
	s_waitcnt vmcnt(6)
	s_barrier
	s_setprio 1
	v_mfma_f32_16x16x32_bf16 v[54:57], v[216:219], v[150:153], v[54:57]
	v_mfma_f32_16x16x32_bf16 v[50:53], v[224:227], v[150:153], v[50:53]
	v_mfma_f32_16x16x32_bf16 v[38:41], v[216:219], v[168:171], v[38:41]
	v_mfma_f32_16x16x32_bf16 v[34:37], v[224:227], v[168:171], v[34:37]
	v_mfma_f32_16x16x32_bf16 v[22:25], v[216:219], v[176:179], v[22:25]
	v_mfma_f32_16x16x32_bf16 v[18:21], v[224:227], v[176:179], v[18:21]
	v_mfma_f32_16x16x32_bf16 v[6:9], v[216:219], v[190:193], v[6:9]
	v_mfma_f32_16x16x32_bf16 v[2:5], v[224:227], v[190:193], v[2:5]
	v_mfma_f32_16x16x32_bf16 v[54:57], v[220:223], v[154:157], v[54:57]
	v_mfma_f32_16x16x32_bf16 v[50:53], v[228:231], v[154:157], v[50:53]
	v_mfma_f32_16x16x32_bf16 v[38:41], v[220:223], v[172:175], v[38:41]
	v_mfma_f32_16x16x32_bf16 v[34:37], v[228:231], v[172:175], v[34:37]
	v_mfma_f32_16x16x32_bf16 v[22:25], v[220:223], v[180:183], v[22:25]
	v_mfma_f32_16x16x32_bf16 v[18:21], v[228:231], v[180:183], v[18:21]
	v_mfma_f32_16x16x32_bf16 v[6:9], v[220:223], v[212:215], v[6:9]
	v_mfma_f32_16x16x32_bf16 v[2:5], v[228:231], v[212:215], v[2:5]
	s_setprio 0
	s_add_i32 s29, s29, 2
	s_add_u32 s42, s42, 0x100
	s_addc_u32 s43, s43, 0
	s_cmp_gt_u32 s29, 29
	s_barrier
	s_cbranch_scc0 .LBB0_192
; __device__ __forceinline__ float bflo(unsigned w) { return __uint_as_float(w << 16); }
; __device__ __forceinline__ float bfhi(unsigned w) { return __uint_as_float(w & 0xffff0000u); }
; __device__ __forceinline__ float lane_read(float v, int src) { return __int_as_float(__builtin_amdgcn_ds_bpermute(src << 2, __float_as_int(v))); }
; __device__ __forceinline__ u32x4 pack8(const f32x4 v0, const f32x4 v1) { u32x4 w; w.x = cvtpk(v0[0], v0[1]); w.y = cvtpk(v0[2], v0[3]); w.z = cvtpk(v1[0], v1[1]); w.w = cvtpk(v1[2], v1[3]); return w; }
;   __device__ __forceinline__ void operator()(const Acc& acc, const Unit& u, int wr, int wc, int fr_, int fq_) const {
;     int fr = fr_, fq = fq_; asm volatile("" : "+v"(fr), "+v"(fq));
;     const int lane = fq * 16 + fr;
;     const int row0 = u.pm * BM + wr * 64 + fr, col0 = u.pn * BM + wc * 32 + 8 * fq;
; #pragma unroll
;     for (int ai = 0; ai < 2; ++ai) {
;       u32x4 hv[4][2];
; #pragma unroll
;       for (int m = 0; m < 4; ++m)
; #pragma unroll
;         for (int bj = 0; bj < 2; ++bj) hv[m][bj] = *(const u32x4*)(rin + (size_t)(row0 + ai * HALF + m * 16) * DM + col0 + bj * HALF);
; #pragma unroll
;       for (int m = 0; m < 4; ++m) { const size_t ro = (size_t)(row0 + ai * HALF + m * 16) * DM + col0; float ss = 0.f;
; #pragma unroll
;         for (int bj = 0; bj < 2; ++bj) { const u32x4 h = hv[m][bj];
;           f32x4 v0 = acc[ai][bj][m][0], v1 = acc[ai][bj][m][1];
;           v0[0] += bflo(h.x); v0[1] += bfhi(h.x); v0[2] += bflo(h.y); v0[3] += bfhi(h.y);
;           v1[0] += bflo(h.z); v1[1] += bfhi(h.z); v1[2] += bflo(h.w); v1[3] += bfhi(h.w);
;           if (FINAL) { *(f32x4*)(outf + ro + bj * HALF) = v0; *(f32x4*)(outf + ro + bj * HALF + 4) = v1; }
;           else { ss += v0[0] * v0[0] + v0[1] * v0[1] + v0[2] * v0[2] + v0[3] * v0[3] + v1[0] * v1[0] + v1[1] * v1[1] + v1[2] * v1[2] + v1[3] * v1[3];
;             *(u32x4*)(outb + ro + bj * HALF) = pack8(v0, v1); } }
;         if (!FINAL) { ss += lane_read(ss, lane ^ 16); ss += lane_read(ss, lane ^ 32);
;           if (fq == 0) rss[(size_t)(row0 + ai * HALF + m * 16) * 32 + u.pn * 4 + wc] = ss; } }
	s_lshl_b32 s4, s22, 8
	v_mov_b32_e32 v130, v187
	v_mov_b32_e32 v131, v186
	s_add_i32 s4, s4, s55
	s_nop 0
	v_add_u32_e32 v170, s4, v130
	s_lshl_b32 s4, s18, 8
	s_or_b32 s4, s4, s90
	v_lshl_add_u32 v168, v131, 3, s4
	v_ashrrev_i32_e32 v169, 31, v168
	v_lshlrev_b32_e32 v130, 2, v130
	v_lshlrev_b64 v[192:193], 1, v[168:169]
	v_ashrrev_i32_e32 v171, 31, v170
	v_lshl_add_u32 v130, v131, 6, v130
	v_lshl_add_u64 v[172:173], s[86:87], 0, v[192:193]
	v_lshlrev_b64 v[198:199], 12, v[170:171]
	v_xor_b32_e32 v191, 64, v130
	v_xor_b32_e32 v190, 0x80, v130
	v_cmp_eq_u32_e32 vcc, 0, v131
	v_lshl_add_u64 v[130:131], v[172:173], 0, v[198:199]
	global_load_dwordx4 v[212:215], v[130:131], off
	global_load_dwordx4 v[154:157], v[130:131], off offset:256
	v_add_u32_e32 v182, 16, v170
	v_ashrrev_i32_e32 v183, 31, v182
	v_add_u32_e32 v178, 32, v170
	v_lshlrev_b64 v[184:185], 12, v[182:183]
	v_ashrrev_i32_e32 v179, 31, v178
	v_add_u32_e32 v174, 48, v170
	v_lshl_add_u64 v[130:131], v[172:173], 0, v[184:185]
	v_lshlrev_b64 v[180:181], 12, v[178:179]
	v_ashrrev_i32_e32 v175, 31, v174
	global_load_dwordx4 v[150:153], v[130:131], off
	global_load_dwordx4 v[146:149], v[130:131], off offset:256
	v_lshl_add_u64 v[130:131], v[172:173], 0, v[180:181]
	v_lshlrev_b64 v[176:177], 12, v[174:175]
	global_load_dwordx4 v[142:145], v[130:131], off
	global_load_dwordx4 v[138:141], v[130:131], off offset:256
	v_lshl_add_u64 v[130:131], v[172:173], 0, v[176:177]
	global_load_dwordx4 v[134:137], v[130:131], off
	s_nop 0
	global_load_dwordx4 v[130:133], v[130:131], off offset:256
	s_lshl_b32 s18, s18, 2
	s_ashr_i32 s19, s18, 31
	s_waitcnt vmcnt(0)
	v_lshlrev_b32_e32 v200, 16, v212
	v_and_b32_e32 v201, 0xffff0000, v212
	v_pk_add_f32 v[126:127], v[126:127], v[200:201]
	v_lshlrev_b32_e32 v200, 16, v213
	v_and_b32_e32 v201, 0xffff0000, v213
	v_pk_add_f32 v[128:129], v[128:129], v[200:201]
	v_lshlrev_b32_e32 v200, 16, v214
	v_and_b32_e32 v201, 0xffff0000, v214
	v_pk_add_f32 v[200:201], v[122:123], v[200:201]
	v_lshlrev_b32_e32 v122, 16, v215
	v_and_b32_e32 v123, 0xffff0000, v215
	v_pk_add_f32 v[202:203], v[124:125], v[122:123]
	v_pk_mul_f32 v[204:205], v[126:127], v[126:127]
	v_cvt_pk_bf16_f32 v122, v126, v127
	v_lshl_add_u64 v[126:127], s[0:1], 0, v[198:199]
	v_cvt_pk_bf16_f32 v123, v128, v129
	v_cvt_pk_bf16_f32 v124, v200, v201
	v_cvt_pk_bf16_f32 v125, v202, v203
	v_lshl_add_u64 v[126:127], v[126:127], 0, v[192:193]
	global_store_dwordx4 v[126:127], v[122:125], off
	v_pk_mul_f32 v[206:207], v[128:129], v[128:129]
	v_pk_mul_f32 v[212:213], v[200:201], v[200:201]
	v_lshlrev_b32_e32 v122, 16, v154
	v_and_b32_e32 v123, 0xffff0000, v154
	v_pk_add_f32 v[118:119], v[118:119], v[122:123]
	v_lshlrev_b32_e32 v122, 16, v155
	v_and_b32_e32 v123, 0xffff0000, v155
	v_pk_add_f32 v[120:121], v[120:121], v[122:123]
	v_lshlrev_b32_e32 v122, 16, v156
	v_and_b32_e32 v123, 0xffff0000, v156
	v_pk_add_f32 v[122:123], v[114:115], v[122:123]
	v_lshlrev_b32_e32 v114, 16, v157
	v_and_b32_e32 v115, 0xffff0000, v157
	v_pk_add_f32 v[124:125], v[116:117], v[114:115]
	v_pk_mul_f32 v[114:115], v[118:119], v[118:119]
	v_pk_mul_f32 v[116:117], v[120:121], v[120:121]
	v_add_f32_e32 v114, v114, v115
	v_add_f32_e32 v115, v204, v205
	v_add_f32_e32 v114, v116, v114
	v_add_f32_e32 v115, v206, v115
	v_pk_mul_f32 v[128:129], v[122:123], v[122:123]
	v_add_f32_e32 v114, v117, v114
	v_add_f32_e32 v115, v207, v115
	v_add_f32_e32 v114, v128, v114
	v_add_f32_e32 v115, v212, v115
	v_pk_mul_f32 v[214:215], v[202:203], v[202:203]
	v_pk_mul_f32 v[154:155], v[124:125], v[124:125]
	v_add_f32_e32 v114, v129, v114
	v_add_f32_e32 v115, v213, v115
	v_add_f32_e32 v114, v154, v114
	v_add_f32_e32 v115, v214, v115
	v_add_f32_e32 v114, v155, v114
	v_add_f32_e32 v115, v215, v115
	v_add_f32_e32 v128, v115, v114
	v_cvt_pk_bf16_f32 v114, v118, v119
	v_cvt_pk_bf16_f32 v115, v120, v121
	v_cvt_pk_bf16_f32 v116, v122, v123
	v_cvt_pk_bf16_f32 v117, v124, v125
	global_store_dwordx4 v[126:127], v[114:117], off offset:256
	ds_bpermute_b32 v114, v191, v128
	s_waitcnt lgkmcnt(0)
	v_add_f32_e32 v114, v128, v114
	ds_bpermute_b32 v115, v190, v114
	s_and_saveexec_b64 s[6:7], vcc
	s_cbranch_execz .LBB0_195
	v_readlane_b32 s8, v255, 1
	v_lshlrev_b64 v[116:117], 7, v[170:171]
	v_readlane_b32 s9, v255, 2
	s_lshl_b32 s4, s54, 2
	s_waitcnt lgkmcnt(0)
	v_add_f32_e32 v114, v114, v115
	v_lshl_add_u64 v[116:117], s[8:9], 0, v[116:117]
	v_lshl_add_u64 v[116:117], s[18:19], 2, v[116:117]
	v_lshl_add_u64 v[116:117], v[116:117], 0, s[4:5]
	global_store_dword v[116:117], v114, off

; #define PG8_STAGE(bufoff, gbase, voff) do { _Pragma("unroll") for (int _i = 0; _i < 2; ++_i) \
;     __builtin_amdgcn_global_load_lds((const unsigned*)((const char*)(gbase) + (voff)[_i]), (LAS unsigned*)(lds + (bufoff) + ldsw + _i * 8192), 16, 0, 0); } while (0)
; #define PG8_WAIT_V(n) asm volatile("s_waitcnt vmcnt(" #n ")" ::: "memory")
; #define PG8_BAR __builtin_amdgcn_s_barrier()
; template <class Epi, bool SPLITA = false>
; __device__ __forceinline__ void gemm_phase(const int tid, LAS unsigned char* lds, const Gemm g, const Order& S, const Epi& E) {
;     ...
;   PG8_STAGE(PG8_SB(0, 0), cB, voffB); PG8_STAGE(PG8_SA(0, 0), cA, voffA); PG8_STAGE(PG8_SB(0, 1), cB + hstepB, voffB); PG8_STAGE(PG8_SA(0, 1), cA + hstepA, voffA);
;   if (wr == 1) PG8_BAR;
;   PG8_WAIT_V(4); PG8_BAR;
;   PG8_STAGE(PG8_SB(1, 0), cB + kstep, voffB); PG8_STAGE(PG8_SA(1, 0), cA + kstep, voffA); PG8_STAGE(PG8_SB(1, 1), cB + hstepB + kstep, voffB);
;   PG8_WAIT_V(6); PG8_BAR;
.LBB0_228:
	v_lshl_add_u64 v[2:3], s[40:41], 0, v[0:1]
	v_mov_b32_e32 v213, v1
	v_bfe_u32 v195, v210, 4, 2
	s_lshl_b32 s6, s1, 6
	s_lshl_b32 s0, s0, 5
	v_lshl_add_u64 v[4:5], s[40:41], 0, v[212:213]
	v_mov_b32_e32 v217, v1
	v_and_b32_e32 v196, 15, v210
	v_writelane_b32 v255, s6, 36
	v_lshlrev_b32_e32 v10, 4, v195
	v_lshlrev_b32_e32 v11, 2, v210
	s_and_b32 s0, s0, 0x60
	s_add_i32 m0, s51, 0x18000
	v_lshl_add_u64 v[2:3], v[2:3], 0, s[96:97]
	v_lshl_add_u64 v[6:7], s[14:15], 0, v[216:217]
	v_mov_b32_e32 v215, v1
	s_and_b32 s3, 0xffff, s3
	v_lshl_or_b32 v10, v196, 6, v10
	s_lshl_b32 s1, s1, 13
	v_and_b32_e32 v11, 32, v11
	v_writelane_b32 v255, s0, 38
	s_lshl_b32 s0, s0, 7
	s_waitcnt vmcnt(4)
	s_barrier
	global_load_lds_dwordx4 v[2:3], off
	v_lshl_add_u64 v[2:3], v[4:5], 0, s[96:97]
	s_add_i32 m0, s51, 0x1a000
	s_add_i32 s47, s51, 0x8000
	s_add_i32 s38, s51, 0xa000
	v_lshl_add_u64 v[8:9], s[14:15], 0, v[214:215]
	v_bitop3_b32 v209, s0, v10, v11 bitop3:0xf6
	global_load_lds_dwordx4 v[2:3], off
	v_lshl_add_u64 v[2:3], v[6:7], 0, s[96:97]
	s_mov_b32 m0, s47
	s_add_u32 s0, s40, 0x80080
	v_bitop3_b32 v12, v10, s1, v11 bitop3:0xde
	global_load_lds_dwordx4 v[2:3], off
	v_lshl_add_u64 v[2:3], v[8:9], 0, s[96:97]
	s_mov_b32 m0, s38
	s_addc_u32 s1, s41, 0
	global_load_lds_dwordx4 v[2:3], off
	s_add_i32 m0, s51, 0x1c000
	s_nop 0
	global_load_lds_dwordx4 v0, s[0:1]
	v_lshl_add_u64 v[2:3], s[0:1], 0, v[212:213]
	s_add_i32 m0, s51, 0x1e000
	s_ashr_i32 s0, s92, 31
	global_load_lds_dwordx4 v[2:3], off
	s_waitcnt vmcnt(6)
	v_writelane_b32 v255, s0, 40
	s_mov_b32 s39, 0
	v_add_u32_e32 v211, 0, v12
	s_mov_b64 s[0:1], s[4:5]
	s_barrier
	s_branch .LBB0_230

; #define PG8_STAGE(bufoff, gbase, voff) do { _Pragma("unroll") for (int _i = 0; _i < 2; ++_i) \
;     __builtin_amdgcn_global_load_lds((const unsigned*)((const char*)(gbase) + (voff)[_i]), (LAS unsigned*)(lds + (bufoff) + ldsw + _i * 8192), 16, 0, 0); } while (0)
; #define PG8_LDA(dst, b, h) do { _Pragma("unroll") for (int m = 0; m < 4; ++m) _Pragma("unroll") for (int k = 0; k < 2; ++k) dst[m][k] = *(const LAS bf16x8*)(lds + PG8_SA(b, h) + aoff + m * 2048 + k * 1024); } while (0)
; #define PG8_WAIT_V(n) asm volatile("s_waitcnt vmcnt(" #n ")" ::: "memory")
; #define PG8_BAR __builtin_amdgcn_s_barrier()
; template <class Epi, bool SPLITA = false>
; __device__ __forceinline__ void gemm_phase(const int tid, LAS unsigned char* lds, const Gemm g, const Order& S, const Epi& E) {
;     ...
;   PG8_STAGE(PG8_SB(0, 0), cB, voffB); PG8_STAGE(PG8_SA(0, 0), cA, voffA); PG8_STAGE(PG8_SB(0, 1), cB + hstepB, voffB); PG8_STAGE(PG8_SA(0, 1), cA + hstepA, voffA);
;   if (wr == 1) PG8_BAR;
;   PG8_WAIT_V(4); PG8_BAR;
;   PG8_STAGE(PG8_SB(1, 0), cB + kstep, voffB); PG8_STAGE(PG8_SA(1, 0), cA + kstep, voffA); PG8_STAGE(PG8_SB(1, 1), cB + hstepB + kstep, voffB);
;   PG8_WAIT_V(6); PG8_BAR;
;   for (;;) {
;     const bool has_next = S.next(ui + 1, nxt);
;     const char* nA = has_next ? (const char*)g.A + (size_t)nxt.pm * tstepA + (size_t)nxt.pn * apn : cA; const char* nA2 = (SPLITA && has_next) ? (const char*)g.A2 + (size_t)nxt.pm * tstepA : cA2; const char* nB = has_next ? (const char*)g.Bt + (size_t)nxt.pn * tstepB : cB;
;     for (int t = 0; t < nt; t += 2) {
;       const bool last = (t == nt - 2);
;       if constexpr (SPLITA) { if (t == nt1) E.mid(acc, cur, wr, wc, fr, fq); }
;       const char* a1 = PG8_TA(t + 1);
;       const char* a2 = last ? nA : PG8_TA(t + 2); const char* b2 = last ? nB : cB + (size_t)(t + 2) * kstep;
;       const char* a3 = last ? nA + kstep : PG8_TA(t + 3); const char* b3 = b2 + kstep;
;       PG8_LDB(B0, 0, 0); PG8_SCHED; PG8_LDA(At, 0, 0); PG8_STAGE(PG8_SA(1, 1), a1 + hstepA, voffA);
;       PG8_WAIT_L(8); PG8_BAR; PG8_WAIT_L(0); PG8_MMA(0, 0, At, B0); PG8_BAR; PG8_SCHED;
;       PG8_LDB(B1, 0, 1); PG8_STAGE(PG8_SB(0, 0), b2, voffB);
;       PG8_BAR; PG8_WAIT_L(0); PG8_MMA(0, 1, At, B1); PG8_BAR;
;       PG8_LDA(At, 0, 1); PG8_STAGE(PG8_SA(0, 0), a2, voffA);
;       PG8_BAR; PG8_WAIT_L(0); PG8_MMA(1, 0, At, B0); PG8_BAR; PG8_SCHED;
.LBB0_237:
	s_add_u32 s3, s52, s40
	s_addc_u32 s4, s53, s41
	s_and_b64 s[22:23], exec, s[48:49]
	s_cselect_b32 s49, s30, s4
	s_cselect_b32 s48, s31, s3
	s_cmp_lt_u32 s2, 16
	s_cselect_b64 s[22:23], -1, 0
	s_and_b64 s[28:29], s[22:23], exec
	s_cselect_b32 s3, 0, -16
	s_add_i32 s3, s3, s2
	s_add_i32 s4, s3, 1
	s_and_b64 s[22:23], s[22:23], exec
	s_cselect_b32 s3, s15, s55
	s_cselect_b32 s20, s14, s54
	s_lshl_b64 s[22:23], s[4:5], 7
	s_add_u32 s4, s20, s22
	s_addc_u32 s20, s3, s23
	s_add_i32 s21, 0, 0x10000
	v_add_u32_e32 v142, s21, v209
	ds_read_b128 v[130:133], v142
	ds_read_b128 v[134:137], v142 offset:1024
	ds_read_b128 v[138:141], v142 offset:2048
	ds_read_b128 v[142:145], v142 offset:3072
	s_add_i32 s3, s2, 2
	s_add_u32 s22, s4, 0x40000
	s_addc_u32 s23, s20, 0
	s_add_i32 m0, s51, 0xc000
	ds_read_b128 v[146:149], v211
	ds_read_b128 v[150:153], v211 offset:1024
	ds_read_b128 v[154:157], v211 offset:2048
	ds_read_b128 v[158:161], v211 offset:3072
	ds_read_b128 v[162:165], v211 offset:4096
	ds_read_b128 v[166:169], v211 offset:5120
	ds_read_b128 v[170:173], v211 offset:6144
	ds_read_b128 v[174:177], v211 offset:7168
	global_load_lds_dwordx4 v216, s[22:23]
	v_lshl_add_u64 v[178:179], s[22:23], 0, v[214:215]
	s_add_i32 m0, s51, 0xe000
	s_nop 0
	global_load_lds_dwordx4 v214, s[22:23]
	s_waitcnt lgkmcnt(8)
	s_barrier
	s_waitcnt lgkmcnt(0)
	s_setprio 1
	s_waitcnt lgkmcnt(0)
	v_mfma_f32_16x16x32_bf16 v[126:129], v[130:133], v[146:149], v[126:129]
	v_mfma_f32_16x16x32_bf16 v[122:125], v[138:141], v[146:149], v[122:125]
	v_mfma_f32_16x16x32_bf16 v[110:113], v[130:133], v[154:157], v[110:113]
	v_mfma_f32_16x16x32_bf16 v[106:109], v[138:141], v[154:157], v[106:109]
	v_mfma_f32_16x16x32_bf16 v[94:97], v[130:133], v[162:165], v[94:97]
	v_mfma_f32_16x16x32_bf16 v[90:93], v[138:141], v[162:165], v[90:93]
	v_mfma_f32_16x16x32_bf16 v[78:81], v[130:133], v[170:173], v[78:81]
	v_mfma_f32_16x16x32_bf16 v[74:77], v[138:141], v[170:173], v[74:77]
	v_mfma_f32_16x16x32_bf16 v[126:129], v[134:137], v[150:153], v[126:129]
	v_mfma_f32_16x16x32_bf16 v[122:125], v[142:145], v[150:153], v[122:125]
	v_mfma_f32_16x16x32_bf16 v[110:113], v[134:137], v[158:161], v[110:113]
	v_mfma_f32_16x16x32_bf16 v[106:109], v[142:145], v[158:161], v[106:109]
	v_mfma_f32_16x16x32_bf16 v[94:97], v[134:137], v[166:169], v[94:97]
	v_mfma_f32_16x16x32_bf16 v[90:93], v[142:145], v[166:169], v[90:93]
	v_mfma_f32_16x16x32_bf16 v[78:81], v[134:137], v[174:177], v[78:81]
	v_mfma_f32_16x16x32_bf16 v[74:77], v[142:145], v[174:177], v[74:77]
	s_setprio 0
	s_barrier
	s_add_i32 s4, 0, 0x14000
	s_add_i32 s20, s21, s93
	v_add_u32_e32 v190, s4, v209
	v_lshl_add_u64 v[198:199], s[48:49], 0, v[0:1]
	s_mov_b32 m0, s20
	ds_read_b128 v[178:181], v190
	ds_read_b128 v[182:185], v190 offset:1024
	ds_read_b128 v[186:189], v190 offset:2048
	ds_read_b128 v[190:193], v190 offset:3072
	global_load_lds_dwordx4 v0, s[48:49]
	v_lshl_add_u64 v[200:201], s[48:49], 0, v[212:213]
	s_add_i32 m0, s20, 0x2000
	s_nop 0
	global_load_lds_dwordx4 v212, s[48:49]
	s_barrier
	s_waitcnt lgkmcnt(0)
	s_setprio 1
	s_waitcnt lgkmcnt(0)
	v_mfma_f32_16x16x32_bf16 v[118:121], v[178:181], v[146:149], v[118:121]
	v_mfma_f32_16x16x32_bf16 v[114:117], v[186:189], v[146:149], v[114:117]
	v_mfma_f32_16x16x32_bf16 v[102:105], v[178:181], v[154:157], v[102:105]
	v_mfma_f32_16x16x32_bf16 v[98:101], v[186:189], v[154:157], v[98:101]
	v_mfma_f32_16x16x32_bf16 v[86:89], v[178:181], v[162:165], v[86:89]
	v_mfma_f32_16x16x32_bf16 v[82:85], v[186:189], v[162:165], v[82:85]
	v_mfma_f32_16x16x32_bf16 v[70:73], v[178:181], v[170:173], v[70:73]
	v_mfma_f32_16x16x32_bf16 v[66:69], v[186:189], v[170:173], v[66:69]
	v_mfma_f32_16x16x32_bf16 v[118:121], v[182:185], v[150:153], v[118:121]
	v_mfma_f32_16x16x32_bf16 v[114:117], v[190:193], v[150:153], v[114:117]
	v_mfma_f32_16x16x32_bf16 v[102:105], v[182:185], v[158:161], v[102:105]
	v_mfma_f32_16x16x32_bf16 v[98:101], v[190:193], v[158:161], v[98:101]
	v_mfma_f32_16x16x32_bf16 v[86:89], v[182:185], v[166:169], v[86:89]
	v_mfma_f32_16x16x32_bf16 v[82:85], v[190:193], v[166:169], v[82:85]
	v_mfma_f32_16x16x32_bf16 v[70:73], v[182:185], v[174:177], v[70:73]
	v_mfma_f32_16x16x32_bf16 v[66:69], v[190:193], v[174:177], v[66:69]
	s_setprio 0
	s_mov_b32 m0, s51
	s_barrier
	ds_read_b128 v[146:149], v211 offset:16384
	ds_read_b128 v[150:153], v211 offset:17408
	ds_read_b128 v[154:157], v211 offset:18432
	ds_read_b128 v[158:161], v211 offset:19456
	ds_read_b128 v[162:165], v211 offset:20480
	ds_read_b128 v[166:169], v211 offset:21504
	ds_read_b128 v[170:173], v211 offset:22528
	ds_read_b128 v[174:177], v211 offset:23552
	global_load_lds_dwordx4 v216, s[90:91]
	s_mov_b32 m0, s44
	s_nop 0
	global_load_lds_dwordx4 v214, s[90:91]
	s_barrier
	s_waitcnt lgkmcnt(0)
	s_setprio 1
	s_waitcnt lgkmcnt(0)
	v_mfma_f32_16x16x32_bf16 v[62:65], v[130:133], v[146:149], v[62:65]
	v_mfma_f32_16x16x32_bf16 v[58:61], v[138:141], v[146:149], v[58:61]
	v_mfma_f32_16x16x32_bf16 v[46:49], v[130:133], v[154:157], v[46:49]
	v_mfma_f32_16x16x32_bf16 v[42:45], v[138:141], v[154:157], v[42:45]
	v_mfma_f32_16x16x32_bf16 v[30:33], v[130:133], v[162:165], v[30:33]
	v_mfma_f32_16x16x32_bf16 v[26:29], v[138:141], v[162:165], v[26:29]
	v_mfma_f32_16x16x32_bf16 v[14:17], v[130:133], v[170:173], v[14:17]
	v_mfma_f32_16x16x32_bf16 v[10:13], v[138:141], v[170:173], v[10:13]
	v_mfma_f32_16x16x32_bf16 v[62:65], v[134:137], v[150:153], v[62:65]
	v_mfma_f32_16x16x32_bf16 v[58:61], v[142:145], v[150:153], v[58:61]
	v_mfma_f32_16x16x32_bf16 v[46:49], v[134:137], v[158:161], v[46:49]
	v_mfma_f32_16x16x32_bf16 v[42:45], v[142:145], v[158:161], v[42:45]
	v_mfma_f32_16x16x32_bf16 v[30:33], v[134:137], v[166:169], v[30:33]
	v_mfma_f32_16x16x32_bf16 v[26:29], v[142:145], v[166:169], v[26:29]
	v_mfma_f32_16x16x32_bf16 v[14:17], v[134:137], v[174:177], v[14:17]
	v_mfma_f32_16x16x32_bf16 v[10:13], v[142:145], v[174:177], v[10:13]
	s_setprio 0
	s_barrier
; #define PG8_STAGE(bufoff, gbase, voff) do { _Pragma("unroll") for (int _i = 0; _i < 2; ++_i) \
;     __builtin_amdgcn_global_load_lds((const unsigned*)((const char*)(gbase) + (voff)[_i]), (LAS unsigned*)(lds + (bufoff) + ldsw + _i * 8192), 16, 0, 0); } while (0)
; #define PG8_LDA(dst, b, h) do { _Pragma("unroll") for (int m = 0; m < 4; ++m) _Pragma("unroll") for (int k = 0; k < 2; ++k) dst[m][k] = *(const LAS bf16x8*)(lds + PG8_SA(b, h) + aoff + m * 2048 + k * 1024); } while (0)
; #define PG8_LDB(dst, b, h) do { _Pragma("unroll") for (int n = 0; n < 2; ++n) _Pragma("unroll") for (int k = 0; k < 2; ++k) dst[n][k] = *(const LAS bf16x8*)(lds + PG8_SB(b, h) + boff + n * 2048 + k * 1024); } while (0)
; #define PG8_MMA(ai, bj, At, Bt) do { __builtin_amdgcn_s_setprio(1); _Pragma("unroll") for (int m = 0; m < 4; ++m) _Pragma("unroll") for (int n = 0; n < 2; ++n) _Pragma("unroll") for (int k = 0; k < 2; ++k) \
;     acc[ai][bj][m][n] = __builtin_amdgcn_mfma_f32_16x16x32_bf16(Bt[n][k], At[m][k], acc[ai][bj][m][n], 0, 0, 0); __builtin_amdgcn_s_setprio(0); } while (0)
; #define PG8_WAIT_V(n) asm volatile("s_waitcnt vmcnt(" #n ")" ::: "memory")
; #define PG8_WAIT_L(n) asm volatile("s_waitcnt lgkmcnt(" #n ")" ::: "memory")
; #define PG8_BAR __builtin_amdgcn_s_barrier()
; #define PG8_SCHED __builtin_amdgcn_sched_barrier(0)
; template <class Epi, bool SPLITA = false>
; __device__ __forceinline__ void gemm_phase(const int tid, LAS unsigned char* lds, const Gemm g, const Order& S, const Epi& E) {
;     ...
;       PG8_BAR; PG8_WAIT_L(0); PG8_MMA(1, 0, At, B0); PG8_BAR; PG8_SCHED;
;       PG8_STAGE(PG8_SB(0, 1), b2 + hstepB, voffB);
;       PG8_WAIT_V(6); PG8_BAR; PG8_MMA(1, 1, At, B1); PG8_BAR;
;       PG8_LDB(B0, 1, 0); PG8_SCHED; PG8_LDA(At, 1, 0); PG8_STAGE(PG8_SA(0, 1), a2 + hstepA, voffA);
;       PG8_WAIT_L(8); PG8_BAR; PG8_WAIT_L(0); PG8_MMA(0, 0, At, B0); PG8_BAR; PG8_SCHED;
;       PG8_LDB(B1, 1, 1); PG8_STAGE(PG8_SB(1, 0), b3, voffB);
;       PG8_BAR; PG8_WAIT_L(0); PG8_MMA(0, 1, At, B1); PG8_BAR;
;       PG8_LDA(At, 1, 1); PG8_STAGE(PG8_SA(1, 0), a3, voffA);
;       PG8_BAR; PG8_WAIT_L(0); PG8_MMA(1, 0, At, B0); PG8_BAR; PG8_SCHED;
	s_add_u32 s22, s48, 0x80000
	s_addc_u32 s23, s49, 0
	s_add_i32 s4, s4, s93
	s_mov_b32 m0, s4
	s_nop 0
	global_load_lds_dwordx4 v0, s[22:23]
	v_lshl_add_u64 v[130:131], s[22:23], 0, v[212:213]
	s_add_i32 m0, s4, 0x2000
	s_nop 0
	global_load_lds_dwordx4 v212, s[22:23]
	s_waitcnt vmcnt(6)
	s_barrier
	s_setprio 1
	v_mfma_f32_16x16x32_bf16 v[54:57], v[178:181], v[146:149], v[54:57]
	v_mfma_f32_16x16x32_bf16 v[50:53], v[186:189], v[146:149], v[50:53]
	v_mfma_f32_16x16x32_bf16 v[38:41], v[178:181], v[154:157], v[38:41]
	v_mfma_f32_16x16x32_bf16 v[34:37], v[186:189], v[154:157], v[34:37]
	v_mfma_f32_16x16x32_bf16 v[22:25], v[178:181], v[162:165], v[22:25]
	v_mfma_f32_16x16x32_bf16 v[18:21], v[186:189], v[162:165], v[18:21]
	v_mfma_f32_16x16x32_bf16 v[6:9], v[178:181], v[170:173], v[6:9]
	v_mfma_f32_16x16x32_bf16 v[2:5], v[186:189], v[170:173], v[2:5]
	v_mfma_f32_16x16x32_bf16 v[54:57], v[182:185], v[150:153], v[54:57]
	v_mfma_f32_16x16x32_bf16 v[50:53], v[190:193], v[150:153], v[50:53]
	v_mfma_f32_16x16x32_bf16 v[38:41], v[182:185], v[158:161], v[38:41]
	v_mfma_f32_16x16x32_bf16 v[34:37], v[190:193], v[158:161], v[34:37]
	v_mfma_f32_16x16x32_bf16 v[22:25], v[182:185], v[166:169], v[22:25]
	v_mfma_f32_16x16x32_bf16 v[18:21], v[190:193], v[166:169], v[18:21]
	v_mfma_f32_16x16x32_bf16 v[6:9], v[182:185], v[174:177], v[6:9]
	v_mfma_f32_16x16x32_bf16 v[2:5], v[190:193], v[174:177], v[2:5]
	s_setprio 0
	s_add_i32 s4, 0, 0x18000
	v_add_u32_e32 v142, s4, v209
	s_barrier
	ds_read_b128 v[130:133], v142
	ds_read_b128 v[134:137], v142 offset:1024
	ds_read_b128 v[138:141], v142 offset:2048
	ds_read_b128 v[142:145], v142 offset:3072
	s_add_u32 s22, s90, 0x40000
	s_addc_u32 s23, s91, 0
	s_mov_b32 m0, s45
	ds_read_b128 v[146:149], v211 offset:32768
	ds_read_b128 v[150:153], v211 offset:33792
	ds_read_b128 v[154:157], v211 offset:34816
	ds_read_b128 v[158:161], v211 offset:35840
	ds_read_b128 v[162:165], v211 offset:36864
	ds_read_b128 v[166:169], v211 offset:37888
	ds_read_b128 v[170:173], v211 offset:38912
	ds_read_b128 v[174:177], v211 offset:39936
	global_load_lds_dwordx4 v216, s[22:23]
	v_lshl_add_u64 v[178:179], s[22:23], 0, v[214:215]
	s_mov_b32 m0, s46
	s_nop 0
	global_load_lds_dwordx4 v214, s[22:23]
	s_waitcnt lgkmcnt(8)
	s_barrier
	s_waitcnt lgkmcnt(0)
	s_setprio 1
	s_waitcnt lgkmcnt(0)
	v_mfma_f32_16x16x32_bf16 v[126:129], v[130:133], v[146:149], v[126:129]
	v_mfma_f32_16x16x32_bf16 v[122:125], v[138:141], v[146:149], v[122:125]
	v_mfma_f32_16x16x32_bf16 v[110:113], v[130:133], v[154:157], v[110:113]
	v_mfma_f32_16x16x32_bf16 v[106:109], v[138:141], v[154:157], v[106:109]
	v_mfma_f32_16x16x32_bf16 v[94:97], v[130:133], v[162:165], v[94:97]
	v_mfma_f32_16x16x32_bf16 v[90:93], v[138:141], v[162:165], v[90:93]
	v_mfma_f32_16x16x32_bf16 v[78:81], v[130:133], v[170:173], v[78:81]
	v_mfma_f32_16x16x32_bf16 v[74:77], v[138:141], v[170:173], v[74:77]
	v_mfma_f32_16x16x32_bf16 v[126:129], v[134:137], v[150:153], v[126:129]
	v_mfma_f32_16x16x32_bf16 v[122:125], v[142:145], v[150:153], v[122:125]
	v_mfma_f32_16x16x32_bf16 v[110:113], v[134:137], v[158:161], v[110:113]
	v_mfma_f32_16x16x32_bf16 v[106:109], v[142:145], v[158:161], v[106:109]
	v_mfma_f32_16x16x32_bf16 v[94:97], v[134:137], v[166:169], v[94:97]
	v_mfma_f32_16x16x32_bf16 v[90:93], v[142:145], v[166:169], v[90:93]
	v_mfma_f32_16x16x32_bf16 v[78:81], v[134:137], v[174:177], v[78:81]
	v_mfma_f32_16x16x32_bf16 v[74:77], v[142:145], v[174:177], v[74:77]
	s_setprio 0
	s_barrier
	s_add_i32 s20, 0, 0x1c000
	s_add_i32 s4, s4, s93
	v_add_u32_e32 v190, s20, v209
	v_lshl_add_u64 v[198:199], v[198:199], 0, s[96:97]
	s_mov_b32 m0, s4
	ds_read_b128 v[178:181], v190
	ds_read_b128 v[182:185], v190 offset:1024
	ds_read_b128 v[186:189], v190 offset:2048
	ds_read_b128 v[190:193], v190 offset:3072
	global_load_lds_dwordx4 v[198:199], off
	v_lshl_add_u64 v[198:199], v[200:201], 0, s[96:97]
	s_add_i32 m0, s4, 0x2000
	s_nop 0
	global_load_lds_dwordx4 v[198:199], off
	s_barrier
; #define PG8_STAGE(bufoff, gbase, voff) do { _Pragma("unroll") for (int _i = 0; _i < 2; ++_i) \
;     __builtin_amdgcn_global_load_lds((const unsigned*)((const char*)(gbase) + (voff)[_i]), (LAS unsigned*)(lds + (bufoff) + ldsw + _i * 8192), 16, 0, 0); } while (0)
; #define PG8_LDA(dst, b, h) do { _Pragma("unroll") for (int m = 0; m < 4; ++m) _Pragma("unroll") for (int k = 0; k < 2; ++k) dst[m][k] = *(const LAS bf16x8*)(lds + PG8_SA(b, h) + aoff + m * 2048 + k * 1024); } while (0)
; #define PG8_LDB(dst, b, h) do { _Pragma("unroll") for (int n = 0; n < 2; ++n) _Pragma("unroll") for (int k = 0; k < 2; ++k) dst[n][k] = *(const LAS bf16x8*)(lds + PG8_SB(b, h) + boff + n * 2048 + k * 1024); } while (0)
; #define PG8_MMA(ai, bj, At, Bt) do { __builtin_amdgcn_s_setprio(1); _Pragma("unroll") for (int m = 0; m < 4; ++m) _Pragma("unroll") for (int n = 0; n < 2; ++n) _Pragma("unroll") for (int k = 0; k < 2; ++k) \
;     acc[ai][bj][m][n] = __builtin_amdgcn_mfma_f32_16x16x32_bf16(Bt[n][k], At[m][k], acc[ai][bj][m][n], 0, 0, 0); __builtin_amdgcn_s_setprio(0); } while (0)
; #define PG8_WAIT_V(n) asm volatile("s_waitcnt vmcnt(" #n ")" ::: "memory")
; #define PG8_WAIT_L(n) asm volatile("s_waitcnt lgkmcnt(" #n ")" ::: "memory")
; #define PG8_BAR __builtin_amdgcn_s_barrier()
; #define PG8_SCHED __builtin_amdgcn_sched_barrier(0)
; template <class Epi, bool SPLITA = false>
; __device__ __forceinline__ void gemm_phase(const int tid, LAS unsigned char* lds, const Gemm g, const Order& S, const Epi& E) {
;     ...
;       PG8_LDB(B1, 1, 1); PG8_STAGE(PG8_SB(1, 0), b3, voffB);
;       PG8_BAR; PG8_WAIT_L(0); PG8_MMA(0, 1, At, B1); PG8_BAR;
;       PG8_LDA(At, 1, 1); PG8_STAGE(PG8_SA(1, 0), a3, voffA);
;       PG8_BAR; PG8_WAIT_L(0); PG8_MMA(1, 0, At, B0); PG8_BAR; PG8_SCHED;
;       PG8_STAGE(PG8_SB(1, 1), b3 + hstepB, voffB);
;       PG8_WAIT_V(6); PG8_BAR; PG8_MMA(1, 1, At, B1); PG8_BAR;
;     }
	s_waitcnt lgkmcnt(0)
	s_setprio 1
	s_waitcnt lgkmcnt(0)
	v_mfma_f32_16x16x32_bf16 v[118:121], v[178:181], v[146:149], v[118:121]
	v_mfma_f32_16x16x32_bf16 v[114:117], v[186:189], v[146:149], v[114:117]
	v_mfma_f32_16x16x32_bf16 v[102:105], v[178:181], v[154:157], v[102:105]
	v_mfma_f32_16x16x32_bf16 v[98:101], v[186:189], v[154:157], v[98:101]
	v_mfma_f32_16x16x32_bf16 v[86:89], v[178:181], v[162:165], v[86:89]
	v_mfma_f32_16x16x32_bf16 v[82:85], v[186:189], v[162:165], v[82:85]
	v_mfma_f32_16x16x32_bf16 v[70:73], v[178:181], v[170:173], v[70:73]
	v_mfma_f32_16x16x32_bf16 v[66:69], v[186:189], v[170:173], v[66:69]
	v_mfma_f32_16x16x32_bf16 v[118:121], v[182:185], v[150:153], v[118:121]
	v_mfma_f32_16x16x32_bf16 v[114:117], v[190:193], v[150:153], v[114:117]
	v_mfma_f32_16x16x32_bf16 v[102:105], v[182:185], v[158:161], v[102:105]
	v_mfma_f32_16x16x32_bf16 v[98:101], v[190:193], v[158:161], v[98:101]
	v_mfma_f32_16x16x32_bf16 v[86:89], v[182:185], v[166:169], v[86:89]
	v_mfma_f32_16x16x32_bf16 v[82:85], v[190:193], v[166:169], v[82:85]
	v_mfma_f32_16x16x32_bf16 v[70:73], v[182:185], v[174:177], v[70:73]
	v_mfma_f32_16x16x32_bf16 v[66:69], v[190:193], v[174:177], v[66:69]
	s_setprio 0
	s_mov_b32 m0, s47
	s_barrier
	ds_read_b128 v[146:149], v211 offset:49152
	ds_read_b128 v[150:153], v211 offset:50176
	ds_read_b128 v[154:157], v211 offset:51200
	ds_read_b128 v[158:161], v211 offset:52224
	ds_read_b128 v[162:165], v211 offset:53248
	ds_read_b128 v[166:169], v211 offset:54272
	ds_read_b128 v[170:173], v211 offset:55296
	ds_read_b128 v[174:177], v211 offset:56320
	global_load_lds_dwordx4 v216, s[42:43]
	s_mov_b32 m0, s38
	s_nop 0
	global_load_lds_dwordx4 v214, s[42:43]
	s_barrier
	s_waitcnt lgkmcnt(0)
	s_setprio 1
	s_waitcnt lgkmcnt(0)
	v_mfma_f32_16x16x32_bf16 v[62:65], v[130:133], v[146:149], v[62:65]
	v_mfma_f32_16x16x32_bf16 v[58:61], v[138:141], v[146:149], v[58:61]
	v_mfma_f32_16x16x32_bf16 v[46:49], v[130:133], v[154:157], v[46:49]
	v_mfma_f32_16x16x32_bf16 v[42:45], v[138:141], v[154:157], v[42:45]
	v_mfma_f32_16x16x32_bf16 v[30:33], v[130:133], v[162:165], v[30:33]
	v_mfma_f32_16x16x32_bf16 v[26:29], v[138:141], v[162:165], v[26:29]
	v_mfma_f32_16x16x32_bf16 v[14:17], v[130:133], v[170:173], v[14:17]
	v_mfma_f32_16x16x32_bf16 v[10:13], v[138:141], v[170:173], v[10:13]
	v_mfma_f32_16x16x32_bf16 v[62:65], v[134:137], v[150:153], v[62:65]
	v_mfma_f32_16x16x32_bf16 v[58:61], v[142:145], v[150:153], v[58:61]
	v_mfma_f32_16x16x32_bf16 v[46:49], v[134:137], v[158:161], v[46:49]
	v_mfma_f32_16x16x32_bf16 v[42:45], v[142:145], v[158:161], v[42:45]
	v_mfma_f32_16x16x32_bf16 v[30:33], v[134:137], v[166:169], v[30:33]
	v_mfma_f32_16x16x32_bf16 v[26:29], v[142:145], v[166:169], v[26:29]
	v_mfma_f32_16x16x32_bf16 v[14:17], v[134:137], v[174:177], v[14:17]
	v_mfma_f32_16x16x32_bf16 v[10:13], v[142:145], v[174:177], v[10:13]
	s_setprio 0
	s_barrier
	s_add_u32 s22, s48, 0x80080
	s_addc_u32 s23, s49, 0
	s_add_i32 s4, s20, s93
	s_mov_b32 m0, s4
	s_nop 0
	global_load_lds_dwordx4 v0, s[22:23]
	s_add_i32 m0, s4, 0x2000
	s_nop 0
	global_load_lds_dwordx4 v212, s[22:23]
	s_waitcnt vmcnt(6)
	s_barrier
	s_setprio 1
	v_mfma_f32_16x16x32_bf16 v[54:57], v[178:181], v[146:149], v[54:57]
	v_mfma_f32_16x16x32_bf16 v[50:53], v[186:189], v[146:149], v[50:53]
	v_mfma_f32_16x16x32_bf16 v[38:41], v[178:181], v[154:157], v[38:41]
	v_mfma_f32_16x16x32_bf16 v[34:37], v[186:189], v[154:157], v[34:37]
	v_mfma_f32_16x16x32_bf16 v[22:25], v[178:181], v[162:165], v[22:25]
	v_mfma_f32_16x16x32_bf16 v[18:21], v[186:189], v[162:165], v[18:21]
	v_mfma_f32_16x16x32_bf16 v[6:9], v[178:181], v[170:173], v[6:9]
	v_mfma_f32_16x16x32_bf16 v[2:5], v[186:189], v[170:173], v[2:5]
	v_mfma_f32_16x16x32_bf16 v[54:57], v[182:185], v[150:153], v[54:57]
	v_mfma_f32_16x16x32_bf16 v[50:53], v[190:193], v[150:153], v[50:53]
	v_mfma_f32_16x16x32_bf16 v[38:41], v[182:185], v[158:161], v[38:41]
	v_mfma_f32_16x16x32_bf16 v[34:37], v[190:193], v[158:161], v[34:37]
	v_mfma_f32_16x16x32_bf16 v[22:25], v[182:185], v[166:169], v[22:25]
	v_mfma_f32_16x16x32_bf16 v[18:21], v[190:193], v[166:169], v[18:21]
	v_mfma_f32_16x16x32_bf16 v[6:9], v[182:185], v[174:177], v[6:9]
	v_mfma_f32_16x16x32_bf16 v[2:5], v[190:193], v[174:177], v[2:5]
	s_setprio 0
	s_add_u32 s40, s40, 0x100
	s_addc_u32 s41, s41, 0
	v_readlane_b32 s90, v255, 31
	s_cmp_gt_u32 s2, 29
	s_mov_b32 s2, s3
	v_readlane_b32 s91, v255, 32
	s_barrier
	s_cbranch_scc1 .LBB0_229

; #define PG8_STAGE(bufoff, gbase, voff) do { _Pragma("unroll") for (int _i = 0; _i < 2; ++_i) \
;     __builtin_amdgcn_global_load_lds((const unsigned*)((const char*)(gbase) + (voff)[_i]), (LAS unsigned*)(lds + (bufoff) + ldsw + _i * 8192), 16, 0, 0); } while (0)
; #define PG8_WAIT_V(n) asm volatile("s_waitcnt vmcnt(" #n ")" ::: "memory")
; #define PG8_BAR __builtin_amdgcn_s_barrier()
; template <class Epi, bool SPLITA = false>
; __device__ __forceinline__ void gemm_phase(const int tid, LAS unsigned char* lds, const Gemm g, const Order& S, const Epi& E) {
;     ...
;   PG8_STAGE(PG8_SB(0, 0), cB, voffB); PG8_STAGE(PG8_SA(0, 0), cA, voffA); PG8_STAGE(PG8_SB(0, 1), cB + hstepB, voffB); PG8_STAGE(PG8_SA(0, 1), cA + hstepA, voffA);
;   if (wr == 1) PG8_BAR;
;   PG8_WAIT_V(4); PG8_BAR;
;   PG8_STAGE(PG8_SB(1, 0), cB + kstep, voffB); PG8_STAGE(PG8_SA(1, 0), cA + kstep, voffA); PG8_STAGE(PG8_SB(1, 1), cB + hstepB + kstep, voffB);
;   PG8_WAIT_V(6); PG8_BAR;
.LBB0_319:
	v_bfe_u32 v144, v210, 4, 2
	v_and_b32_e32 v145, 15, v210
	v_lshlrev_b32_e32 v18, 4, v144
	v_lshlrev_b32_e32 v19, 2, v210
	s_lshl_b32 s44, s0, 6
	v_lshl_or_b32 v18, v145, 6, v18
	s_lshl_b32 s0, s0, 13
	v_and_b32_e32 v19, 32, v19
	v_bitop3_b32 v20, v18, s0, v19 bitop3:0xde
	s_lshl_b32 s0, s1, 5
	s_and_b32 s45, s0, 0x60
	s_add_i32 m0, s30, 0x18000
	v_lshl_add_u64 v[8:9], v[8:9], 0, s[96:97]
	s_lshl_b32 s0, s45, 7
	s_waitcnt vmcnt(4)
	s_barrier
	global_load_lds_dwordx4 v[8:9], off
	v_lshl_add_u64 v[6:7], v[6:7], 0, s[96:97]
	s_add_i32 m0, s30, 0x1a000
	s_add_i32 s46, s30, 0x8000
	s_add_i32 s47, s30, 0xa000
	v_bitop3_b32 v146, s0, v18, v19 bitop3:0xf6
	global_load_lds_dwordx4 v[6:7], off
	v_lshl_add_u64 v[4:5], v[4:5], 0, s[96:97]
	s_mov_b32 m0, s46
	s_add_u32 s0, s10, 0x88080
	global_load_lds_dwordx4 v[4:5], off
	v_lshl_add_u64 v[2:3], v[2:3], 0, s[96:97]
	s_mov_b32 m0, s47
	s_addc_u32 s1, s11, 0
	global_load_lds_dwordx4 v[2:3], off
	s_add_i32 m0, s30, 0x1c000
	s_nop 0
	global_load_lds_dwordx4 v0, s[0:1]
	v_lshl_add_u64 v[2:3], s[0:1], 0, v[134:135]
	s_add_i32 m0, s30, 0x1e000
	s_movk_i32 s6, 0x880
	global_load_lds_dwordx4 v134, s[0:1]
	v_lshrrev_b32_e32 v3, 1, v10
	v_mul_lo_u32 v2, v12, s6
	s_mov_b32 s7, 0x8800
	v_mad_u64_u32 v[2:3], s[0:1], v3, s7, v[2:3]
	v_or_b32_e32 v2, v2, v11
	v_add_lshl_u32 v136, v2, v13, 1
	v_lshrrev_b32_e32 v3, 1, v14
	v_mul_lo_u32 v2, v16, s6
	s_waitcnt vmcnt(6)
	v_mad_u64_u32 v[2:3], s[0:1], v3, s7, v[2:3]
	v_or_b32_e32 v2, v2, v15
	s_ashr_i32 s48, s92, 31
	v_mov_b32_e32 v137, v1
	v_add_lshl_u32 v138, v2, v17, 1
	v_mov_b32_e32 v139, v1
	s_mov_b32 s49, 0
	v_add_u32_e32 v147, 0, v20
	s_barrier
	s_waitcnt vmcnt(0)
	s_branch .LBB0_321

; #define PG8_STAGE(bufoff, gbase, voff) do { _Pragma("unroll") for (int _i = 0; _i < 2; ++_i) \
;     __builtin_amdgcn_global_load_lds((const unsigned*)((const char*)(gbase) + (voff)[_i]), (LAS unsigned*)(lds + (bufoff) + ldsw + _i * 8192), 16, 0, 0); } while (0)
; #define PG8_LDA(dst, b, h) do { _Pragma("unroll") for (int m = 0; m < 4; ++m) _Pragma("unroll") for (int k = 0; k < 2; ++k) dst[m][k] = *(const LAS bf16x8*)(lds + PG8_SA(b, h) + aoff + m * 2048 + k * 1024); } while (0)
; #define PG8_LDB(dst, b, h) do { _Pragma("unroll") for (int n = 0; n < 2; ++n) _Pragma("unroll") for (int k = 0; k < 2; ++k) dst[n][k] = *(const LAS bf16x8*)(lds + PG8_SB(b, h) + boff + n * 2048 + k * 1024); } while (0)
; #define PG8_MMA(ai, bj, At, Bt) do { __builtin_amdgcn_s_setprio(1); _Pragma("unroll") for (int m = 0; m < 4; ++m) _Pragma("unroll") for (int n = 0; n < 2; ++n) _Pragma("unroll") for (int k = 0; k < 2; ++k) \
;     acc[ai][bj][m][n] = __builtin_amdgcn_mfma_f32_16x16x32_bf16(Bt[n][k], At[m][k], acc[ai][bj][m][n], 0, 0, 0); __builtin_amdgcn_s_setprio(0); } while (0)
; #define PG8_WAIT_L(n) asm volatile("s_waitcnt lgkmcnt(" #n ")" ::: "memory")
; #define PG8_BAR __builtin_amdgcn_s_barrier()
; #define PG8_SCHED __builtin_amdgcn_sched_barrier(0)
; template <class Epi, bool SPLITA = false>
; __device__ __forceinline__ void gemm_phase(const int tid, LAS unsigned char* lds, const Gemm g, const Order& S, const Epi& E) {
;     ...
;     for (int t = 0; t < nt; t += 2) {
;       const bool last = (t == nt - 2);
;       if constexpr (SPLITA) { if (t == nt1) E.mid(acc, cur, wr, wc, fr, fq); }
;       const char* a1 = PG8_TA(t + 1);
;       const char* a2 = last ? nA : PG8_TA(t + 2); const char* b2 = last ? nB : cB + (size_t)(t + 2) * kstep;
;       const char* a3 = last ? nA + kstep : PG8_TA(t + 3); const char* b3 = b2 + kstep;
;       PG8_LDB(B0, 0, 0); PG8_SCHED; PG8_LDA(At, 0, 0); PG8_STAGE(PG8_SA(1, 1), a1 + hstepA, voffA);
;       PG8_WAIT_L(8); PG8_BAR; PG8_WAIT_L(0); PG8_MMA(0, 0, At, B0); PG8_BAR; PG8_SCHED;
;       PG8_LDB(B1, 0, 1); PG8_STAGE(PG8_SB(0, 0), b2, voffB);
;       PG8_BAR; PG8_WAIT_L(0); PG8_MMA(0, 1, At, B1); PG8_BAR;
;       PG8_LDA(At, 0, 1); PG8_STAGE(PG8_SA(0, 0), a2, voffA);
;       PG8_BAR; PG8_WAIT_L(0); PG8_MMA(1, 0, At, B0); PG8_BAR; PG8_SCHED;
.LBB0_328:
	s_add_u32 s12, s8, s10
	s_addc_u32 s13, s9, s11
	s_add_u32 s16, s12, 0x100
	s_addc_u32 s17, s13, 0
	s_add_u32 s20, s55, s10
	s_addc_u32 s21, s90, s11
	s_add_u32 s12, s12, 0x180
	s_addc_u32 s13, s13, 0
	s_add_i32 s22, 0, 0x10000
	v_add_u32_e32 v160, s22, v146
	ds_read_b128 v[148:151], v160
	ds_read_b128 v[152:155], v160 offset:1024
	ds_read_b128 v[156:159], v160 offset:2048
	ds_read_b128 v[160:163], v160 offset:3072
	s_cmpk_eq_i32 s10, 0x1000
	s_cselect_b32 s15, s41, s13
	s_cselect_b32 s14, s40, s12
	s_cselect_b32 s13, s7, s21
	s_cselect_b32 s12, s6, s20
	s_cselect_b32 s17, s1, s17
	s_cselect_b32 s16, s0, s16
	v_lshl_add_u64 v[192:193], v[140:141], 0, s[10:11]
	s_add_i32 m0, s30, 0xc000
	ds_read_b128 v[164:167], v147
	ds_read_b128 v[168:171], v147 offset:1024
	ds_read_b128 v[172:175], v147 offset:2048
	ds_read_b128 v[176:179], v147 offset:3072
	ds_read_b128 v[180:183], v147 offset:4096
	ds_read_b128 v[184:187], v147 offset:5120
	ds_read_b128 v[188:191], v147 offset:6144
	ds_read_b128 v[212:215], v147 offset:7168
	global_load_lds_dwordx4 v[192:193], off
	v_lshl_add_u64 v[192:193], v[142:143], 0, s[10:11]
	s_add_i32 m0, s30, 0xe000
	s_nop 0
	global_load_lds_dwordx4 v[192:193], off
	s_waitcnt lgkmcnt(8)
	s_barrier
	s_waitcnt lgkmcnt(0)
	s_setprio 1
	s_waitcnt lgkmcnt(0)
	v_mfma_f32_16x16x32_bf16 v[126:129], v[148:151], v[164:167], v[126:129]
	v_mfma_f32_16x16x32_bf16 v[122:125], v[156:159], v[164:167], v[122:125]
	v_mfma_f32_16x16x32_bf16 v[110:113], v[148:151], v[172:175], v[110:113]
	v_mfma_f32_16x16x32_bf16 v[106:109], v[156:159], v[172:175], v[106:109]
	v_mfma_f32_16x16x32_bf16 v[94:97], v[148:151], v[180:183], v[94:97]
	v_mfma_f32_16x16x32_bf16 v[90:93], v[156:159], v[180:183], v[90:93]
	v_mfma_f32_16x16x32_bf16 v[78:81], v[148:151], v[188:191], v[78:81]
	v_mfma_f32_16x16x32_bf16 v[74:77], v[156:159], v[188:191], v[74:77]
	v_mfma_f32_16x16x32_bf16 v[126:129], v[152:155], v[168:171], v[126:129]
	v_mfma_f32_16x16x32_bf16 v[122:125], v[160:163], v[168:171], v[122:125]
	v_mfma_f32_16x16x32_bf16 v[110:113], v[152:155], v[176:179], v[110:113]
	v_mfma_f32_16x16x32_bf16 v[106:109], v[160:163], v[176:179], v[106:109]
	v_mfma_f32_16x16x32_bf16 v[94:97], v[152:155], v[184:187], v[94:97]
	v_mfma_f32_16x16x32_bf16 v[90:93], v[160:163], v[184:187], v[90:93]
	v_mfma_f32_16x16x32_bf16 v[78:81], v[152:155], v[212:215], v[78:81]
	v_mfma_f32_16x16x32_bf16 v[74:77], v[160:163], v[212:215], v[74:77]
	s_setprio 0
	s_barrier
	s_add_i32 s20, 0, 0x14000
	v_add_u32_e32 v192, s20, v146
	s_add_i32 s21, s22, s18
	ds_read_b128 v[216:219], v192
	ds_read_b128 v[220:223], v192 offset:1024
	ds_read_b128 v[224:227], v192 offset:2048
	ds_read_b128 v[228:231], v192 offset:3072
	v_lshl_add_u64 v[192:193], s[12:13], 0, v[0:1]
	s_mov_b32 m0, s21
	v_lshl_add_u64 v[198:199], s[12:13], 0, v[134:135]
	global_load_lds_dwordx4 v0, s[12:13]
	s_add_i32 m0, s21, 0x2000
	s_nop 0
	global_load_lds_dwordx4 v134, s[12:13]
	s_barrier
	s_waitcnt lgkmcnt(0)
	s_setprio 1
	s_waitcnt lgkmcnt(0)
	v_mfma_f32_16x16x32_bf16 v[118:121], v[216:219], v[164:167], v[118:121]
	v_mfma_f32_16x16x32_bf16 v[114:117], v[224:227], v[164:167], v[114:117]
	v_mfma_f32_16x16x32_bf16 v[102:105], v[216:219], v[172:175], v[102:105]
	v_mfma_f32_16x16x32_bf16 v[98:101], v[224:227], v[172:175], v[98:101]
	v_mfma_f32_16x16x32_bf16 v[86:89], v[216:219], v[180:183], v[86:89]
	v_mfma_f32_16x16x32_bf16 v[82:85], v[224:227], v[180:183], v[82:85]
	v_mfma_f32_16x16x32_bf16 v[70:73], v[216:219], v[188:191], v[70:73]
	v_mfma_f32_16x16x32_bf16 v[66:69], v[224:227], v[188:191], v[66:69]
	v_mfma_f32_16x16x32_bf16 v[118:121], v[220:223], v[168:171], v[118:121]
	v_mfma_f32_16x16x32_bf16 v[114:117], v[228:231], v[168:171], v[114:117]
	v_mfma_f32_16x16x32_bf16 v[102:105], v[220:223], v[176:179], v[102:105]
	v_mfma_f32_16x16x32_bf16 v[98:101], v[228:231], v[176:179], v[98:101]
	v_mfma_f32_16x16x32_bf16 v[86:89], v[220:223], v[184:187], v[86:89]
	v_mfma_f32_16x16x32_bf16 v[82:85], v[228:231], v[184:187], v[82:85]
	v_mfma_f32_16x16x32_bf16 v[70:73], v[220:223], v[212:215], v[70:73]
	v_mfma_f32_16x16x32_bf16 v[66:69], v[228:231], v[212:215], v[66:69]
	s_setprio 0
	s_mov_b32 m0, s30
	s_barrier
	ds_read_b128 v[164:167], v147 offset:16384
	ds_read_b128 v[168:171], v147 offset:17408
	ds_read_b128 v[172:175], v147 offset:18432
	ds_read_b128 v[176:179], v147 offset:19456
	ds_read_b128 v[180:183], v147 offset:20480
	ds_read_b128 v[184:187], v147 offset:21504
	ds_read_b128 v[188:191], v147 offset:22528
	ds_read_b128 v[212:215], v147 offset:23552
	global_load_lds_dwordx4 v130, s[16:17]
	s_mov_b32 m0, s31
	s_nop 0
	global_load_lds_dwordx4 v132, s[16:17]
	s_barrier
	s_waitcnt lgkmcnt(0)
	s_setprio 1
	s_waitcnt lgkmcnt(0)
	v_mfma_f32_16x16x32_bf16 v[62:65], v[148:151], v[164:167], v[62:65]
	v_mfma_f32_16x16x32_bf16 v[58:61], v[156:159], v[164:167], v[58:61]
	v_mfma_f32_16x16x32_bf16 v[46:49], v[148:151], v[172:175], v[46:49]
	v_mfma_f32_16x16x32_bf16 v[42:45], v[156:159], v[172:175], v[42:45]
	v_mfma_f32_16x16x32_bf16 v[30:33], v[148:151], v[180:183], v[30:33]
	v_mfma_f32_16x16x32_bf16 v[26:29], v[156:159], v[180:183], v[26:29]
	v_mfma_f32_16x16x32_bf16 v[14:17], v[148:151], v[188:191], v[14:17]
	v_mfma_f32_16x16x32_bf16 v[10:13], v[156:159], v[188:191], v[10:13]
	v_mfma_f32_16x16x32_bf16 v[62:65], v[152:155], v[168:171], v[62:65]
	v_mfma_f32_16x16x32_bf16 v[58:61], v[160:163], v[168:171], v[58:61]
	v_mfma_f32_16x16x32_bf16 v[46:49], v[152:155], v[176:179], v[46:49]
	v_mfma_f32_16x16x32_bf16 v[42:45], v[160:163], v[176:179], v[42:45]
	v_mfma_f32_16x16x32_bf16 v[30:33], v[152:155], v[184:187], v[30:33]
	v_mfma_f32_16x16x32_bf16 v[26:29], v[160:163], v[184:187], v[26:29]
	v_mfma_f32_16x16x32_bf16 v[14:17], v[152:155], v[212:215], v[14:17]
	v_mfma_f32_16x16x32_bf16 v[10:13], v[160:163], v[212:215], v[10:13]
	s_setprio 0
	s_barrier
; #define PG8_STAGE(bufoff, gbase, voff) do { _Pragma("unroll") for (int _i = 0; _i < 2; ++_i) \
;     __builtin_amdgcn_global_load_lds((const unsigned*)((const char*)(gbase) + (voff)[_i]), (LAS unsigned*)(lds + (bufoff) + ldsw + _i * 8192), 16, 0, 0); } while (0)
; #define PG8_LDA(dst, b, h) do { _Pragma("unroll") for (int m = 0; m < 4; ++m) _Pragma("unroll") for (int k = 0; k < 2; ++k) dst[m][k] = *(const LAS bf16x8*)(lds + PG8_SA(b, h) + aoff + m * 2048 + k * 1024); } while (0)
; #define PG8_LDB(dst, b, h) do { _Pragma("unroll") for (int n = 0; n < 2; ++n) _Pragma("unroll") for (int k = 0; k < 2; ++k) dst[n][k] = *(const LAS bf16x8*)(lds + PG8_SB(b, h) + boff + n * 2048 + k * 1024); } while (0)
; #define PG8_MMA(ai, bj, At, Bt) do { __builtin_amdgcn_s_setprio(1); _Pragma("unroll") for (int m = 0; m < 4; ++m) _Pragma("unroll") for (int n = 0; n < 2; ++n) _Pragma("unroll") for (int k = 0; k < 2; ++k) \
;     acc[ai][bj][m][n] = __builtin_amdgcn_mfma_f32_16x16x32_bf16(Bt[n][k], At[m][k], acc[ai][bj][m][n], 0, 0, 0); __builtin_amdgcn_s_setprio(0); } while (0)
; #define PG8_WAIT_V(n) asm volatile("s_waitcnt vmcnt(" #n ")" ::: "memory")
; #define PG8_WAIT_L(n) asm volatile("s_waitcnt lgkmcnt(" #n ")" ::: "memory")
; #define PG8_BAR __builtin_amdgcn_s_barrier()
; #define PG8_SCHED __builtin_amdgcn_sched_barrier(0)
; template <class Epi, bool SPLITA = false>
; __device__ __forceinline__ void gemm_phase(const int tid, LAS unsigned char* lds, const Gemm g, const Order& S, const Epi& E) {
;     ...
;       PG8_BAR; PG8_WAIT_L(0); PG8_MMA(1, 0, At, B0); PG8_BAR; PG8_SCHED;
;       PG8_STAGE(PG8_SB(0, 1), b2 + hstepB, voffB);
;       PG8_WAIT_V(6); PG8_BAR; PG8_MMA(1, 1, At, B1); PG8_BAR;
;       PG8_LDB(B0, 1, 0); PG8_SCHED; PG8_LDA(At, 1, 0); PG8_STAGE(PG8_SA(0, 1), a2 + hstepA, voffA);
;       PG8_WAIT_L(8); PG8_BAR; PG8_WAIT_L(0); PG8_MMA(0, 0, At, B0); PG8_BAR; PG8_SCHED;
;       PG8_LDB(B1, 1, 1); PG8_STAGE(PG8_SB(1, 0), b3, voffB);
;       PG8_BAR; PG8_WAIT_L(0); PG8_MMA(0, 1, At, B1); PG8_BAR;
;       PG8_LDA(At, 1, 1); PG8_STAGE(PG8_SA(1, 0), a3, voffA);
;       PG8_BAR; PG8_WAIT_L(0); PG8_MMA(1, 0, At, B0); PG8_BAR; PG8_SCHED;
	s_add_u32 s22, s12, 0x88000
	s_addc_u32 s23, s13, 0
	s_add_i32 s20, s20, s18
	s_mov_b32 m0, s20
	s_nop 0
	global_load_lds_dwordx4 v0, s[22:23]
	v_lshl_add_u64 v[148:149], s[22:23], 0, v[134:135]
	s_add_i32 m0, s20, 0x2000
	s_nop 0
	global_load_lds_dwordx4 v134, s[22:23]
	s_waitcnt vmcnt(6)
	s_barrier
	s_setprio 1
	v_mfma_f32_16x16x32_bf16 v[54:57], v[216:219], v[164:167], v[54:57]
	v_mfma_f32_16x16x32_bf16 v[50:53], v[224:227], v[164:167], v[50:53]
	v_mfma_f32_16x16x32_bf16 v[38:41], v[216:219], v[172:175], v[38:41]
	v_mfma_f32_16x16x32_bf16 v[34:37], v[224:227], v[172:175], v[34:37]
	v_mfma_f32_16x16x32_bf16 v[22:25], v[216:219], v[180:183], v[22:25]
	v_mfma_f32_16x16x32_bf16 v[18:21], v[224:227], v[180:183], v[18:21]
	v_mfma_f32_16x16x32_bf16 v[6:9], v[216:219], v[188:191], v[6:9]
	v_mfma_f32_16x16x32_bf16 v[2:5], v[224:227], v[188:191], v[2:5]
	v_mfma_f32_16x16x32_bf16 v[54:57], v[220:223], v[168:171], v[54:57]
	v_mfma_f32_16x16x32_bf16 v[50:53], v[228:231], v[168:171], v[50:53]
	v_mfma_f32_16x16x32_bf16 v[38:41], v[220:223], v[176:179], v[38:41]
	v_mfma_f32_16x16x32_bf16 v[34:37], v[228:231], v[176:179], v[34:37]
	v_mfma_f32_16x16x32_bf16 v[22:25], v[220:223], v[184:187], v[22:25]
	v_mfma_f32_16x16x32_bf16 v[18:21], v[228:231], v[184:187], v[18:21]
	v_mfma_f32_16x16x32_bf16 v[6:9], v[220:223], v[212:215], v[6:9]
	v_mfma_f32_16x16x32_bf16 v[2:5], v[228:231], v[212:215], v[2:5]
	s_setprio 0
	s_add_i32 s20, 0, 0x18000
	v_add_u32_e32 v160, s20, v146
	s_barrier
	ds_read_b128 v[148:151], v160
	ds_read_b128 v[152:155], v160 offset:1024
	ds_read_b128 v[156:159], v160 offset:2048
	ds_read_b128 v[160:163], v160 offset:3072
	s_add_u32 s16, s16, 0x88000
	s_addc_u32 s17, s17, 0
	s_mov_b32 m0, s42
	ds_read_b128 v[164:167], v147 offset:32768
	ds_read_b128 v[168:171], v147 offset:33792
	ds_read_b128 v[172:175], v147 offset:34816
	ds_read_b128 v[176:179], v147 offset:35840
	ds_read_b128 v[180:183], v147 offset:36864
	ds_read_b128 v[184:187], v147 offset:37888
	ds_read_b128 v[188:191], v147 offset:38912
	ds_read_b128 v[212:215], v147 offset:39936
	global_load_lds_dwordx4 v130, s[16:17]
	s_mov_b32 m0, s43
	s_nop 0
	global_load_lds_dwordx4 v132, s[16:17]
	s_waitcnt lgkmcnt(8)
	s_barrier
	s_waitcnt lgkmcnt(0)
	s_setprio 1
	s_waitcnt lgkmcnt(0)
	v_mfma_f32_16x16x32_bf16 v[126:129], v[148:151], v[164:167], v[126:129]
	v_mfma_f32_16x16x32_bf16 v[122:125], v[156:159], v[164:167], v[122:125]
	v_mfma_f32_16x16x32_bf16 v[110:113], v[148:151], v[172:175], v[110:113]
	v_mfma_f32_16x16x32_bf16 v[106:109], v[156:159], v[172:175], v[106:109]
	v_mfma_f32_16x16x32_bf16 v[94:97], v[148:151], v[180:183], v[94:97]
	v_mfma_f32_16x16x32_bf16 v[90:93], v[156:159], v[180:183], v[90:93]
	v_mfma_f32_16x16x32_bf16 v[78:81], v[148:151], v[188:191], v[78:81]
	v_mfma_f32_16x16x32_bf16 v[74:77], v[156:159], v[188:191], v[74:77]
	v_mfma_f32_16x16x32_bf16 v[126:129], v[152:155], v[168:171], v[126:129]
	v_mfma_f32_16x16x32_bf16 v[122:125], v[160:163], v[168:171], v[122:125]
	v_mfma_f32_16x16x32_bf16 v[110:113], v[152:155], v[176:179], v[110:113]
	v_mfma_f32_16x16x32_bf16 v[106:109], v[160:163], v[176:179], v[106:109]
	v_mfma_f32_16x16x32_bf16 v[94:97], v[152:155], v[184:187], v[94:97]
	v_mfma_f32_16x16x32_bf16 v[90:93], v[160:163], v[184:187], v[90:93]
	v_mfma_f32_16x16x32_bf16 v[78:81], v[152:155], v[212:215], v[78:81]
	v_mfma_f32_16x16x32_bf16 v[74:77], v[160:163], v[212:215], v[74:77]
	s_setprio 0
	s_barrier
	s_add_i32 s16, 0, 0x1c000
	s_add_i32 s17, s20, s18
	v_add_u32_e32 v195, s16, v146
	v_lshl_add_u64 v[192:193], v[192:193], 0, s[96:97]
	s_mov_b32 m0, s17
	ds_read_b128 v[216:219], v195
	ds_read_b128 v[220:223], v195 offset:1024
	ds_read_b128 v[224:227], v195 offset:2048
	ds_read_b128 v[228:231], v195 offset:3072
	global_load_lds_dwordx4 v[192:193], off
	v_lshl_add_u64 v[192:193], v[198:199], 0, s[96:97]
	s_add_i32 m0, s17, 0x2000
	s_nop 0
	global_load_lds_dwordx4 v[192:193], off
	s_barrier
	s_waitcnt lgkmcnt(0)
	s_setprio 1
	s_waitcnt lgkmcnt(0)
	v_mfma_f32_16x16x32_bf16 v[118:121], v[216:219], v[164:167], v[118:121]
	v_mfma_f32_16x16x32_bf16 v[114:117], v[224:227], v[164:167], v[114:117]
	v_mfma_f32_16x16x32_bf16 v[102:105], v[216:219], v[172:175], v[102:105]
	v_mfma_f32_16x16x32_bf16 v[98:101], v[224:227], v[172:175], v[98:101]
	v_mfma_f32_16x16x32_bf16 v[86:89], v[216:219], v[180:183], v[86:89]
	v_mfma_f32_16x16x32_bf16 v[82:85], v[224:227], v[180:183], v[82:85]
	v_mfma_f32_16x16x32_bf16 v[70:73], v[216:219], v[188:191], v[70:73]
	v_mfma_f32_16x16x32_bf16 v[66:69], v[224:227], v[188:191], v[66:69]
	v_mfma_f32_16x16x32_bf16 v[118:121], v[220:223], v[168:171], v[118:121]
	v_mfma_f32_16x16x32_bf16 v[114:117], v[228:231], v[168:171], v[114:117]
	v_mfma_f32_16x16x32_bf16 v[102:105], v[220:223], v[176:179], v[102:105]
	v_mfma_f32_16x16x32_bf16 v[98:101], v[228:231], v[176:179], v[98:101]
	v_mfma_f32_16x16x32_bf16 v[86:89], v[220:223], v[184:187], v[86:89]
	v_mfma_f32_16x16x32_bf16 v[82:85], v[228:231], v[184:187], v[82:85]
	v_mfma_f32_16x16x32_bf16 v[70:73], v[220:223], v[212:215], v[70:73]
	v_mfma_f32_16x16x32_bf16 v[66:69], v[228:231], v[212:215], v[66:69]
	s_setprio 0
	s_mov_b32 m0, s46
	s_barrier
; #define PG8_STAGE(bufoff, gbase, voff) do { _Pragma("unroll") for (int _i = 0; _i < 2; ++_i) \
;     __builtin_amdgcn_global_load_lds((const unsigned*)((const char*)(gbase) + (voff)[_i]), (LAS unsigned*)(lds + (bufoff) + ldsw + _i * 8192), 16, 0, 0); } while (0)
; #define PG8_LDA(dst, b, h) do { _Pragma("unroll") for (int m = 0; m < 4; ++m) _Pragma("unroll") for (int k = 0; k < 2; ++k) dst[m][k] = *(const LAS bf16x8*)(lds + PG8_SA(b, h) + aoff + m * 2048 + k * 1024); } while (0)
; #define PG8_LDB(dst, b, h) do { _Pragma("unroll") for (int n = 0; n < 2; ++n) _Pragma("unroll") for (int k = 0; k < 2; ++k) dst[n][k] = *(const LAS bf16x8*)(lds + PG8_SB(b, h) + boff + n * 2048 + k * 1024); } while (0)
; #define PG8_MMA(ai, bj, At, Bt) do { __builtin_amdgcn_s_setprio(1); _Pragma("unroll") for (int m = 0; m < 4; ++m) _Pragma("unroll") for (int n = 0; n < 2; ++n) _Pragma("unroll") for (int k = 0; k < 2; ++k) \
;     acc[ai][bj][m][n] = __builtin_amdgcn_mfma_f32_16x16x32_bf16(Bt[n][k], At[m][k], acc[ai][bj][m][n], 0, 0, 0); __builtin_amdgcn_s_setprio(0); } while (0)
; #define PG8_WAIT_V(n) asm volatile("s_waitcnt vmcnt(" #n ")" ::: "memory")
; #define PG8_BAR __builtin_amdgcn_s_barrier()
; template <class Epi, bool SPLITA = false>
; __device__ __forceinline__ void gemm_phase(const int tid, LAS unsigned char* lds, const Gemm g, const Order& S, const Epi& E) {
;     ...
;       PG8_LDB(B1, 1, 1); PG8_STAGE(PG8_SB(1, 0), b3, voffB);
;       PG8_BAR; PG8_WAIT_L(0); PG8_MMA(0, 1, At, B1); PG8_BAR;
;       PG8_LDA(At, 1, 1); PG8_STAGE(PG8_SA(1, 0), a3, voffA);
;       PG8_BAR; PG8_WAIT_L(0); PG8_MMA(1, 0, At, B0); PG8_BAR; PG8_SCHED;
;       PG8_STAGE(PG8_SB(1, 1), b3 + hstepB, voffB);
;       PG8_WAIT_V(6); PG8_BAR; PG8_MMA(1, 1, At, B1); PG8_BAR;
;   __device__ __forceinline__ void operator()(const Acc& acc, const Unit& u, int wr, int wc, int fr_, int fq_) const {
;     ...
;     const int z = u.pn >> 2, b = z >> 4, k1 = z & 15, j0 = (u.pn & 3) * 256 + wc * 32 + 8 * fq;
;     const int r0 = u.pm * BM + wr * 64 + fr;
; #pragma unroll
;     for (int ai = 0; ai < 2; ++ai)
; #pragma unroll
;       for (int m = 0; m < 4; ++m) { const int k2 = r0 + ai * HALF + m * 16;
;         if (k2 < FN2) { bf16_t* rowp = F + (size_t)row_of(b, k1 + 16 * k2) * 1024 + j0;
; #pragma unroll
;           for (int bj = 0; bj < 2; ++bj) *(u32x4*)(rowp + bj * HALF) = pack8(acc[ai][bj][m][0], acc[ai][bj][m][1]); } }
	ds_read_b128 v[164:167], v147 offset:49152
	ds_read_b128 v[168:171], v147 offset:50176
	ds_read_b128 v[172:175], v147 offset:51200
	ds_read_b128 v[176:179], v147 offset:52224
	ds_read_b128 v[180:183], v147 offset:53248
	ds_read_b128 v[184:187], v147 offset:54272
	ds_read_b128 v[188:191], v147 offset:55296
	ds_read_b128 v[212:215], v147 offset:56320
	global_load_lds_dwordx4 v130, s[14:15]
	s_mov_b32 m0, s47
	s_nop 0
	global_load_lds_dwordx4 v132, s[14:15]
	s_barrier
	s_waitcnt lgkmcnt(0)
	s_setprio 1
	s_waitcnt lgkmcnt(0)
	v_mfma_f32_16x16x32_bf16 v[62:65], v[148:151], v[164:167], v[62:65]
	v_mfma_f32_16x16x32_bf16 v[58:61], v[156:159], v[164:167], v[58:61]
	v_mfma_f32_16x16x32_bf16 v[46:49], v[148:151], v[172:175], v[46:49]
	v_mfma_f32_16x16x32_bf16 v[42:45], v[156:159], v[172:175], v[42:45]
	v_mfma_f32_16x16x32_bf16 v[30:33], v[148:151], v[180:183], v[30:33]
	v_mfma_f32_16x16x32_bf16 v[26:29], v[156:159], v[180:183], v[26:29]
	v_mfma_f32_16x16x32_bf16 v[14:17], v[148:151], v[188:191], v[14:17]
	v_mfma_f32_16x16x32_bf16 v[10:13], v[156:159], v[188:191], v[10:13]
	v_mfma_f32_16x16x32_bf16 v[62:65], v[152:155], v[168:171], v[62:65]
	v_mfma_f32_16x16x32_bf16 v[58:61], v[160:163], v[168:171], v[58:61]
	v_mfma_f32_16x16x32_bf16 v[46:49], v[152:155], v[176:179], v[46:49]
	v_mfma_f32_16x16x32_bf16 v[42:45], v[160:163], v[176:179], v[42:45]
	v_mfma_f32_16x16x32_bf16 v[30:33], v[152:155], v[184:187], v[30:33]
	v_mfma_f32_16x16x32_bf16 v[26:29], v[160:163], v[184:187], v[26:29]
	v_mfma_f32_16x16x32_bf16 v[14:17], v[152:155], v[212:215], v[14:17]
	v_mfma_f32_16x16x32_bf16 v[10:13], v[160:163], v[212:215], v[10:13]
	s_setprio 0
	s_barrier
	s_add_u32 s12, s12, 0x88080
	s_addc_u32 s13, s13, 0
	s_add_i32 s14, s16, s18
	s_mov_b32 m0, s14
	s_nop 0
	global_load_lds_dwordx4 v0, s[12:13]
	s_add_i32 m0, s14, 0x2000
	s_nop 0
	global_load_lds_dwordx4 v134, s[12:13]
	s_waitcnt vmcnt(6)
	s_barrier
	s_setprio 1
	v_mfma_f32_16x16x32_bf16 v[54:57], v[216:219], v[164:167], v[54:57]
	v_mfma_f32_16x16x32_bf16 v[50:53], v[224:227], v[164:167], v[50:53]
	v_mfma_f32_16x16x32_bf16 v[38:41], v[216:219], v[172:175], v[38:41]
	v_mfma_f32_16x16x32_bf16 v[34:37], v[224:227], v[172:175], v[34:37]
	v_mfma_f32_16x16x32_bf16 v[22:25], v[216:219], v[180:183], v[22:25]
	v_mfma_f32_16x16x32_bf16 v[18:21], v[224:227], v[180:183], v[18:21]
	v_mfma_f32_16x16x32_bf16 v[6:9], v[216:219], v[188:191], v[6:9]
	v_mfma_f32_16x16x32_bf16 v[2:5], v[224:227], v[188:191], v[2:5]
	v_mfma_f32_16x16x32_bf16 v[54:57], v[220:223], v[168:171], v[54:57]
	v_mfma_f32_16x16x32_bf16 v[50:53], v[228:231], v[168:171], v[50:53]
	v_mfma_f32_16x16x32_bf16 v[38:41], v[220:223], v[176:179], v[38:41]
	v_mfma_f32_16x16x32_bf16 v[34:37], v[228:231], v[176:179], v[34:37]
	v_mfma_f32_16x16x32_bf16 v[22:25], v[220:223], v[184:187], v[22:25]
	v_mfma_f32_16x16x32_bf16 v[18:21], v[228:231], v[184:187], v[18:21]
	v_mfma_f32_16x16x32_bf16 v[6:9], v[220:223], v[212:215], v[6:9]
	v_mfma_f32_16x16x32_bf16 v[2:5], v[228:231], v[212:215], v[2:5]
	s_setprio 0
	s_add_i32 s91, s91, 2
	s_add_u32 s10, s10, 0x100
	s_addc_u32 s11, s11, 0
	s_cmp_gt_u32 s91, 31
	s_barrier
	s_cbranch_scc0 .LBB0_328
	s_lshl_b32 s10, s51, 8
	v_mov_b32_e32 v141, v145
	v_mov_b32_e32 v140, v144
	s_and_b32 s10, s10, 0x300
	s_or_b32 s10, s10, s45
	v_lshl_add_u32 v140, v140, 3, s10
	s_lshl_b32 s10, s52, 8
	s_ashr_i32 s8, s51, 6
	s_add_i32 s10, s10, s44
	s_bfe_u32 s9, s51, 0x40002
	v_add_u32_e32 v142, s10, v141
	s_lshl_b32 s10, s8, 14
	s_lshl_b32 s11, s8, 4
	s_movk_i32 s8, 0x401
	s_add_i32 s10, s10, -16
	s_add_i32 s11, s11, 0x8000
	v_ashrrev_i32_e32 v141, 31, v140
	v_cmp_gt_i32_e32 vcc, s8, v142
	v_lshl_or_b32 v143, v142, 4, s9
	s_and_saveexec_b64 s[8:9], vcc
	s_cbranch_execz .LBB0_331
	v_mov_b32_e32 v148, s10
	v_mov_b32_e32 v149, s11
	v_cmp_gt_i32_e32 vcc, 16, v143
	v_readlane_b32 s12, v255, 1
	v_readlane_b32 s13, v255, 2
	v_cndmask_b32_e32 v148, v148, v149, vcc
	v_add_u32_e32 v148, v148, v143
	v_ashrrev_i32_e32 v149, 31, v148
	v_lshlrev_b64 v[148:149], 11, v[148:149]
	v_lshl_add_u64 v[148:149], s[12:13], 0, v[148:149]
	v_lshl_add_u64 v[148:149], v[140:141], 1, v[148:149]
	v_cvt_pk_bf16_f32 v126, v126, v127
	v_cvt_pk_bf16_f32 v127, v128, v129
	v_cvt_pk_bf16_f32 v128, v122, v123
	v_cvt_pk_bf16_f32 v129, v124, v125
	v_cvt_pk_bf16_f32 v118, v118, v119
	v_cvt_pk_bf16_f32 v119, v120, v121
	v_cvt_pk_bf16_f32 v120, v114, v115
	v_cvt_pk_bf16_f32 v121, v116, v117
	global_store_dwordx4 v[148:149], v[126:129], off
	global_store_dwordx4 v[148:149], v[118:121], off offset:256

; #define PG8_STAGE(bufoff, gbase, voff) do { _Pragma("unroll") for (int _i = 0; _i < 2; ++_i) \
;     __builtin_amdgcn_global_load_lds((const unsigned*)((const char*)(gbase) + (voff)[_i]), (LAS unsigned*)(lds + (bufoff) + ldsw + _i * 8192), 16, 0, 0); } while (0)
; #define PG8_WAIT_V(n) asm volatile("s_waitcnt vmcnt(" #n ")" ::: "memory")
; #define PG8_BAR __builtin_amdgcn_s_barrier()
; template <class Epi, bool SPLITA = false>
; __device__ __forceinline__ void gemm_phase(const int tid, LAS unsigned char* lds, const Gemm g, const Order& S, const Epi& E) {
;     ...
;   PG8_STAGE(PG8_SB(0, 0), cB, voffB); PG8_STAGE(PG8_SA(0, 0), cA, voffA); PG8_STAGE(PG8_SB(0, 1), cB + hstepB, voffB); PG8_STAGE(PG8_SA(0, 1), cA + hstepA, voffA);
;   if (wr == 1) PG8_BAR;
;   PG8_WAIT_V(4); PG8_BAR;
;   PG8_STAGE(PG8_SB(1, 0), cB + kstep, voffB); PG8_STAGE(PG8_SA(1, 0), cA + kstep, voffA); PG8_STAGE(PG8_SB(1, 1), cB + hstepB + kstep, voffB);
;   PG8_WAIT_V(6); PG8_BAR;
.LBB0_388:
	s_and_b32 s90, 0xffff, s3
	s_ashr_i32 s3, s0, 31
	v_bfe_u32 v144, v210, 4, 2
	s_lshr_b32 s3, s3, 26
	s_lshl_b32 s1, s1, 5
	v_and_b32_e32 v145, 15, v210
	s_add_i32 s3, s0, s3
	v_lshlrev_b32_e32 v12, 4, v144
	v_lshlrev_b32_e32 v13, 2, v210
	s_and_b32 s48, s1, 0x60
	s_ashr_i32 s46, s3, 6
	s_lshl_b32 s47, s2, 6
	v_lshl_or_b32 v12, v145, 6, v12
	s_lshl_b32 s2, s2, 13
	v_and_b32_e32 v13, 32, v13
	s_lshl_b32 s1, s48, 7
	v_readlane_b32 s8, v255, 24
	v_bitop3_b32 v14, v12, s2, v13 bitop3:0xde
	v_readlane_b32 s9, v255, 25
	s_add_u32 s2, s8, 0x3c1e0080
	v_mov_b32_e32 v135, v1
	s_addc_u32 s3, s9, 0
	v_mov_b32_e32 v131, v1
	v_bitop3_b32 v146, s1, v12, v13 bitop3:0xf6
	s_add_i32 m0, s30, 0x18000
	s_waitcnt vmcnt(4)
	s_barrier
	global_load_lds_dwordx4 v134, s[2:3]
	s_add_i32 m0, s30, 0x1a000
	s_add_i32 s49, s30, 0x8000
	s_add_i32 s51, s30, 0xa000
	global_load_lds_dwordx4 v130, s[2:3]
	v_lshl_add_u64 v[4:5], v[4:5], 0, s[96:97]
	s_mov_b32 m0, s49
	s_add_u32 s2, s8, 0x3c1e8080
	global_load_lds_dwordx4 v[4:5], off
	v_lshl_add_u64 v[2:3], v[2:3], 0, s[96:97]
	s_mov_b32 m0, s51
	s_addc_u32 s3, s9, 0
	global_load_lds_dwordx4 v[2:3], off
	s_add_i32 m0, s30, 0x1c000
	s_nop 0
	global_load_lds_dwordx4 v134, s[2:3]
	v_lshl_add_u64 v[2:3], s[2:3], 0, v[130:131]
	s_add_i32 m0, s30, 0x1e000
	s_cmp_gt_i32 s0, 63
	global_load_lds_dwordx4 v130, s[2:3]
	v_lshlrev_b32_e32 v2, 14, v9
	v_and_b32_e32 v2, 0xffff8000, v2
	v_lshl_add_u32 v2, v10, 11, v2
	v_and_b32_e32 v3, 1, v9
	v_lshl_or_b32 v2, v3, 6, v2
	v_lshl_add_u32 v2, v11, 1, v2
	v_mov_b32_e32 v3, v1
	s_mov_b64 s[0:1], 0x40080
	v_lshl_add_u64 v[136:137], v[2:3], 0, s[0:1]
	v_lshlrev_b32_e32 v2, 14, v6
	v_and_b32_e32 v2, 0xffff8000, v2
	v_lshl_add_u32 v2, v7, 11, v2
	v_and_b32_e32 v3, 1, v6
	s_waitcnt vmcnt(6)
	v_lshl_or_b32 v2, v3, 6, v2
	v_lshl_add_u32 v2, v8, 1, v2
	v_mov_b32_e32 v3, v1
	s_cselect_b64 s[2:3], -1, 0
	s_add_i32 s52, s46, -2
	s_ashr_i32 s53, s92, 31
	v_lshl_add_u64 v[138:139], v[2:3], 0, s[0:1]
	s_mov_b32 s54, 0
	v_add_u32_e32 v147, 0, v14
	s_barrier
	s_waitcnt vmcnt(0)
	s_branch .LBB0_390

; #define PG8_STAGE(bufoff, gbase, voff) do { _Pragma("unroll") for (int _i = 0; _i < 2; ++_i) \
;     __builtin_amdgcn_global_load_lds((const unsigned*)((const char*)(gbase) + (voff)[_i]), (LAS unsigned*)(lds + (bufoff) + ldsw + _i * 8192), 16, 0, 0); } while (0)
; #define PG8_LDA(dst, b, h) do { _Pragma("unroll") for (int m = 0; m < 4; ++m) _Pragma("unroll") for (int k = 0; k < 2; ++k) dst[m][k] = *(const LAS bf16x8*)(lds + PG8_SA(b, h) + aoff + m * 2048 + k * 1024); } while (0)
; #define PG8_LDB(dst, b, h) do { _Pragma("unroll") for (int n = 0; n < 2; ++n) _Pragma("unroll") for (int k = 0; k < 2; ++k) dst[n][k] = *(const LAS bf16x8*)(lds + PG8_SB(b, h) + boff + n * 2048 + k * 1024); } while (0)
; #define PG8_MMA(ai, bj, At, Bt) do { __builtin_amdgcn_s_setprio(1); _Pragma("unroll") for (int m = 0; m < 4; ++m) _Pragma("unroll") for (int n = 0; n < 2; ++n) _Pragma("unroll") for (int k = 0; k < 2; ++k) \
;     acc[ai][bj][m][n] = __builtin_amdgcn_mfma_f32_16x16x32_bf16(Bt[n][k], At[m][k], acc[ai][bj][m][n], 0, 0, 0); __builtin_amdgcn_s_setprio(0); } while (0)
; #define PG8_WAIT_L(n) asm volatile("s_waitcnt lgkmcnt(" #n ")" ::: "memory")
; #define PG8_BAR __builtin_amdgcn_s_barrier()
; #define PG8_SCHED __builtin_amdgcn_sched_barrier(0)
; template <class Epi, bool SPLITA = false>
; __device__ __forceinline__ void gemm_phase(const int tid, LAS unsigned char* lds, const Gemm g, const Order& S, const Epi& E) {
;     ...
;     for (int t = 0; t < nt; t += 2) {
;       const bool last = (t == nt - 2);
;       if constexpr (SPLITA) { if (t == nt1) E.mid(acc, cur, wr, wc, fr, fq); }
;       const char* a1 = PG8_TA(t + 1);
;       const char* a2 = last ? nA : PG8_TA(t + 2); const char* b2 = last ? nB : cB + (size_t)(t + 2) * kstep;
;       const char* a3 = last ? nA + kstep : PG8_TA(t + 3); const char* b3 = b2 + kstep;
;       PG8_LDB(B0, 0, 0); PG8_SCHED; PG8_LDA(At, 0, 0); PG8_STAGE(PG8_SA(1, 1), a1 + hstepA, voffA);
;       PG8_WAIT_L(8); PG8_BAR; PG8_WAIT_L(0); PG8_MMA(0, 0, At, B0); PG8_BAR; PG8_SCHED;
;       PG8_LDB(B1, 0, 1); PG8_STAGE(PG8_SB(0, 0), b2, voffB);
;       PG8_BAR; PG8_WAIT_L(0); PG8_MMA(0, 1, At, B1); PG8_BAR;
;       PG8_LDA(At, 0, 1); PG8_STAGE(PG8_SA(0, 0), a2, voffA);
;       PG8_BAR; PG8_WAIT_L(0); PG8_MMA(1, 0, At, B0); PG8_BAR; PG8_SCHED;
.LBB0_400:
	s_add_i32 s29, s18, 2
	s_add_u32 s16, s14, 0x100
	s_addc_u32 s17, s15, 0
	s_add_u32 s19, s12, s14
	s_addc_u32 s20, s13, s15
	s_add_u32 s21, s19, 0x100
	s_addc_u32 s22, s20, 0
	s_add_u32 s19, s19, 0x180
	s_addc_u32 s20, s20, 0
	s_add_i32 s23, 0, 0x10000
	v_add_u32_e32 v160, s23, v146
	ds_read_b128 v[148:151], v160
	ds_read_b128 v[152:155], v160 offset:1024
	ds_read_b128 v[156:159], v160 offset:2048
	ds_read_b128 v[160:163], v160 offset:3072
	s_cmp_eq_u32 s52, s18
	s_cselect_b32 s18, 0, s16
	s_cselect_b32 s41, s11, s20
	s_cselect_b32 s40, s9, s19
	s_cselect_b32 s19, 0, s17
	s_cselect_b32 s42, s0, s21
	s_cselect_b32 s43, s1, s22
	s_add_u32 s18, s6, s18
	s_addc_u32 s19, s7, s19
	v_lshl_add_u64 v[192:193], v[140:141], 0, s[14:15]
	s_add_i32 m0, s30, 0xc000
	ds_read_b128 v[164:167], v147
	ds_read_b128 v[168:171], v147 offset:1024
	ds_read_b128 v[172:175], v147 offset:2048
	ds_read_b128 v[176:179], v147 offset:3072
	ds_read_b128 v[180:183], v147 offset:4096
	ds_read_b128 v[184:187], v147 offset:5120
	ds_read_b128 v[188:191], v147 offset:6144
	ds_read_b128 v[212:215], v147 offset:7168
	global_load_lds_dwordx4 v[192:193], off
	v_lshl_add_u64 v[192:193], v[142:143], 0, s[14:15]
	s_add_i32 m0, s30, 0xe000
	s_nop 0
	global_load_lds_dwordx4 v[192:193], off
	s_waitcnt lgkmcnt(8)
	s_barrier
	s_waitcnt lgkmcnt(0)
	s_setprio 1
	s_waitcnt lgkmcnt(0)
	v_mfma_f32_16x16x32_bf16 v[122:125], v[148:151], v[164:167], v[122:125]
	v_mfma_f32_16x16x32_bf16 v[126:129], v[156:159], v[164:167], v[126:129]
	v_mfma_f32_16x16x32_bf16 v[110:113], v[148:151], v[172:175], v[110:113]
	v_mfma_f32_16x16x32_bf16 v[106:109], v[156:159], v[172:175], v[106:109]
	v_mfma_f32_16x16x32_bf16 v[94:97], v[148:151], v[180:183], v[94:97]
	v_mfma_f32_16x16x32_bf16 v[90:93], v[156:159], v[180:183], v[90:93]
	v_mfma_f32_16x16x32_bf16 v[78:81], v[148:151], v[188:191], v[78:81]
	v_mfma_f32_16x16x32_bf16 v[74:77], v[156:159], v[188:191], v[74:77]
	v_mfma_f32_16x16x32_bf16 v[122:125], v[152:155], v[168:171], v[122:125]
	v_mfma_f32_16x16x32_bf16 v[126:129], v[160:163], v[168:171], v[126:129]
	v_mfma_f32_16x16x32_bf16 v[110:113], v[152:155], v[176:179], v[110:113]
	v_mfma_f32_16x16x32_bf16 v[106:109], v[160:163], v[176:179], v[106:109]
	v_mfma_f32_16x16x32_bf16 v[94:97], v[152:155], v[184:187], v[94:97]
	v_mfma_f32_16x16x32_bf16 v[90:93], v[160:163], v[184:187], v[90:93]
	v_mfma_f32_16x16x32_bf16 v[78:81], v[152:155], v[212:215], v[78:81]
	v_mfma_f32_16x16x32_bf16 v[74:77], v[160:163], v[212:215], v[74:77]
	s_setprio 0
	s_barrier
	s_add_i32 s20, 0, 0x14000
	v_add_u32_e32 v192, s20, v146
	s_add_i32 s14, s23, s28
	ds_read_b128 v[216:219], v192
	ds_read_b128 v[220:223], v192 offset:1024
	ds_read_b128 v[224:227], v192 offset:2048
	ds_read_b128 v[228:231], v192 offset:3072
	v_lshl_add_u64 v[192:193], s[18:19], 0, v[134:135]
	s_mov_b32 m0, s14
	v_lshl_add_u64 v[232:233], s[18:19], 0, v[130:131]
	global_load_lds_dwordx4 v134, s[18:19]
	s_add_i32 m0, s14, 0x2000
	s_nop 0
	global_load_lds_dwordx4 v130, s[18:19]
	s_barrier
	s_waitcnt lgkmcnt(0)
	s_setprio 1
	s_waitcnt lgkmcnt(0)
	v_mfma_f32_16x16x32_bf16 v[118:121], v[216:219], v[164:167], v[118:121]
	v_mfma_f32_16x16x32_bf16 v[114:117], v[224:227], v[164:167], v[114:117]
	v_mfma_f32_16x16x32_bf16 v[102:105], v[216:219], v[172:175], v[102:105]
	v_mfma_f32_16x16x32_bf16 v[98:101], v[224:227], v[172:175], v[98:101]
	v_mfma_f32_16x16x32_bf16 v[86:89], v[216:219], v[180:183], v[86:89]
	v_mfma_f32_16x16x32_bf16 v[82:85], v[224:227], v[180:183], v[82:85]
	v_mfma_f32_16x16x32_bf16 v[70:73], v[216:219], v[188:191], v[70:73]
	v_mfma_f32_16x16x32_bf16 v[66:69], v[224:227], v[188:191], v[66:69]
	v_mfma_f32_16x16x32_bf16 v[118:121], v[220:223], v[168:171], v[118:121]
	v_mfma_f32_16x16x32_bf16 v[114:117], v[228:231], v[168:171], v[114:117]
	v_mfma_f32_16x16x32_bf16 v[102:105], v[220:223], v[176:179], v[102:105]
	v_mfma_f32_16x16x32_bf16 v[98:101], v[228:231], v[176:179], v[98:101]
	v_mfma_f32_16x16x32_bf16 v[86:89], v[220:223], v[184:187], v[86:89]
	v_mfma_f32_16x16x32_bf16 v[82:85], v[228:231], v[184:187], v[82:85]
	v_mfma_f32_16x16x32_bf16 v[70:73], v[220:223], v[212:215], v[70:73]
	v_mfma_f32_16x16x32_bf16 v[66:69], v[228:231], v[212:215], v[66:69]
	s_setprio 0
	s_mov_b32 m0, s30
	s_barrier
	ds_read_b128 v[164:167], v147 offset:16384
	ds_read_b128 v[168:171], v147 offset:17408
	ds_read_b128 v[172:175], v147 offset:18432
	ds_read_b128 v[176:179], v147 offset:19456
	ds_read_b128 v[180:183], v147 offset:20480
	ds_read_b128 v[184:187], v147 offset:21504
	ds_read_b128 v[188:191], v147 offset:22528
	ds_read_b128 v[212:215], v147 offset:23552
	global_load_lds_dwordx4 v0, s[42:43]
	s_mov_b32 m0, s31
	s_nop 0
	global_load_lds_dwordx4 v132, s[42:43]
	s_barrier
	s_waitcnt lgkmcnt(0)
	s_setprio 1
	s_waitcnt lgkmcnt(0)
	v_mfma_f32_16x16x32_bf16 v[62:65], v[148:151], v[164:167], v[62:65]
	v_mfma_f32_16x16x32_bf16 v[58:61], v[156:159], v[164:167], v[58:61]
	v_mfma_f32_16x16x32_bf16 v[46:49], v[148:151], v[172:175], v[46:49]
	v_mfma_f32_16x16x32_bf16 v[42:45], v[156:159], v[172:175], v[42:45]
	v_mfma_f32_16x16x32_bf16 v[30:33], v[148:151], v[180:183], v[30:33]
	v_mfma_f32_16x16x32_bf16 v[26:29], v[156:159], v[180:183], v[26:29]
	v_mfma_f32_16x16x32_bf16 v[14:17], v[148:151], v[188:191], v[14:17]
	v_mfma_f32_16x16x32_bf16 v[10:13], v[156:159], v[188:191], v[10:13]
	v_mfma_f32_16x16x32_bf16 v[62:65], v[152:155], v[168:171], v[62:65]
	v_mfma_f32_16x16x32_bf16 v[58:61], v[160:163], v[168:171], v[58:61]
	v_mfma_f32_16x16x32_bf16 v[46:49], v[152:155], v[176:179], v[46:49]
	v_mfma_f32_16x16x32_bf16 v[42:45], v[160:163], v[176:179], v[42:45]
	v_mfma_f32_16x16x32_bf16 v[30:33], v[152:155], v[184:187], v[30:33]
	v_mfma_f32_16x16x32_bf16 v[26:29], v[160:163], v[184:187], v[26:29]
	v_mfma_f32_16x16x32_bf16 v[14:17], v[152:155], v[212:215], v[14:17]
	v_mfma_f32_16x16x32_bf16 v[10:13], v[160:163], v[212:215], v[10:13]
	s_setprio 0
	s_barrier
; #define PG8_STAGE(bufoff, gbase, voff) do { _Pragma("unroll") for (int _i = 0; _i < 2; ++_i) \
;     __builtin_amdgcn_global_load_lds((const unsigned*)((const char*)(gbase) + (voff)[_i]), (LAS unsigned*)(lds + (bufoff) + ldsw + _i * 8192), 16, 0, 0); } while (0)
; #define PG8_LDA(dst, b, h) do { _Pragma("unroll") for (int m = 0; m < 4; ++m) _Pragma("unroll") for (int k = 0; k < 2; ++k) dst[m][k] = *(const LAS bf16x8*)(lds + PG8_SA(b, h) + aoff + m * 2048 + k * 1024); } while (0)
; #define PG8_LDB(dst, b, h) do { _Pragma("unroll") for (int n = 0; n < 2; ++n) _Pragma("unroll") for (int k = 0; k < 2; ++k) dst[n][k] = *(const LAS bf16x8*)(lds + PG8_SB(b, h) + boff + n * 2048 + k * 1024); } while (0)
; #define PG8_MMA(ai, bj, At, Bt) do { __builtin_amdgcn_s_setprio(1); _Pragma("unroll") for (int m = 0; m < 4; ++m) _Pragma("unroll") for (int n = 0; n < 2; ++n) _Pragma("unroll") for (int k = 0; k < 2; ++k) \
;     acc[ai][bj][m][n] = __builtin_amdgcn_mfma_f32_16x16x32_bf16(Bt[n][k], At[m][k], acc[ai][bj][m][n], 0, 0, 0); __builtin_amdgcn_s_setprio(0); } while (0)
; #define PG8_WAIT_V(n) asm volatile("s_waitcnt vmcnt(" #n ")" ::: "memory")
; #define PG8_WAIT_L(n) asm volatile("s_waitcnt lgkmcnt(" #n ")" ::: "memory")
; #define PG8_BAR __builtin_amdgcn_s_barrier()
; #define PG8_SCHED __builtin_amdgcn_sched_barrier(0)
; template <class Epi, bool SPLITA = false>
; __device__ __forceinline__ void gemm_phase(const int tid, LAS unsigned char* lds, const Gemm g, const Order& S, const Epi& E) {
;     ...
;       PG8_BAR; PG8_WAIT_L(0); PG8_MMA(1, 0, At, B0); PG8_BAR; PG8_SCHED;
;       PG8_STAGE(PG8_SB(0, 1), b2 + hstepB, voffB);
;       PG8_WAIT_V(6); PG8_BAR; PG8_MMA(1, 1, At, B1); PG8_BAR;
;       PG8_LDB(B0, 1, 0); PG8_SCHED; PG8_LDA(At, 1, 0); PG8_STAGE(PG8_SA(0, 1), a2 + hstepA, voffA);
;       PG8_WAIT_L(8); PG8_BAR; PG8_WAIT_L(0); PG8_MMA(0, 0, At, B0); PG8_BAR; PG8_SCHED;
;       PG8_LDB(B1, 1, 1); PG8_STAGE(PG8_SB(1, 0), b3, voffB);
;       PG8_BAR; PG8_WAIT_L(0); PG8_MMA(0, 1, At, B1); PG8_BAR;
;       PG8_LDA(At, 1, 1); PG8_STAGE(PG8_SA(1, 0), a3, voffA);
;       PG8_BAR; PG8_WAIT_L(0); PG8_MMA(1, 0, At, B0); PG8_BAR; PG8_SCHED;
	s_add_u32 s14, s18, 0x8000
	s_addc_u32 s15, s19, 0
	s_add_i32 s20, s20, s28
	s_mov_b32 m0, s20
	s_nop 0
	global_load_lds_dwordx4 v134, s[14:15]
	v_lshl_add_u64 v[148:149], s[14:15], 0, v[130:131]
	s_add_i32 m0, s20, 0x2000
	s_nop 0
	global_load_lds_dwordx4 v130, s[14:15]
	s_waitcnt vmcnt(6)
	s_barrier
	s_setprio 1
	v_mfma_f32_16x16x32_bf16 v[54:57], v[216:219], v[164:167], v[54:57]
	v_mfma_f32_16x16x32_bf16 v[50:53], v[224:227], v[164:167], v[50:53]
	v_mfma_f32_16x16x32_bf16 v[38:41], v[216:219], v[172:175], v[38:41]
	v_mfma_f32_16x16x32_bf16 v[34:37], v[224:227], v[172:175], v[34:37]
	v_mfma_f32_16x16x32_bf16 v[22:25], v[216:219], v[180:183], v[22:25]
	v_mfma_f32_16x16x32_bf16 v[18:21], v[224:227], v[180:183], v[18:21]
	v_mfma_f32_16x16x32_bf16 v[6:9], v[216:219], v[188:191], v[6:9]
	v_mfma_f32_16x16x32_bf16 v[2:5], v[224:227], v[188:191], v[2:5]
	v_mfma_f32_16x16x32_bf16 v[54:57], v[220:223], v[168:171], v[54:57]
	v_mfma_f32_16x16x32_bf16 v[50:53], v[228:231], v[168:171], v[50:53]
	v_mfma_f32_16x16x32_bf16 v[38:41], v[220:223], v[176:179], v[38:41]
	v_mfma_f32_16x16x32_bf16 v[34:37], v[228:231], v[176:179], v[34:37]
	v_mfma_f32_16x16x32_bf16 v[22:25], v[220:223], v[184:187], v[22:25]
	v_mfma_f32_16x16x32_bf16 v[18:21], v[228:231], v[184:187], v[18:21]
	v_mfma_f32_16x16x32_bf16 v[6:9], v[220:223], v[212:215], v[6:9]
	v_mfma_f32_16x16x32_bf16 v[2:5], v[228:231], v[212:215], v[2:5]
	s_setprio 0
	s_add_i32 s20, 0, 0x18000
	v_add_u32_e32 v160, s20, v146
	s_barrier
	ds_read_b128 v[148:151], v160
	ds_read_b128 v[152:155], v160 offset:1024
	ds_read_b128 v[156:159], v160 offset:2048
	ds_read_b128 v[160:163], v160 offset:3072
	s_add_u32 s14, s42, 0x40000
	s_addc_u32 s15, s43, 0
	s_mov_b32 m0, s44
	ds_read_b128 v[164:167], v147 offset:32768
	ds_read_b128 v[168:171], v147 offset:33792
	ds_read_b128 v[172:175], v147 offset:34816
	ds_read_b128 v[176:179], v147 offset:35840
	ds_read_b128 v[180:183], v147 offset:36864
	ds_read_b128 v[184:187], v147 offset:37888
	ds_read_b128 v[188:191], v147 offset:38912
	ds_read_b128 v[212:215], v147 offset:39936
	global_load_lds_dwordx4 v0, s[14:15]
	v_lshl_add_u64 v[216:217], s[14:15], 0, v[132:133]
	s_mov_b32 m0, s45
	s_nop 0
	global_load_lds_dwordx4 v132, s[14:15]
	s_waitcnt lgkmcnt(8)
	s_barrier
	s_waitcnt lgkmcnt(0)
	s_setprio 1
	s_waitcnt lgkmcnt(0)
	v_mfma_f32_16x16x32_bf16 v[122:125], v[148:151], v[164:167], v[122:125]
	v_mfma_f32_16x16x32_bf16 v[126:129], v[156:159], v[164:167], v[126:129]
	v_mfma_f32_16x16x32_bf16 v[110:113], v[148:151], v[172:175], v[110:113]
	v_mfma_f32_16x16x32_bf16 v[106:109], v[156:159], v[172:175], v[106:109]
	v_mfma_f32_16x16x32_bf16 v[94:97], v[148:151], v[180:183], v[94:97]
	v_mfma_f32_16x16x32_bf16 v[90:93], v[156:159], v[180:183], v[90:93]
	v_mfma_f32_16x16x32_bf16 v[78:81], v[148:151], v[188:191], v[78:81]
	v_mfma_f32_16x16x32_bf16 v[74:77], v[156:159], v[188:191], v[74:77]
	v_mfma_f32_16x16x32_bf16 v[122:125], v[152:155], v[168:171], v[122:125]
	v_mfma_f32_16x16x32_bf16 v[126:129], v[160:163], v[168:171], v[126:129]
	v_mfma_f32_16x16x32_bf16 v[110:113], v[152:155], v[176:179], v[110:113]
	v_mfma_f32_16x16x32_bf16 v[106:109], v[160:163], v[176:179], v[106:109]
	v_mfma_f32_16x16x32_bf16 v[94:97], v[152:155], v[184:187], v[94:97]
	v_mfma_f32_16x16x32_bf16 v[90:93], v[160:163], v[184:187], v[90:93]
	v_mfma_f32_16x16x32_bf16 v[78:81], v[152:155], v[212:215], v[78:81]
	v_mfma_f32_16x16x32_bf16 v[74:77], v[160:163], v[212:215], v[74:77]
	s_setprio 0
	s_barrier
	s_add_i32 s21, 0, 0x1c000
	s_add_i32 s14, s20, s28
	v_add_u32_e32 v195, s21, v146
	v_lshl_add_u64 v[192:193], v[192:193], 0, s[96:97]
	s_mov_b32 m0, s14
	ds_read_b128 v[216:219], v195
	ds_read_b128 v[220:223], v195 offset:1024
	ds_read_b128 v[224:227], v195 offset:2048
	ds_read_b128 v[228:231], v195 offset:3072
	global_load_lds_dwordx4 v[192:193], off
	v_lshl_add_u64 v[192:193], v[232:233], 0, s[96:97]
	s_add_i32 m0, s14, 0x2000
	s_nop 0
	global_load_lds_dwordx4 v[192:193], off
	s_barrier
; #define PG8_STAGE(bufoff, gbase, voff) do { _Pragma("unroll") for (int _i = 0; _i < 2; ++_i) \
;     __builtin_amdgcn_global_load_lds((const unsigned*)((const char*)(gbase) + (voff)[_i]), (LAS unsigned*)(lds + (bufoff) + ldsw + _i * 8192), 16, 0, 0); } while (0)
; #define PG8_LDA(dst, b, h) do { _Pragma("unroll") for (int m = 0; m < 4; ++m) _Pragma("unroll") for (int k = 0; k < 2; ++k) dst[m][k] = *(const LAS bf16x8*)(lds + PG8_SA(b, h) + aoff + m * 2048 + k * 1024); } while (0)
; #define PG8_LDB(dst, b, h) do { _Pragma("unroll") for (int n = 0; n < 2; ++n) _Pragma("unroll") for (int k = 0; k < 2; ++k) dst[n][k] = *(const LAS bf16x8*)(lds + PG8_SB(b, h) + boff + n * 2048 + k * 1024); } while (0)
; #define PG8_MMA(ai, bj, At, Bt) do { __builtin_amdgcn_s_setprio(1); _Pragma("unroll") for (int m = 0; m < 4; ++m) _Pragma("unroll") for (int n = 0; n < 2; ++n) _Pragma("unroll") for (int k = 0; k < 2; ++k) \
;     acc[ai][bj][m][n] = __builtin_amdgcn_mfma_f32_16x16x32_bf16(Bt[n][k], At[m][k], acc[ai][bj][m][n], 0, 0, 0); __builtin_amdgcn_s_setprio(0); } while (0)
; #define PG8_WAIT_V(n) asm volatile("s_waitcnt vmcnt(" #n ")" ::: "memory")
; #define PG8_WAIT_L(n) asm volatile("s_waitcnt lgkmcnt(" #n ")" ::: "memory")
; #define PG8_BAR __builtin_amdgcn_s_barrier()
; #define PG8_SCHED __builtin_amdgcn_sched_barrier(0)
; template <class Epi, bool SPLITA = false>
; __device__ __forceinline__ void gemm_phase(const int tid, LAS unsigned char* lds, const Gemm g, const Order& S, const Epi& E) {
;     ...
;       PG8_LDB(B1, 1, 1); PG8_STAGE(PG8_SB(1, 0), b3, voffB);
;       PG8_BAR; PG8_WAIT_L(0); PG8_MMA(0, 1, At, B1); PG8_BAR;
;       PG8_LDA(At, 1, 1); PG8_STAGE(PG8_SA(1, 0), a3, voffA);
;       PG8_BAR; PG8_WAIT_L(0); PG8_MMA(1, 0, At, B0); PG8_BAR; PG8_SCHED;
;       PG8_STAGE(PG8_SB(1, 1), b3 + hstepB, voffB);
;       PG8_WAIT_V(6); PG8_BAR; PG8_MMA(1, 1, At, B1); PG8_BAR;
	s_waitcnt lgkmcnt(0)
	s_setprio 1
	s_waitcnt lgkmcnt(0)
	v_mfma_f32_16x16x32_bf16 v[118:121], v[216:219], v[164:167], v[118:121]
	v_mfma_f32_16x16x32_bf16 v[114:117], v[224:227], v[164:167], v[114:117]
	v_mfma_f32_16x16x32_bf16 v[102:105], v[216:219], v[172:175], v[102:105]
	v_mfma_f32_16x16x32_bf16 v[98:101], v[224:227], v[172:175], v[98:101]
	v_mfma_f32_16x16x32_bf16 v[86:89], v[216:219], v[180:183], v[86:89]
	v_mfma_f32_16x16x32_bf16 v[82:85], v[224:227], v[180:183], v[82:85]
	v_mfma_f32_16x16x32_bf16 v[70:73], v[216:219], v[188:191], v[70:73]
	v_mfma_f32_16x16x32_bf16 v[66:69], v[224:227], v[188:191], v[66:69]
	v_mfma_f32_16x16x32_bf16 v[118:121], v[220:223], v[168:171], v[118:121]
	v_mfma_f32_16x16x32_bf16 v[114:117], v[228:231], v[168:171], v[114:117]
	v_mfma_f32_16x16x32_bf16 v[102:105], v[220:223], v[176:179], v[102:105]
	v_mfma_f32_16x16x32_bf16 v[98:101], v[228:231], v[176:179], v[98:101]
	v_mfma_f32_16x16x32_bf16 v[86:89], v[220:223], v[184:187], v[86:89]
	v_mfma_f32_16x16x32_bf16 v[82:85], v[228:231], v[184:187], v[82:85]
	v_mfma_f32_16x16x32_bf16 v[70:73], v[220:223], v[212:215], v[70:73]
	v_mfma_f32_16x16x32_bf16 v[66:69], v[228:231], v[212:215], v[66:69]
	s_setprio 0
	s_mov_b32 m0, s49
	s_barrier
	ds_read_b128 v[164:167], v147 offset:49152
	ds_read_b128 v[168:171], v147 offset:50176
	ds_read_b128 v[172:175], v147 offset:51200
	ds_read_b128 v[176:179], v147 offset:52224
	ds_read_b128 v[180:183], v147 offset:53248
	ds_read_b128 v[184:187], v147 offset:54272
	ds_read_b128 v[188:191], v147 offset:55296
	ds_read_b128 v[212:215], v147 offset:56320
	global_load_lds_dwordx4 v0, s[40:41]
	s_mov_b32 m0, s51
	s_nop 0
	global_load_lds_dwordx4 v132, s[40:41]
	s_barrier
	s_waitcnt lgkmcnt(0)
	s_setprio 1
	s_waitcnt lgkmcnt(0)
	v_mfma_f32_16x16x32_bf16 v[62:65], v[148:151], v[164:167], v[62:65]
	v_mfma_f32_16x16x32_bf16 v[58:61], v[156:159], v[164:167], v[58:61]
	v_mfma_f32_16x16x32_bf16 v[46:49], v[148:151], v[172:175], v[46:49]
	v_mfma_f32_16x16x32_bf16 v[42:45], v[156:159], v[172:175], v[42:45]
	v_mfma_f32_16x16x32_bf16 v[30:33], v[148:151], v[180:183], v[30:33]
	v_mfma_f32_16x16x32_bf16 v[26:29], v[156:159], v[180:183], v[26:29]
	v_mfma_f32_16x16x32_bf16 v[14:17], v[148:151], v[188:191], v[14:17]
	v_mfma_f32_16x16x32_bf16 v[10:13], v[156:159], v[188:191], v[10:13]
	v_mfma_f32_16x16x32_bf16 v[62:65], v[152:155], v[168:171], v[62:65]
	v_mfma_f32_16x16x32_bf16 v[58:61], v[160:163], v[168:171], v[58:61]
	v_mfma_f32_16x16x32_bf16 v[46:49], v[152:155], v[176:179], v[46:49]
	v_mfma_f32_16x16x32_bf16 v[42:45], v[160:163], v[176:179], v[42:45]
	v_mfma_f32_16x16x32_bf16 v[30:33], v[152:155], v[184:187], v[30:33]
	v_mfma_f32_16x16x32_bf16 v[26:29], v[160:163], v[184:187], v[26:29]
	v_mfma_f32_16x16x32_bf16 v[14:17], v[152:155], v[212:215], v[14:17]
	v_mfma_f32_16x16x32_bf16 v[10:13], v[160:163], v[212:215], v[10:13]
	s_setprio 0
	s_barrier
	s_add_u32 s14, s18, 0x8080
	s_addc_u32 s15, s19, 0
	s_add_i32 s18, s21, s28
	s_mov_b32 m0, s18
	s_nop 0
	global_load_lds_dwordx4 v134, s[14:15]
	s_add_i32 m0, s18, 0x2000
	s_nop 0
	global_load_lds_dwordx4 v130, s[14:15]
	s_waitcnt vmcnt(6)
	s_barrier
	s_setprio 1
	v_mfma_f32_16x16x32_bf16 v[54:57], v[216:219], v[164:167], v[54:57]
	v_mfma_f32_16x16x32_bf16 v[50:53], v[224:227], v[164:167], v[50:53]
	v_mfma_f32_16x16x32_bf16 v[38:41], v[216:219], v[172:175], v[38:41]
	v_mfma_f32_16x16x32_bf16 v[34:37], v[224:227], v[172:175], v[34:37]
	v_mfma_f32_16x16x32_bf16 v[22:25], v[216:219], v[180:183], v[22:25]
	v_mfma_f32_16x16x32_bf16 v[18:21], v[224:227], v[180:183], v[18:21]
	v_mfma_f32_16x16x32_bf16 v[6:9], v[216:219], v[188:191], v[6:9]
	v_mfma_f32_16x16x32_bf16 v[2:5], v[224:227], v[188:191], v[2:5]
	v_mfma_f32_16x16x32_bf16 v[54:57], v[220:223], v[168:171], v[54:57]
	v_mfma_f32_16x16x32_bf16 v[50:53], v[228:231], v[168:171], v[50:53]
	v_mfma_f32_16x16x32_bf16 v[38:41], v[220:223], v[176:179], v[38:41]
	v_mfma_f32_16x16x32_bf16 v[34:37], v[228:231], v[176:179], v[34:37]
	v_mfma_f32_16x16x32_bf16 v[22:25], v[220:223], v[184:187], v[22:25]
	v_mfma_f32_16x16x32_bf16 v[18:21], v[228:231], v[184:187], v[18:21]
	v_mfma_f32_16x16x32_bf16 v[6:9], v[220:223], v[212:215], v[6:9]
	v_mfma_f32_16x16x32_bf16 v[2:5], v[228:231], v[212:215], v[2:5]
	s_setprio 0
	s_cmp_ge_i32 s29, s46
	s_mov_b64 s[14:15], s[16:17]
	s_mov_b32 s18, s29
	s_barrier
	s_cbranch_scc0 .LBB0_400
	s_mov_b64 s[20:21], s[34:35]
	v_mov_b32_e32 v219, v196
	s_branch .LBB0_389

; #define PG8_STAGE(bufoff, gbase, voff) do { _Pragma("unroll") for (int _i = 0; _i < 2; ++_i) \
;     __builtin_amdgcn_global_load_lds((const unsigned*)((const char*)(gbase) + (voff)[_i]), (LAS unsigned*)(lds + (bufoff) + ldsw + _i * 8192), 16, 0, 0); } while (0)
; #define PG8_WAIT_V(n) asm volatile("s_waitcnt vmcnt(" #n ")" ::: "memory")
; #define PG8_BAR __builtin_amdgcn_s_barrier()
; template <class Epi, bool SPLITA = false>
; __device__ __forceinline__ void gemm_phase(const int tid, LAS unsigned char* lds, const Gemm g, const Order& S, const Epi& E) {
;     ...
;   PG8_STAGE(PG8_SB(0, 0), cB, voffB); PG8_STAGE(PG8_SA(0, 0), cA, voffA); PG8_STAGE(PG8_SB(0, 1), cB + hstepB, voffB); PG8_STAGE(PG8_SA(0, 1), cA + hstepA, voffA);
;   if (wr == 1) PG8_BAR;
;   PG8_WAIT_V(4); PG8_BAR;
;   PG8_STAGE(PG8_SB(1, 0), cB + kstep, voffB); PG8_STAGE(PG8_SA(1, 0), cA + kstep, voffA); PG8_STAGE(PG8_SB(1, 1), cB + hstepB + kstep, voffB);
;   PG8_WAIT_V(6); PG8_BAR;
.LBB0_458:
	s_lshl_b64 s[6:7], s[6:7], 2
	v_bfe_u32 v180, v210, 4, 2
	s_add_u32 s6, s66, s6
	v_and_b32_e32 v181, 15, v210
	v_lshlrev_b32_e32 v16, 4, v180
	v_lshlrev_b32_e32 v17, 2, v210
	s_addc_u32 s7, s67, s7
	v_lshl_or_b32 v16, v181, 6, v16
	s_lshl_b32 s1, s4, 13
	v_and_b32_e32 v17, 32, v17
	v_bitop3_b32 v18, v16, s1, v17 bitop3:0xde
	s_lshl_b32 s1, s8, 5
	s_and_b32 s47, s1, 0x60
	s_add_i32 m0, s19, 0x18000
	v_lshl_add_u64 v[8:9], v[8:9], 0, s[96:97]
	s_lshl_b32 s46, s4, 6
	s_lshl_b32 s1, s47, 7
	s_waitcnt vmcnt(4)
	s_barrier
	global_load_lds_dwordx4 v[8:9], off
	v_lshl_add_u64 v[6:7], v[6:7], 0, s[96:97]
	s_add_i32 m0, s19, 0x1a000
	s_add_i32 s51, s19, 0x8000
	s_add_i32 s52, s19, 0xa000
	global_load_lds_dwordx4 v[6:7], off
	v_lshl_add_u64 v[4:5], v[4:5], 0, s[96:97]
	s_mov_b32 m0, s51
	s_add_u32 s8, s40, 0x80080
	global_load_lds_dwordx4 v[4:5], off
	v_lshl_add_u64 v[2:3], v[2:3], 0, s[96:97]
	s_mov_b32 m0, s52
	s_addc_u32 s9, s41, 0
	global_load_lds_dwordx4 v[2:3], off
	s_add_i32 m0, s19, 0x1c000
	s_nop 0
	global_load_lds_dwordx4 v0, s[8:9]
	v_lshl_add_u64 v[2:3], s[8:9], 0, v[150:151]
	s_add_i32 m0, s19, 0x1e000
	v_bitop3_b32 v182, s1, v16, v17 bitop3:0xf6
	global_load_lds_dwordx4 v150, s[8:9]
	v_lshlrev_b32_e32 v2, 15, v10
	v_and_b32_e32 v2, 0xffff0000, v2
	v_lshl_add_u32 v2, v11, 12, v2
	v_and_b32_e32 v3, 1, v10
	v_lshl_or_b32 v2, v3, 6, v2
	v_lshl_add_u32 v152, v12, 1, v2
	v_lshlrev_b32_e32 v2, 15, v13
	v_and_b32_e32 v2, 0xffff0000, v2
	s_waitcnt vmcnt(6)
	v_lshl_add_u32 v2, v14, 12, v2
	v_and_b32_e32 v3, 1, v13
	v_lshl_or_b32 v2, v3, 6, v2
	s_ashr_i32 s53, s92, 31
	v_mov_b32_e32 v153, v1
	v_lshl_add_u32 v154, v15, 1, v2
	v_mov_b32_e32 v155, v1
	s_mov_b32 s90, 0
	v_add_u32_e32 v183, 0, v18
	s_barrier
	s_branch .LBB0_460

; #define PG8_STAGE(bufoff, gbase, voff) do { _Pragma("unroll") for (int _i = 0; _i < 2; ++_i) \
;     __builtin_amdgcn_global_load_lds((const unsigned*)((const char*)(gbase) + (voff)[_i]), (LAS unsigned*)(lds + (bufoff) + ldsw + _i * 8192), 16, 0, 0); } while (0)
; #define PG8_LDA(dst, b, h) do { _Pragma("unroll") for (int m = 0; m < 4; ++m) _Pragma("unroll") for (int k = 0; k < 2; ++k) dst[m][k] = *(const LAS bf16x8*)(lds + PG8_SA(b, h) + aoff + m * 2048 + k * 1024); } while (0)
; #define PG8_LDB(dst, b, h) do { _Pragma("unroll") for (int n = 0; n < 2; ++n) _Pragma("unroll") for (int k = 0; k < 2; ++k) dst[n][k] = *(const LAS bf16x8*)(lds + PG8_SB(b, h) + boff + n * 2048 + k * 1024); } while (0)
; #define PG8_MMA(ai, bj, At, Bt) do { __builtin_amdgcn_s_setprio(1); _Pragma("unroll") for (int m = 0; m < 4; ++m) _Pragma("unroll") for (int n = 0; n < 2; ++n) _Pragma("unroll") for (int k = 0; k < 2; ++k) \
;     acc[ai][bj][m][n] = __builtin_amdgcn_mfma_f32_16x16x32_bf16(Bt[n][k], At[m][k], acc[ai][bj][m][n], 0, 0, 0); __builtin_amdgcn_s_setprio(0); } while (0)
; #define PG8_WAIT_L(n) asm volatile("s_waitcnt lgkmcnt(" #n ")" ::: "memory")
; #define PG8_BAR __builtin_amdgcn_s_barrier()
; #define PG8_SCHED __builtin_amdgcn_sched_barrier(0)
; template <class Epi, bool SPLITA = false>
; __device__ __forceinline__ void gemm_phase(const int tid, LAS unsigned char* lds, const Gemm g, const Order& S, const Epi& E) {
;     ...
;       PG8_LDB(B0, 0, 0); PG8_SCHED; PG8_LDA(At, 0, 0); PG8_STAGE(PG8_SA(1, 1), a1 + hstepA, voffA);
;       PG8_WAIT_L(8); PG8_BAR; PG8_WAIT_L(0); PG8_MMA(0, 0, At, B0); PG8_BAR; PG8_SCHED;
;       PG8_LDB(B1, 0, 1); PG8_STAGE(PG8_SB(0, 0), b2, voffB);
;       PG8_BAR; PG8_WAIT_L(0); PG8_MMA(0, 1, At, B1); PG8_BAR;
;       PG8_LDA(At, 0, 1); PG8_STAGE(PG8_SA(0, 0), a2, voffA);
;       PG8_BAR; PG8_WAIT_L(0); PG8_MMA(1, 0, At, B0); PG8_BAR; PG8_SCHED;
.LBB0_463:
	s_add_u32 s20, s16, s40
	s_addc_u32 s21, s17, s41
	s_add_u32 s22, s20, 0x100
	s_addc_u32 s23, s21, 0
	s_add_u32 s29, vcc_lo, s40
	s_addc_u32 s42, vcc_hi, s41
	s_add_u32 s20, s20, 0x180
	s_addc_u32 s21, s21, 0
	s_add_i32 s94, 0, 0x10000
	v_add_u32_e32 v156, s94, v182
	ds_read_b128 v[62:65], v156
	ds_read_b128 v[74:77], v156 offset:1024
	ds_read_b128 v[78:81], v156 offset:2048
	ds_read_b128 v[156:159], v156 offset:3072
	s_cmpk_eq_i32 s40, 0xf00
	s_cselect_b32 s49, s93, s21
	s_cselect_b32 s48, s91, s20
	s_cselect_b32 s43, s9, s42
	s_cselect_b32 s42, s28, s29
	s_cselect_b32 s55, s1, s23
	s_cselect_b32 s54, s11, s22
	v_lshl_add_u64 v[192:193], v[58:59], 0, s[40:41]
	s_add_i32 m0, s19, 0xc000
	ds_read_b128 v[160:163], v183
	ds_read_b128 v[164:167], v183 offset:1024
	ds_read_b128 v[168:171], v183 offset:2048
	ds_read_b128 v[172:175], v183 offset:3072
	ds_read_b128 v[176:179], v183 offset:4096
	ds_read_b128 v[184:187], v183 offset:5120
	ds_read_b128 v[188:191], v183 offset:6144
	ds_read_b128 v[212:215], v183 offset:7168
	global_load_lds_dwordx4 v[192:193], off
	v_lshl_add_u64 v[192:193], v[60:61], 0, s[40:41]
	s_add_i32 m0, s19, 0xe000
	s_nop 0
	global_load_lds_dwordx4 v[192:193], off
	s_waitcnt lgkmcnt(8)
	s_barrier
	s_waitcnt lgkmcnt(0)
	s_setprio 1
	s_waitcnt lgkmcnt(0)
	v_mfma_f32_16x16x32_bf16 v[142:145], v[62:65], v[160:163], v[142:145]
	v_mfma_f32_16x16x32_bf16 v[138:141], v[78:81], v[160:163], v[138:141]
	v_mfma_f32_16x16x32_bf16 v[126:129], v[62:65], v[168:171], v[126:129]
	v_mfma_f32_16x16x32_bf16 v[122:125], v[78:81], v[168:171], v[122:125]
	v_mfma_f32_16x16x32_bf16 v[110:113], v[62:65], v[176:179], v[110:113]
	v_mfma_f32_16x16x32_bf16 v[106:109], v[78:81], v[176:179], v[106:109]
	v_mfma_f32_16x16x32_bf16 v[94:97], v[62:65], v[188:191], v[94:97]
	v_mfma_f32_16x16x32_bf16 v[90:93], v[78:81], v[188:191], v[90:93]
	v_mfma_f32_16x16x32_bf16 v[142:145], v[74:77], v[164:167], v[142:145]
	v_mfma_f32_16x16x32_bf16 v[138:141], v[156:159], v[164:167], v[138:141]
	v_mfma_f32_16x16x32_bf16 v[126:129], v[74:77], v[172:175], v[126:129]
	v_mfma_f32_16x16x32_bf16 v[122:125], v[156:159], v[172:175], v[122:125]
	v_mfma_f32_16x16x32_bf16 v[110:113], v[74:77], v[184:187], v[110:113]
	v_mfma_f32_16x16x32_bf16 v[106:109], v[156:159], v[184:187], v[106:109]
	v_mfma_f32_16x16x32_bf16 v[94:97], v[74:77], v[212:215], v[94:97]
	v_mfma_f32_16x16x32_bf16 v[90:93], v[156:159], v[212:215], v[90:93]
	s_setprio 0
	s_barrier
	s_add_i32 s20, 0, 0x14000
	v_add_u32_e32 v192, s20, v182
	s_add_i32 s21, s94, s30
	ds_read_b128 v[216:219], v192
	ds_read_b128 v[220:223], v192 offset:1024
	ds_read_b128 v[224:227], v192 offset:2048
	ds_read_b128 v[228:231], v192 offset:3072
	v_lshl_add_u64 v[192:193], s[42:43], 0, v[0:1]
	s_mov_b32 m0, s21
	v_lshl_add_u64 v[232:233], s[42:43], 0, v[150:151]
	global_load_lds_dwordx4 v0, s[42:43]
	s_add_i32 m0, s21, 0x2000
	s_nop 0
	global_load_lds_dwordx4 v150, s[42:43]
	s_barrier
	s_waitcnt lgkmcnt(0)
	s_setprio 1
	s_waitcnt lgkmcnt(0)
	v_mfma_f32_16x16x32_bf16 v[134:137], v[216:219], v[160:163], v[134:137]
	v_mfma_f32_16x16x32_bf16 v[130:133], v[224:227], v[160:163], v[130:133]
	v_mfma_f32_16x16x32_bf16 v[118:121], v[216:219], v[168:171], v[118:121]
	v_mfma_f32_16x16x32_bf16 v[114:117], v[224:227], v[168:171], v[114:117]
	v_mfma_f32_16x16x32_bf16 v[102:105], v[216:219], v[176:179], v[102:105]
	v_mfma_f32_16x16x32_bf16 v[98:101], v[224:227], v[176:179], v[98:101]
	v_mfma_f32_16x16x32_bf16 v[86:89], v[216:219], v[188:191], v[86:89]
	v_mfma_f32_16x16x32_bf16 v[82:85], v[224:227], v[188:191], v[82:85]
	v_mfma_f32_16x16x32_bf16 v[134:137], v[220:223], v[164:167], v[134:137]
	v_mfma_f32_16x16x32_bf16 v[130:133], v[228:231], v[164:167], v[130:133]
	v_mfma_f32_16x16x32_bf16 v[118:121], v[220:223], v[172:175], v[118:121]
	v_mfma_f32_16x16x32_bf16 v[114:117], v[228:231], v[172:175], v[114:117]
	v_mfma_f32_16x16x32_bf16 v[102:105], v[220:223], v[184:187], v[102:105]
	v_mfma_f32_16x16x32_bf16 v[98:101], v[228:231], v[184:187], v[98:101]
	v_mfma_f32_16x16x32_bf16 v[86:89], v[220:223], v[212:215], v[86:89]
	v_mfma_f32_16x16x32_bf16 v[82:85], v[228:231], v[212:215], v[82:85]
	s_setprio 0
	s_mov_b32 m0, s19
	s_barrier
	ds_read_b128 v[160:163], v183 offset:16384
	ds_read_b128 v[164:167], v183 offset:17408
	ds_read_b128 v[168:171], v183 offset:18432
	ds_read_b128 v[172:175], v183 offset:19456
	ds_read_b128 v[176:179], v183 offset:20480
	ds_read_b128 v[184:187], v183 offset:21504
	ds_read_b128 v[188:191], v183 offset:22528
	ds_read_b128 v[212:215], v183 offset:23552
	global_load_lds_dwordx4 v146, s[54:55]
	s_mov_b32 m0, s31
	s_nop 0
	global_load_lds_dwordx4 v148, s[54:55]
	s_barrier
	s_waitcnt lgkmcnt(0)
	s_setprio 1
	s_waitcnt lgkmcnt(0)
	v_mfma_f32_16x16x32_bf16 v[70:73], v[62:65], v[160:163], v[70:73]
	v_mfma_f32_16x16x32_bf16 v[66:69], v[78:81], v[160:163], v[66:69]
	v_mfma_f32_16x16x32_bf16 v[46:49], v[62:65], v[168:171], v[46:49]
	v_mfma_f32_16x16x32_bf16 v[42:45], v[78:81], v[168:171], v[42:45]
	v_mfma_f32_16x16x32_bf16 v[30:33], v[62:65], v[176:179], v[30:33]
	v_mfma_f32_16x16x32_bf16 v[26:29], v[78:81], v[176:179], v[26:29]
	v_mfma_f32_16x16x32_bf16 v[14:17], v[62:65], v[188:191], v[14:17]
	v_mfma_f32_16x16x32_bf16 v[10:13], v[78:81], v[188:191], v[10:13]
	v_mfma_f32_16x16x32_bf16 v[70:73], v[74:77], v[164:167], v[70:73]
	v_mfma_f32_16x16x32_bf16 v[66:69], v[156:159], v[164:167], v[66:69]
	v_mfma_f32_16x16x32_bf16 v[46:49], v[74:77], v[172:175], v[46:49]
	v_mfma_f32_16x16x32_bf16 v[42:45], v[156:159], v[172:175], v[42:45]
	v_mfma_f32_16x16x32_bf16 v[30:33], v[74:77], v[184:187], v[30:33]
	v_mfma_f32_16x16x32_bf16 v[26:29], v[156:159], v[184:187], v[26:29]
	v_mfma_f32_16x16x32_bf16 v[14:17], v[74:77], v[212:215], v[14:17]
	v_mfma_f32_16x16x32_bf16 v[10:13], v[156:159], v[212:215], v[10:13]
	s_setprio 0
	s_barrier
; #define PG8_STAGE(bufoff, gbase, voff) do { _Pragma("unroll") for (int _i = 0; _i < 2; ++_i) \
;     __builtin_amdgcn_global_load_lds((const unsigned*)((const char*)(gbase) + (voff)[_i]), (LAS unsigned*)(lds + (bufoff) + ldsw + _i * 8192), 16, 0, 0); } while (0)
; #define PG8_LDA(dst, b, h) do { _Pragma("unroll") for (int m = 0; m < 4; ++m) _Pragma("unroll") for (int k = 0; k < 2; ++k) dst[m][k] = *(const LAS bf16x8*)(lds + PG8_SA(b, h) + aoff + m * 2048 + k * 1024); } while (0)
; #define PG8_LDB(dst, b, h) do { _Pragma("unroll") for (int n = 0; n < 2; ++n) _Pragma("unroll") for (int k = 0; k < 2; ++k) dst[n][k] = *(const LAS bf16x8*)(lds + PG8_SB(b, h) + boff + n * 2048 + k * 1024); } while (0)
; #define PG8_MMA(ai, bj, At, Bt) do { __builtin_amdgcn_s_setprio(1); _Pragma("unroll") for (int m = 0; m < 4; ++m) _Pragma("unroll") for (int n = 0; n < 2; ++n) _Pragma("unroll") for (int k = 0; k < 2; ++k) \
;     acc[ai][bj][m][n] = __builtin_amdgcn_mfma_f32_16x16x32_bf16(Bt[n][k], At[m][k], acc[ai][bj][m][n], 0, 0, 0); __builtin_amdgcn_s_setprio(0); } while (0)
; #define PG8_WAIT_V(n) asm volatile("s_waitcnt vmcnt(" #n ")" ::: "memory")
; #define PG8_WAIT_L(n) asm volatile("s_waitcnt lgkmcnt(" #n ")" ::: "memory")
; #define PG8_BAR __builtin_amdgcn_s_barrier()
; #define PG8_SCHED __builtin_amdgcn_sched_barrier(0)
; template <class Epi, bool SPLITA = false>
; __device__ __forceinline__ void gemm_phase(const int tid, LAS unsigned char* lds, const Gemm g, const Order& S, const Epi& E) {
;     ...
;       PG8_STAGE(PG8_SB(0, 1), b2 + hstepB, voffB);
;       PG8_WAIT_V(6); PG8_BAR; PG8_MMA(1, 1, At, B1); PG8_BAR;
;       PG8_LDB(B0, 1, 0); PG8_SCHED; PG8_LDA(At, 1, 0); PG8_STAGE(PG8_SA(0, 1), a2 + hstepA, voffA);
;       PG8_WAIT_L(8); PG8_BAR; PG8_WAIT_L(0); PG8_MMA(0, 0, At, B0); PG8_BAR; PG8_SCHED;
;       PG8_LDB(B1, 1, 1); PG8_STAGE(PG8_SB(1, 0), b3, voffB);
	s_add_u32 s22, s42, 0x80000
	s_addc_u32 s23, s43, 0
	s_add_i32 s20, s20, s30
	s_mov_b32 m0, s20
	s_nop 0
	global_load_lds_dwordx4 v0, s[22:23]
	v_lshl_add_u64 v[62:63], s[22:23], 0, v[150:151]
	s_add_i32 m0, s20, 0x2000
	s_nop 0
	global_load_lds_dwordx4 v150, s[22:23]
	s_waitcnt vmcnt(6)
	s_barrier
	s_setprio 1
	v_mfma_f32_16x16x32_bf16 v[54:57], v[216:219], v[160:163], v[54:57]
	v_mfma_f32_16x16x32_bf16 v[50:53], v[224:227], v[160:163], v[50:53]
	v_mfma_f32_16x16x32_bf16 v[38:41], v[216:219], v[168:171], v[38:41]
	v_mfma_f32_16x16x32_bf16 v[34:37], v[224:227], v[168:171], v[34:37]
	v_mfma_f32_16x16x32_bf16 v[22:25], v[216:219], v[176:179], v[22:25]
	v_mfma_f32_16x16x32_bf16 v[18:21], v[224:227], v[176:179], v[18:21]
	v_mfma_f32_16x16x32_bf16 v[6:9], v[216:219], v[188:191], v[6:9]
	v_mfma_f32_16x16x32_bf16 v[2:5], v[224:227], v[188:191], v[2:5]
	v_mfma_f32_16x16x32_bf16 v[54:57], v[220:223], v[164:167], v[54:57]
	v_mfma_f32_16x16x32_bf16 v[50:53], v[228:231], v[164:167], v[50:53]
	v_mfma_f32_16x16x32_bf16 v[38:41], v[220:223], v[172:175], v[38:41]
	v_mfma_f32_16x16x32_bf16 v[34:37], v[228:231], v[172:175], v[34:37]
	v_mfma_f32_16x16x32_bf16 v[22:25], v[220:223], v[184:187], v[22:25]
	v_mfma_f32_16x16x32_bf16 v[18:21], v[228:231], v[184:187], v[18:21]
	v_mfma_f32_16x16x32_bf16 v[6:9], v[220:223], v[212:215], v[6:9]
	v_mfma_f32_16x16x32_bf16 v[2:5], v[228:231], v[212:215], v[2:5]
	s_setprio 0
	s_add_i32 s20, 0, 0x18000
	v_add_u32_e32 v156, s20, v182
	s_barrier
	ds_read_b128 v[62:65], v156
	ds_read_b128 v[74:77], v156 offset:1024
	ds_read_b128 v[78:81], v156 offset:2048
	ds_read_b128 v[156:159], v156 offset:3072
	s_add_u32 s22, s54, 0x80000
	s_addc_u32 s23, s55, 0
	s_mov_b32 m0, s44
	ds_read_b128 v[160:163], v183 offset:32768
	ds_read_b128 v[164:167], v183 offset:33792
	ds_read_b128 v[168:171], v183 offset:34816
	ds_read_b128 v[172:175], v183 offset:35840
	ds_read_b128 v[176:179], v183 offset:36864
	ds_read_b128 v[184:187], v183 offset:37888
	ds_read_b128 v[188:191], v183 offset:38912
	ds_read_b128 v[212:215], v183 offset:39936
	global_load_lds_dwordx4 v146, s[22:23]
	v_lshl_add_u64 v[216:217], s[22:23], 0, v[148:149]
	s_mov_b32 m0, s45
	s_nop 0
	global_load_lds_dwordx4 v148, s[22:23]
	s_waitcnt lgkmcnt(8)
	s_barrier
	s_waitcnt lgkmcnt(0)
	s_setprio 1
	s_waitcnt lgkmcnt(0)
	v_mfma_f32_16x16x32_bf16 v[142:145], v[62:65], v[160:163], v[142:145]
	v_mfma_f32_16x16x32_bf16 v[138:141], v[78:81], v[160:163], v[138:141]
	v_mfma_f32_16x16x32_bf16 v[126:129], v[62:65], v[168:171], v[126:129]
	v_mfma_f32_16x16x32_bf16 v[122:125], v[78:81], v[168:171], v[122:125]
	v_mfma_f32_16x16x32_bf16 v[110:113], v[62:65], v[176:179], v[110:113]
	v_mfma_f32_16x16x32_bf16 v[106:109], v[78:81], v[176:179], v[106:109]
	v_mfma_f32_16x16x32_bf16 v[94:97], v[62:65], v[188:191], v[94:97]
	v_mfma_f32_16x16x32_bf16 v[90:93], v[78:81], v[188:191], v[90:93]
	v_mfma_f32_16x16x32_bf16 v[142:145], v[74:77], v[164:167], v[142:145]
	v_mfma_f32_16x16x32_bf16 v[138:141], v[156:159], v[164:167], v[138:141]
	v_mfma_f32_16x16x32_bf16 v[126:129], v[74:77], v[172:175], v[126:129]
	v_mfma_f32_16x16x32_bf16 v[122:125], v[156:159], v[172:175], v[122:125]
	v_mfma_f32_16x16x32_bf16 v[110:113], v[74:77], v[184:187], v[110:113]
	v_mfma_f32_16x16x32_bf16 v[106:109], v[156:159], v[184:187], v[106:109]
	v_mfma_f32_16x16x32_bf16 v[94:97], v[74:77], v[212:215], v[94:97]
	v_mfma_f32_16x16x32_bf16 v[90:93], v[156:159], v[212:215], v[90:93]
	s_setprio 0
	s_barrier
	s_add_i32 s21, 0, 0x1c000
	s_add_i32 s20, s20, s30
	v_add_u32_e32 v195, s21, v182
	v_lshl_add_u64 v[192:193], v[192:193], 0, s[96:97]
	s_mov_b32 m0, s20
	ds_read_b128 v[216:219], v195
	ds_read_b128 v[220:223], v195 offset:1024
	ds_read_b128 v[224:227], v195 offset:2048
	ds_read_b128 v[228:231], v195 offset:3072
	global_load_lds_dwordx4 v[192:193], off
	v_lshl_add_u64 v[192:193], v[232:233], 0, s[96:97]
	s_add_i32 m0, s20, 0x2000
	s_nop 0
	global_load_lds_dwordx4 v[192:193], off
	s_barrier
; #define PG8_STAGE(bufoff, gbase, voff) do { _Pragma("unroll") for (int _i = 0; _i < 2; ++_i) \
;     __builtin_amdgcn_global_load_lds((const unsigned*)((const char*)(gbase) + (voff)[_i]), (LAS unsigned*)(lds + (bufoff) + ldsw + _i * 8192), 16, 0, 0); } while (0)
; #define PG8_LDA(dst, b, h) do { _Pragma("unroll") for (int m = 0; m < 4; ++m) _Pragma("unroll") for (int k = 0; k < 2; ++k) dst[m][k] = *(const LAS bf16x8*)(lds + PG8_SA(b, h) + aoff + m * 2048 + k * 1024); } while (0)
; #define PG8_MMA(ai, bj, At, Bt) do { __builtin_amdgcn_s_setprio(1); _Pragma("unroll") for (int m = 0; m < 4; ++m) _Pragma("unroll") for (int n = 0; n < 2; ++n) _Pragma("unroll") for (int k = 0; k < 2; ++k) \
;     acc[ai][bj][m][n] = __builtin_amdgcn_mfma_f32_16x16x32_bf16(Bt[n][k], At[m][k], acc[ai][bj][m][n], 0, 0, 0); __builtin_amdgcn_s_setprio(0); } while (0)
; #define PG8_WAIT_V(n) asm volatile("s_waitcnt vmcnt(" #n ")" ::: "memory")
; #define PG8_WAIT_L(n) asm volatile("s_waitcnt lgkmcnt(" #n ")" ::: "memory")
; #define PG8_BAR __builtin_amdgcn_s_barrier()
; #define PG8_SCHED __builtin_amdgcn_sched_barrier(0)
; template <class Epi, bool SPLITA = false>
; __device__ __forceinline__ void gemm_phase(const int tid, LAS unsigned char* lds, const Gemm g, const Order& S, const Epi& E) {
;     ...
;       PG8_BAR; PG8_WAIT_L(0); PG8_MMA(0, 1, At, B1); PG8_BAR;
;       PG8_LDA(At, 1, 1); PG8_STAGE(PG8_SA(1, 0), a3, voffA);
;       PG8_BAR; PG8_WAIT_L(0); PG8_MMA(1, 0, At, B0); PG8_BAR; PG8_SCHED;
;       PG8_STAGE(PG8_SB(1, 1), b3 + hstepB, voffB);
;       PG8_WAIT_V(6); PG8_BAR; PG8_MMA(1, 1, At, B1); PG8_BAR;
;     }
;   __device__ __forceinline__ void operator()(const Acc& acc, const Unit& u, int wr, int wc, int fr_, int fq_) const {
;     ...
;     bf16_t* base; int ld, c0; bool gate = false;
;     if (u.pn < 4) { base = Q; ld = 1024; c0 = u.pn * 256; }
;     else if (u.pn == 4) { base = Kb; ld = 256; c0 = 0; }
;     else if (u.pn == 5) { base = Vb; ld = 256; c0 = 0; }
;     else if (u.pn < 10) { base = F; ld = 1024; c0 = (u.pn - 6) * 256; }
;     else { base = Gt; ld = 4096; c0 = (u.pn - 10) * 256; gate = true; }
	s_waitcnt lgkmcnt(0)
	s_setprio 1
	s_waitcnt lgkmcnt(0)
	v_mfma_f32_16x16x32_bf16 v[134:137], v[216:219], v[160:163], v[134:137]
	v_mfma_f32_16x16x32_bf16 v[130:133], v[224:227], v[160:163], v[130:133]
	v_mfma_f32_16x16x32_bf16 v[118:121], v[216:219], v[168:171], v[118:121]
	v_mfma_f32_16x16x32_bf16 v[114:117], v[224:227], v[168:171], v[114:117]
	v_mfma_f32_16x16x32_bf16 v[102:105], v[216:219], v[176:179], v[102:105]
	v_mfma_f32_16x16x32_bf16 v[98:101], v[224:227], v[176:179], v[98:101]
	v_mfma_f32_16x16x32_bf16 v[86:89], v[216:219], v[188:191], v[86:89]
	v_mfma_f32_16x16x32_bf16 v[82:85], v[224:227], v[188:191], v[82:85]
	v_mfma_f32_16x16x32_bf16 v[134:137], v[220:223], v[164:167], v[134:137]
	v_mfma_f32_16x16x32_bf16 v[130:133], v[228:231], v[164:167], v[130:133]
	v_mfma_f32_16x16x32_bf16 v[118:121], v[220:223], v[172:175], v[118:121]
	v_mfma_f32_16x16x32_bf16 v[114:117], v[228:231], v[172:175], v[114:117]
	v_mfma_f32_16x16x32_bf16 v[102:105], v[220:223], v[184:187], v[102:105]
	v_mfma_f32_16x16x32_bf16 v[98:101], v[228:231], v[184:187], v[98:101]
	v_mfma_f32_16x16x32_bf16 v[86:89], v[220:223], v[212:215], v[86:89]
	v_mfma_f32_16x16x32_bf16 v[82:85], v[228:231], v[212:215], v[82:85]
	s_setprio 0
	s_mov_b32 m0, s51
	s_barrier
	ds_read_b128 v[160:163], v183 offset:49152
	ds_read_b128 v[164:167], v183 offset:50176
	ds_read_b128 v[168:171], v183 offset:51200
	ds_read_b128 v[172:175], v183 offset:52224
	ds_read_b128 v[176:179], v183 offset:53248
	ds_read_b128 v[184:187], v183 offset:54272
	ds_read_b128 v[188:191], v183 offset:55296
	ds_read_b128 v[212:215], v183 offset:56320
	global_load_lds_dwordx4 v146, s[48:49]
	s_mov_b32 m0, s52
	s_nop 0
	global_load_lds_dwordx4 v148, s[48:49]
	s_barrier
	s_waitcnt lgkmcnt(0)
	s_setprio 1
	s_waitcnt lgkmcnt(0)
	v_mfma_f32_16x16x32_bf16 v[70:73], v[62:65], v[160:163], v[70:73]
	v_mfma_f32_16x16x32_bf16 v[66:69], v[78:81], v[160:163], v[66:69]
	v_mfma_f32_16x16x32_bf16 v[46:49], v[62:65], v[168:171], v[46:49]
	v_mfma_f32_16x16x32_bf16 v[42:45], v[78:81], v[168:171], v[42:45]
	v_mfma_f32_16x16x32_bf16 v[30:33], v[62:65], v[176:179], v[30:33]
	v_mfma_f32_16x16x32_bf16 v[26:29], v[78:81], v[176:179], v[26:29]
	v_mfma_f32_16x16x32_bf16 v[14:17], v[62:65], v[188:191], v[14:17]
	v_mfma_f32_16x16x32_bf16 v[10:13], v[78:81], v[188:191], v[10:13]
	v_mfma_f32_16x16x32_bf16 v[70:73], v[74:77], v[164:167], v[70:73]
	v_mfma_f32_16x16x32_bf16 v[66:69], v[156:159], v[164:167], v[66:69]
	v_mfma_f32_16x16x32_bf16 v[46:49], v[74:77], v[172:175], v[46:49]
	v_mfma_f32_16x16x32_bf16 v[42:45], v[156:159], v[172:175], v[42:45]
	v_mfma_f32_16x16x32_bf16 v[30:33], v[74:77], v[184:187], v[30:33]
	v_mfma_f32_16x16x32_bf16 v[26:29], v[156:159], v[184:187], v[26:29]
	v_mfma_f32_16x16x32_bf16 v[14:17], v[74:77], v[212:215], v[14:17]
	v_mfma_f32_16x16x32_bf16 v[10:13], v[156:159], v[212:215], v[10:13]
	s_setprio 0
	s_barrier
	s_add_u32 s22, s42, 0x80080
	s_addc_u32 s23, s43, 0
	s_add_i32 s20, s21, s30
	s_mov_b32 m0, s20
	s_nop 0
	global_load_lds_dwordx4 v0, s[22:23]
	s_add_i32 m0, s20, 0x2000
	s_nop 0
	global_load_lds_dwordx4 v150, s[22:23]
	s_waitcnt vmcnt(6)
	s_barrier
	s_setprio 1
	v_mfma_f32_16x16x32_bf16 v[54:57], v[216:219], v[160:163], v[54:57]
	v_mfma_f32_16x16x32_bf16 v[50:53], v[224:227], v[160:163], v[50:53]
	v_mfma_f32_16x16x32_bf16 v[38:41], v[216:219], v[168:171], v[38:41]
	v_mfma_f32_16x16x32_bf16 v[34:37], v[224:227], v[168:171], v[34:37]
	v_mfma_f32_16x16x32_bf16 v[22:25], v[216:219], v[176:179], v[22:25]
	v_mfma_f32_16x16x32_bf16 v[18:21], v[224:227], v[176:179], v[18:21]
	v_mfma_f32_16x16x32_bf16 v[6:9], v[216:219], v[188:191], v[6:9]
	v_mfma_f32_16x16x32_bf16 v[2:5], v[224:227], v[188:191], v[2:5]
	v_mfma_f32_16x16x32_bf16 v[54:57], v[220:223], v[164:167], v[54:57]
	v_mfma_f32_16x16x32_bf16 v[50:53], v[228:231], v[164:167], v[50:53]
	v_mfma_f32_16x16x32_bf16 v[38:41], v[220:223], v[172:175], v[38:41]
	v_mfma_f32_16x16x32_bf16 v[34:37], v[228:231], v[172:175], v[34:37]
	v_mfma_f32_16x16x32_bf16 v[22:25], v[220:223], v[184:187], v[22:25]
	v_mfma_f32_16x16x32_bf16 v[18:21], v[228:231], v[184:187], v[18:21]
	v_mfma_f32_16x16x32_bf16 v[6:9], v[220:223], v[212:215], v[6:9]
	v_mfma_f32_16x16x32_bf16 v[2:5], v[228:231], v[212:215], v[2:5]
	s_setprio 0
	s_add_i32 s4, s4, 2
	s_add_u32 s40, s40, 0x100
	s_addc_u32 s41, s41, 0
	s_cmp_gt_u32 s4, 29
	s_barrier
	s_cbranch_scc0 .LBB0_463
	v_mov_b32_e32 v158, v181
	v_mov_b32_e32 v58, v180
	s_cmp_gt_i32 s0, 3
	s_mov_b64 s[48:49], -1
	s_mov_b64 s[20:21], s[34:35]
	s_cbranch_scc0 .LBB0_475
	s_cmp_lt_i32 s0, 5
	s_mov_b64 s[48:49], 0
	s_cbranch_scc1 .LBB0_474
	s_cmp_lg_u32 s0, 5
	s_mov_b64 s[54:55], -1
	s_cbranch_scc0 .LBB0_472
	s_lshl_b32 s4, s0, 8
	s_cmp_gt_u32 s0, 9
	s_mov_b64 s[40:41], -1
	s_mov_b64 s[42:43], -1
	s_cbranch_scc0 .LBB0_469
	s_add_i32 s1, s4, 0xfffff600
	s_mov_b64 s[42:43], 0
